# adds: attention epilogue gate loads issued together (counted waits), s_setprio and redundant post-barrier waits removed from GEMM K-loops, nt hint on P7 streaming loads/stores
# speedup vs baseline: 1.0080x; 1.0080x over previous
.LBB0_759:
	s_add_u32 s8, s6, 0xfff00080
	s_addc_u32 s9, s7, -1
	s_add_i32 s46, 0, 0x10000
	s_cmp_eq_u32 s45, 60
	s_cselect_b32 s43, s15, s9
	s_cselect_b32 s42, s33, s8
	v_add_u32_e32 v2, s46, v154
	s_cselect_b32 s9, s31, s44
	s_cselect_b32 s8, s37, s40
	s_add_i32 s51, 0, 0x14000
	ds_read_b128 v[144:147], v2
	ds_read_b128 v[148:151], v2 offset:1024
	ds_read_b128 v[156:159], v2 offset:2048
	ds_read_b128 v[160:163], v2 offset:3072
	v_add_u32_e32 v2, s51, v154
	ds_read_b128 v[164:167], v2
	ds_read_b128 v[168:171], v2 offset:1024
	ds_read_b128 v[172:175], v2 offset:2048
	ds_read_b128 v[176:179], v2 offset:3072
	v_lshl_add_u64 v[196:197], s[6:7], 0, v[140:141]
	s_add_i32 m0, s55, 0xc000
	ds_read_b128 v[180:183], v155
	ds_read_b128 v[184:187], v155 offset:1024
	ds_read_b128 v[188:191], v155 offset:2048
	ds_read_b128 v[192:195], v155 offset:3072
	ds_read_b128 v[204:207], v155 offset:4096
	ds_read_b128 v[208:211], v155 offset:5120
	ds_read_b128 v[230:233], v155 offset:6144
	ds_read_b128 v[234:237], v155 offset:7168
	global_load_lds_dwordx4 v[196:197], off
	v_lshl_add_u64 v[196:197], s[6:7], 0, v[142:143]
	s_add_i32 m0, s55, 0xe000
	s_nop 0
	global_load_lds_dwordx4 v[196:197], off
	s_waitcnt vmcnt(8)
	s_waitcnt lgkmcnt(0)
	s_barrier
	v_mfma_f32_16x16x32_bf16 v[64:67], v[144:147], v[180:183], v[64:67]
	v_mfma_f32_16x16x32_bf16 v[60:63], v[156:159], v[180:183], v[60:63]
	v_mfma_f32_16x16x32_bf16 v[56:59], v[144:147], v[188:191], v[56:59]
	v_mfma_f32_16x16x32_bf16 v[52:55], v[156:159], v[188:191], v[52:55]
	v_mfma_f32_16x16x32_bf16 v[48:51], v[144:147], v[204:207], v[48:51]
	v_mfma_f32_16x16x32_bf16 v[44:47], v[156:159], v[204:207], v[44:47]
	v_mfma_f32_16x16x32_bf16 v[40:43], v[144:147], v[230:233], v[40:43]
	v_mfma_f32_16x16x32_bf16 v[36:39], v[156:159], v[230:233], v[36:39]
	v_mfma_f32_16x16x32_bf16 v[64:67], v[148:151], v[184:187], v[64:67]
	v_mfma_f32_16x16x32_bf16 v[60:63], v[160:163], v[184:187], v[60:63]
	v_mfma_f32_16x16x32_bf16 v[56:59], v[148:151], v[192:195], v[56:59]
	v_mfma_f32_16x16x32_bf16 v[52:55], v[160:163], v[192:195], v[52:55]
	v_mfma_f32_16x16x32_bf16 v[48:51], v[148:151], v[208:211], v[48:51]
	v_mfma_f32_16x16x32_bf16 v[44:47], v[160:163], v[208:211], v[44:47]
	v_mfma_f32_16x16x32_bf16 v[40:43], v[148:151], v[234:237], v[40:43]
	v_mfma_f32_16x16x32_bf16 v[36:39], v[160:163], v[234:237], v[36:39]
	v_mfma_f32_16x16x32_bf16 v[128:131], v[164:167], v[180:183], v[128:131]
	v_mfma_f32_16x16x32_bf16 v[124:127], v[172:175], v[180:183], v[124:127]
	v_mfma_f32_16x16x32_bf16 v[120:123], v[164:167], v[188:191], v[120:123]
	v_mfma_f32_16x16x32_bf16 v[116:119], v[172:175], v[188:191], v[116:119]
	v_mfma_f32_16x16x32_bf16 v[112:115], v[164:167], v[204:207], v[112:115]
	v_mfma_f32_16x16x32_bf16 v[108:111], v[172:175], v[204:207], v[108:111]
	v_mfma_f32_16x16x32_bf16 v[104:107], v[164:167], v[230:233], v[104:107]
	v_mfma_f32_16x16x32_bf16 v[100:103], v[172:175], v[230:233], v[100:103]
	v_mfma_f32_16x16x32_bf16 v[128:131], v[168:171], v[184:187], v[128:131]
	v_mfma_f32_16x16x32_bf16 v[124:127], v[176:179], v[184:187], v[124:127]
	v_mfma_f32_16x16x32_bf16 v[120:123], v[168:171], v[192:195], v[120:123]
	v_mfma_f32_16x16x32_bf16 v[116:119], v[176:179], v[192:195], v[116:119]
	v_mfma_f32_16x16x32_bf16 v[112:115], v[168:171], v[208:211], v[112:115]
	v_mfma_f32_16x16x32_bf16 v[108:111], v[176:179], v[208:211], v[108:111]
	v_mfma_f32_16x16x32_bf16 v[104:107], v[168:171], v[234:237], v[104:107]
	v_mfma_f32_16x16x32_bf16 v[100:103], v[176:179], v[234:237], v[100:103]
	s_barrier
	s_add_i32 s46, s46, s54
	v_lshl_add_u64 v[196:197], s[8:9], 0, v[136:137]
	s_mov_b32 m0, s46
	ds_read_b128 v[180:183], v155 offset:16384
	ds_read_b128 v[184:187], v155 offset:17408
	ds_read_b128 v[188:191], v155 offset:18432
	ds_read_b128 v[192:195], v155 offset:19456
	ds_read_b128 v[204:207], v155 offset:20480
	ds_read_b128 v[208:211], v155 offset:21504
	ds_read_b128 v[230:233], v155 offset:22528
	ds_read_b128 v[234:237], v155 offset:23552
	global_load_lds_dwordx4 v[196:197], off
	s_add_i32 m0, s46, 0x2000
	s_add_u32 s46, s8, 0x100000
	v_lshl_add_u64 v[198:199], s[8:9], 0, v[132:133]
	s_addc_u32 s47, s9, 0
	s_add_i32 s51, s51, s54
	global_load_lds_dwordx4 v[198:199], off
	v_lshl_add_u64 v[212:213], s[46:47], 0, v[136:137]
	s_mov_b32 m0, s51
	v_lshl_add_u64 v[214:215], s[42:43], 0, v[134:135]
	global_load_lds_dwordx4 v[212:213], off
	v_lshl_add_u64 v[212:213], s[46:47], 0, v[132:133]
	s_add_i32 m0, s51, 0x2000
	s_nop 0
	global_load_lds_dwordx4 v[212:213], off
	v_lshl_add_u64 v[212:213], s[42:43], 0, v[138:139]
	s_mov_b32 m0, s55
	s_nop 0
	global_load_lds_dwordx4 v[212:213], off
	s_mov_b32 m0, s56
	s_nop 0
	global_load_lds_dwordx4 v[214:215], off
	s_waitcnt vmcnt(8)
	s_waitcnt lgkmcnt(0)
	s_barrier
	v_mfma_f32_16x16x32_bf16 v[32:35], v[144:147], v[180:183], v[32:35]
	v_mfma_f32_16x16x32_bf16 v[28:31], v[156:159], v[180:183], v[28:31]
	v_mfma_f32_16x16x32_bf16 v[24:27], v[144:147], v[188:191], v[24:27]
	v_mfma_f32_16x16x32_bf16 v[20:23], v[156:159], v[188:191], v[20:23]
	v_mfma_f32_16x16x32_bf16 v[16:19], v[144:147], v[204:207], v[16:19]
	v_mfma_f32_16x16x32_bf16 v[12:15], v[156:159], v[204:207], v[12:15]
	v_mfma_f32_16x16x32_bf16 v[8:11], v[144:147], v[230:233], v[8:11]
	v_mfma_f32_16x16x32_bf16 v[4:7], v[156:159], v[230:233], v[4:7]
	v_mfma_f32_16x16x32_bf16 v[32:35], v[148:151], v[184:187], v[32:35]
	v_mfma_f32_16x16x32_bf16 v[28:31], v[160:163], v[184:187], v[28:31]
	v_mfma_f32_16x16x32_bf16 v[24:27], v[148:151], v[192:195], v[24:27]
	v_mfma_f32_16x16x32_bf16 v[20:23], v[160:163], v[192:195], v[20:23]
	v_mfma_f32_16x16x32_bf16 v[16:19], v[148:151], v[208:211], v[16:19]
	v_mfma_f32_16x16x32_bf16 v[12:15], v[160:163], v[208:211], v[12:15]
	v_mfma_f32_16x16x32_bf16 v[8:11], v[148:151], v[234:237], v[8:11]
	v_mfma_f32_16x16x32_bf16 v[4:7], v[160:163], v[234:237], v[4:7]
	v_mfma_f32_16x16x32_bf16 v[96:99], v[164:167], v[180:183], v[96:99]
	v_mfma_f32_16x16x32_bf16 v[92:95], v[172:175], v[180:183], v[92:95]
	v_mfma_f32_16x16x32_bf16 v[88:91], v[164:167], v[188:191], v[88:91]
	v_mfma_f32_16x16x32_bf16 v[84:87], v[172:175], v[188:191], v[84:87]
	v_mfma_f32_16x16x32_bf16 v[80:83], v[164:167], v[204:207], v[80:83]
	v_mfma_f32_16x16x32_bf16 v[76:79], v[172:175], v[204:207], v[76:79]
	v_mfma_f32_16x16x32_bf16 v[72:75], v[164:167], v[230:233], v[72:75]
	v_mfma_f32_16x16x32_bf16 v[68:71], v[172:175], v[230:233], v[68:71]
	v_mfma_f32_16x16x32_bf16 v[96:99], v[168:171], v[184:187], v[96:99]
	v_mfma_f32_16x16x32_bf16 v[92:95], v[176:179], v[184:187], v[92:95]
	v_mfma_f32_16x16x32_bf16 v[88:91], v[168:171], v[192:195], v[88:91]
	v_mfma_f32_16x16x32_bf16 v[84:87], v[176:179], v[192:195], v[84:87]
	v_mfma_f32_16x16x32_bf16 v[80:83], v[168:171], v[208:211], v[80:83]
	v_mfma_f32_16x16x32_bf16 v[76:79], v[176:179], v[208:211], v[76:79]
	v_mfma_f32_16x16x32_bf16 v[72:75], v[168:171], v[234:237], v[72:75]
	v_mfma_f32_16x16x32_bf16 v[68:71], v[176:179], v[234:237], v[68:71]
	s_barrier
	s_add_i32 s46, 0, 0x18000
	v_add_u32_e32 v2, s46, v154
	s_add_i32 s47, 0, 0x1c000
	ds_read_b128 v[144:147], v2
	ds_read_b128 v[148:151], v2 offset:1024
	ds_read_b128 v[156:159], v2 offset:2048
	ds_read_b128 v[160:163], v2 offset:3072
	v_add_u32_e32 v2, s47, v154
	ds_read_b128 v[164:167], v2
	ds_read_b128 v[168:171], v2 offset:1024
	ds_read_b128 v[172:175], v2 offset:2048
	ds_read_b128 v[176:179], v2 offset:3072
	s_add_u32 s42, s42, 0x100000
	s_addc_u32 s43, s43, 0
	s_mov_b32 m0, s57
	v_lshl_add_u64 v[226:227], s[42:43], 0, v[138:139]
	ds_read_b128 v[180:183], v155 offset:32768
	ds_read_b128 v[184:187], v155 offset:33792
	ds_read_b128 v[188:191], v155 offset:34816
	ds_read_b128 v[192:195], v155 offset:35840
	ds_read_b128 v[204:207], v155 offset:36864
	ds_read_b128 v[208:211], v155 offset:37888
	ds_read_b128 v[230:233], v155 offset:38912
	ds_read_b128 v[234:237], v155 offset:39936
	global_load_lds_dwordx4 v[226:227], off
	v_lshl_add_u64 v[226:227], s[42:43], 0, v[134:135]
	s_mov_b32 m0, s87
	s_nop 0
	global_load_lds_dwordx4 v[226:227], off
	s_waitcnt vmcnt(8)
	s_waitcnt lgkmcnt(0)
	s_barrier
	v_mfma_f32_16x16x32_bf16 v[64:67], v[144:147], v[180:183], v[64:67]
	v_mfma_f32_16x16x32_bf16 v[60:63], v[156:159], v[180:183], v[60:63]
	v_mfma_f32_16x16x32_bf16 v[56:59], v[144:147], v[188:191], v[56:59]
	v_mfma_f32_16x16x32_bf16 v[52:55], v[156:159], v[188:191], v[52:55]
	v_mfma_f32_16x16x32_bf16 v[48:51], v[144:147], v[204:207], v[48:51]
	v_mfma_f32_16x16x32_bf16 v[44:47], v[156:159], v[204:207], v[44:47]
	v_mfma_f32_16x16x32_bf16 v[40:43], v[144:147], v[230:233], v[40:43]
	v_mfma_f32_16x16x32_bf16 v[36:39], v[156:159], v[230:233], v[36:39]
	v_mfma_f32_16x16x32_bf16 v[64:67], v[148:151], v[184:187], v[64:67]
	v_mfma_f32_16x16x32_bf16 v[60:63], v[160:163], v[184:187], v[60:63]
	v_mfma_f32_16x16x32_bf16 v[56:59], v[148:151], v[192:195], v[56:59]
	v_mfma_f32_16x16x32_bf16 v[52:55], v[160:163], v[192:195], v[52:55]
	v_mfma_f32_16x16x32_bf16 v[48:51], v[148:151], v[208:211], v[48:51]
	v_mfma_f32_16x16x32_bf16 v[44:47], v[160:163], v[208:211], v[44:47]
	v_mfma_f32_16x16x32_bf16 v[40:43], v[148:151], v[234:237], v[40:43]
	v_mfma_f32_16x16x32_bf16 v[36:39], v[160:163], v[234:237], v[36:39]
	v_mfma_f32_16x16x32_bf16 v[128:131], v[164:167], v[180:183], v[128:131]
	v_mfma_f32_16x16x32_bf16 v[124:127], v[172:175], v[180:183], v[124:127]
	v_mfma_f32_16x16x32_bf16 v[120:123], v[164:167], v[188:191], v[120:123]
	v_mfma_f32_16x16x32_bf16 v[116:119], v[172:175], v[188:191], v[116:119]
	v_mfma_f32_16x16x32_bf16 v[112:115], v[164:167], v[204:207], v[112:115]
	v_mfma_f32_16x16x32_bf16 v[108:111], v[172:175], v[204:207], v[108:111]
	v_mfma_f32_16x16x32_bf16 v[104:107], v[164:167], v[230:233], v[104:107]
	v_mfma_f32_16x16x32_bf16 v[100:103], v[172:175], v[230:233], v[100:103]
	v_mfma_f32_16x16x32_bf16 v[128:131], v[168:171], v[184:187], v[128:131]
	v_mfma_f32_16x16x32_bf16 v[124:127], v[176:179], v[184:187], v[124:127]
	v_mfma_f32_16x16x32_bf16 v[120:123], v[168:171], v[192:195], v[120:123]
	v_mfma_f32_16x16x32_bf16 v[116:119], v[176:179], v[192:195], v[116:119]
	v_mfma_f32_16x16x32_bf16 v[112:115], v[168:171], v[208:211], v[112:115]
	v_mfma_f32_16x16x32_bf16 v[108:111], v[176:179], v[208:211], v[108:111]
	v_mfma_f32_16x16x32_bf16 v[104:107], v[168:171], v[234:237], v[104:107]
	v_mfma_f32_16x16x32_bf16 v[100:103], v[176:179], v[234:237], v[100:103]
	s_barrier
	s_add_i32 s42, s46, s54
	v_lshl_add_u64 v[196:197], v[196:197], 0, s[94:95]
	s_mov_b32 m0, s42
	ds_read_b128 v[180:183], v155 offset:49152
	ds_read_b128 v[184:187], v155 offset:50176
	ds_read_b128 v[188:191], v155 offset:51200
	ds_read_b128 v[192:195], v155 offset:52224
	ds_read_b128 v[204:207], v155 offset:53248
	ds_read_b128 v[208:211], v155 offset:54272
	ds_read_b128 v[230:233], v155 offset:55296
	ds_read_b128 v[234:237], v155 offset:56320
	global_load_lds_dwordx4 v[196:197], off
	s_add_i32 m0, s42, 0x2000
	s_add_u32 s8, s8, 0x100080
	v_lshl_add_u64 v[196:197], v[198:199], 0, s[94:95]
	s_addc_u32 s9, s9, 0
	s_add_i32 s42, s47, s54
	global_load_lds_dwordx4 v[196:197], off
	v_lshl_add_u64 v[196:197], s[8:9], 0, v[136:137]
	s_mov_b32 m0, s42
	s_nop 0
	global_load_lds_dwordx4 v[196:197], off
	v_lshl_add_u64 v[196:197], s[8:9], 0, v[132:133]
	s_add_i32 m0, s42, 0x2000
	s_nop 0
	global_load_lds_dwordx4 v[196:197], off
	v_lshl_add_u64 v[196:197], v[212:213], 0, s[94:95]
	s_mov_b32 m0, s59
	s_nop 0
	global_load_lds_dwordx4 v[196:197], off
	v_lshl_add_u64 v[196:197], v[214:215], 0, s[94:95]
	s_mov_b32 m0, s71
	s_nop 0
	global_load_lds_dwordx4 v[196:197], off
	s_waitcnt vmcnt(8)
	s_waitcnt lgkmcnt(0)
	s_barrier
	v_mfma_f32_16x16x32_bf16 v[32:35], v[144:147], v[180:183], v[32:35]
	v_mfma_f32_16x16x32_bf16 v[28:31], v[156:159], v[180:183], v[28:31]
	v_mfma_f32_16x16x32_bf16 v[24:27], v[144:147], v[188:191], v[24:27]
	v_mfma_f32_16x16x32_bf16 v[20:23], v[156:159], v[188:191], v[20:23]
	v_mfma_f32_16x16x32_bf16 v[16:19], v[144:147], v[204:207], v[16:19]
	v_mfma_f32_16x16x32_bf16 v[12:15], v[156:159], v[204:207], v[12:15]
	v_mfma_f32_16x16x32_bf16 v[8:11], v[144:147], v[230:233], v[8:11]
	v_mfma_f32_16x16x32_bf16 v[4:7], v[156:159], v[230:233], v[4:7]
	v_mfma_f32_16x16x32_bf16 v[32:35], v[148:151], v[184:187], v[32:35]
	v_mfma_f32_16x16x32_bf16 v[28:31], v[160:163], v[184:187], v[28:31]
	v_mfma_f32_16x16x32_bf16 v[24:27], v[148:151], v[192:195], v[24:27]
	v_mfma_f32_16x16x32_bf16 v[20:23], v[160:163], v[192:195], v[20:23]
	v_mfma_f32_16x16x32_bf16 v[16:19], v[148:151], v[208:211], v[16:19]
	v_mfma_f32_16x16x32_bf16 v[12:15], v[160:163], v[208:211], v[12:15]
	v_mfma_f32_16x16x32_bf16 v[8:11], v[148:151], v[234:237], v[8:11]
	v_mfma_f32_16x16x32_bf16 v[4:7], v[160:163], v[234:237], v[4:7]
	v_mfma_f32_16x16x32_bf16 v[96:99], v[164:167], v[180:183], v[96:99]
	v_mfma_f32_16x16x32_bf16 v[92:95], v[172:175], v[180:183], v[92:95]
	v_mfma_f32_16x16x32_bf16 v[88:91], v[164:167], v[188:191], v[88:91]
	v_mfma_f32_16x16x32_bf16 v[84:87], v[172:175], v[188:191], v[84:87]
	v_mfma_f32_16x16x32_bf16 v[80:83], v[164:167], v[204:207], v[80:83]
	v_mfma_f32_16x16x32_bf16 v[76:79], v[172:175], v[204:207], v[76:79]
	v_mfma_f32_16x16x32_bf16 v[72:75], v[164:167], v[230:233], v[72:75]
	v_mfma_f32_16x16x32_bf16 v[68:71], v[172:175], v[230:233], v[68:71]
	v_mfma_f32_16x16x32_bf16 v[96:99], v[168:171], v[184:187], v[96:99]
	v_mfma_f32_16x16x32_bf16 v[92:95], v[176:179], v[184:187], v[92:95]
	v_mfma_f32_16x16x32_bf16 v[88:91], v[168:171], v[192:195], v[88:91]
	v_mfma_f32_16x16x32_bf16 v[84:87], v[176:179], v[192:195], v[84:87]
	v_mfma_f32_16x16x32_bf16 v[80:83], v[168:171], v[208:211], v[80:83]
	v_mfma_f32_16x16x32_bf16 v[76:79], v[176:179], v[208:211], v[76:79]
	v_mfma_f32_16x16x32_bf16 v[72:75], v[168:171], v[234:237], v[72:75]
	v_mfma_f32_16x16x32_bf16 v[68:71], v[176:179], v[234:237], v[68:71]
	s_barrier
	s_add_i32 s45, s45, 2
	s_add_u32 s6, s6, 0x100
	s_addc_u32 s7, s7, 0
	s_add_u32 s40, s40, 0x100
	s_addc_u32 s44, s44, 0
	s_cmp_gt_u32 s45, 61
	s_cbranch_scc0 .LBB0_759
	s_and_b64 vcc, exec, s[18:19]
	s_cbranch_vccz .LBB0_762
	s_barrier

.LBB0_839:
	s_add_u32 s8, s6, 0xfff80080
	s_addc_u32 s9, s7, -1
	s_add_i32 s45, 0, 0x10000
	s_cmp_eq_u32 s44, 28
	s_cselect_b32 s11, s12, s9
	s_cselect_b32 s10, s13, s8
	v_add_u32_e32 v2, s45, v194
	s_cselect_b32 s9, s27, s43
	s_cselect_b32 s8, s29, s42
	s_add_i32 s62, 0, 0x14000
	ds_read_b128 v[30:33], v2
	ds_read_b128 v[34:37], v2 offset:1024
	ds_read_b128 v[46:49], v2 offset:2048
	ds_read_b128 v[50:53], v2 offset:3072
	v_add_u32_e32 v2, s62, v194
	ds_read_b128 v[162:165], v2
	ds_read_b128 v[166:169], v2 offset:1024
	ds_read_b128 v[170:173], v2 offset:2048
	ds_read_b128 v[174:177], v2 offset:3072
	v_lshl_add_u64 v[4:5], s[6:7], 0, v[158:159]
	s_add_i32 m0, s53, 0xc000
	ds_read_b128 v[178:181], v195
	ds_read_b128 v[182:185], v195 offset:1024
	ds_read_b128 v[186:189], v195 offset:2048
	ds_read_b128 v[204:207], v195 offset:3072
	ds_read_b128 v[208:211], v195 offset:4096
	ds_read_b128 v[230:233], v195 offset:5120
	ds_read_b128 v[234:237], v195 offset:6144
	ds_read_b128 v[238:241], v195 offset:7168
	global_load_lds_dwordx4 v[4:5], off
	v_lshl_add_u64 v[4:5], s[6:7], 0, v[160:161]
	s_add_i32 m0, s53, 0xe000
	s_nop 0
	global_load_lds_dwordx4 v[4:5], off
	s_waitcnt vmcnt(8)
	s_waitcnt lgkmcnt(0)
	s_barrier
	v_mfma_i32_16x16x64_i8 v[146:149], v[30:33], v[178:181], v[146:149]
	v_mfma_i32_16x16x64_i8 v[142:145], v[46:49], v[178:181], v[142:145]
	v_mfma_i32_16x16x64_i8 v[130:133], v[30:33], v[186:189], v[130:133]
	v_mfma_i32_16x16x64_i8 v[126:129], v[46:49], v[186:189], v[126:129]
	v_mfma_i32_16x16x64_i8 v[114:117], v[30:33], v[208:211], v[114:117]
	v_mfma_i32_16x16x64_i8 v[110:113], v[46:49], v[208:211], v[110:113]
	v_mfma_i32_16x16x64_i8 v[98:101], v[30:33], v[234:237], v[98:101]
	v_mfma_i32_16x16x64_i8 v[94:97], v[46:49], v[234:237], v[94:97]
	v_mfma_i32_16x16x64_i8 v[146:149], v[34:37], v[182:185], v[146:149]
	v_mfma_i32_16x16x64_i8 v[142:145], v[50:53], v[182:185], v[142:145]
	v_mfma_i32_16x16x64_i8 v[130:133], v[34:37], v[204:207], v[130:133]
	v_mfma_i32_16x16x64_i8 v[126:129], v[50:53], v[204:207], v[126:129]
	v_mfma_i32_16x16x64_i8 v[114:117], v[34:37], v[230:233], v[114:117]
	v_mfma_i32_16x16x64_i8 v[110:113], v[50:53], v[230:233], v[110:113]
	v_mfma_i32_16x16x64_i8 v[98:101], v[34:37], v[238:241], v[98:101]
	v_mfma_i32_16x16x64_i8 v[94:97], v[50:53], v[238:241], v[94:97]
	v_mfma_i32_16x16x64_i8 v[138:141], v[162:165], v[178:181], v[138:141]
	v_mfma_i32_16x16x64_i8 v[134:137], v[170:173], v[178:181], v[134:137]
	v_mfma_i32_16x16x64_i8 v[122:125], v[162:165], v[186:189], v[122:125]
	v_mfma_i32_16x16x64_i8 v[118:121], v[170:173], v[186:189], v[118:121]
	v_mfma_i32_16x16x64_i8 v[106:109], v[162:165], v[208:211], v[106:109]
	v_mfma_i32_16x16x64_i8 v[102:105], v[170:173], v[208:211], v[102:105]
	v_mfma_i32_16x16x64_i8 v[90:93], v[162:165], v[234:237], v[90:93]
	v_mfma_i32_16x16x64_i8 v[86:89], v[170:173], v[234:237], v[86:89]
	v_mfma_i32_16x16x64_i8 v[138:141], v[166:169], v[182:185], v[138:141]
	v_mfma_i32_16x16x64_i8 v[134:137], v[174:177], v[182:185], v[134:137]
	v_mfma_i32_16x16x64_i8 v[122:125], v[166:169], v[204:207], v[122:125]
	v_mfma_i32_16x16x64_i8 v[118:121], v[174:177], v[204:207], v[118:121]
	v_mfma_i32_16x16x64_i8 v[106:109], v[166:169], v[230:233], v[106:109]
	v_mfma_i32_16x16x64_i8 v[102:105], v[174:177], v[230:233], v[102:105]
	v_mfma_i32_16x16x64_i8 v[90:93], v[166:169], v[238:241], v[90:93]
	v_mfma_i32_16x16x64_i8 v[86:89], v[174:177], v[238:241], v[86:89]
	s_barrier
	s_add_i32 s45, s45, s52
	v_lshl_add_u64 v[190:191], s[8:9], 0, v[154:155]
	s_mov_b32 m0, s45
	ds_read_b128 v[178:181], v195 offset:16384
	ds_read_b128 v[182:185], v195 offset:17408
	ds_read_b128 v[186:189], v195 offset:18432
	ds_read_b128 v[204:207], v195 offset:19456
	ds_read_b128 v[208:211], v195 offset:20480
	ds_read_b128 v[230:233], v195 offset:21504
	ds_read_b128 v[234:237], v195 offset:22528
	ds_read_b128 v[238:241], v195 offset:23552
	global_load_lds_dwordx4 v[190:191], off
	s_add_i32 m0, s45, 0x2000
	s_add_u32 s48, s8, 0x80000
	v_lshl_add_u64 v[196:197], s[8:9], 0, v[150:151]
	s_addc_u32 s49, s9, 0
	s_add_i32 s45, s62, s52
	global_load_lds_dwordx4 v[196:197], off
	v_lshl_add_u64 v[4:5], s[48:49], 0, v[154:155]
	s_mov_b32 m0, s45
	v_lshl_add_u64 v[198:199], s[10:11], 0, v[156:157]
	global_load_lds_dwordx4 v[4:5], off
	v_lshl_add_u64 v[4:5], s[48:49], 0, v[150:151]
	s_add_i32 m0, s45, 0x2000
	v_lshl_add_u64 v[212:213], s[10:11], 0, v[152:153]
	global_load_lds_dwordx4 v[4:5], off
	s_mov_b32 m0, s53
	s_nop 0
	global_load_lds_dwordx4 v[198:199], off
	s_mov_b32 m0, s54
	s_nop 0
	global_load_lds_dwordx4 v[212:213], off
	s_waitcnt vmcnt(8)
	s_waitcnt lgkmcnt(0)
	s_barrier
	v_mfma_i32_16x16x64_i8 v[82:85], v[30:33], v[178:181], v[82:85]
	v_mfma_i32_16x16x64_i8 v[78:81], v[46:49], v[178:181], v[78:81]
	v_mfma_i32_16x16x64_i8 v[66:69], v[30:33], v[186:189], v[66:69]
	v_mfma_i32_16x16x64_i8 v[62:65], v[46:49], v[186:189], v[62:65]
	v_mfma_i32_16x16x64_i8 v[42:45], v[30:33], v[208:211], v[42:45]
	v_mfma_i32_16x16x64_i8 v[38:41], v[46:49], v[208:211], v[38:41]
	v_mfma_i32_16x16x64_i8 v[18:21], v[30:33], v[234:237], v[18:21]
	v_mfma_i32_16x16x64_i8 v[14:17], v[46:49], v[234:237], v[14:17]
	v_mfma_i32_16x16x64_i8 v[82:85], v[34:37], v[182:185], v[82:85]
	v_mfma_i32_16x16x64_i8 v[78:81], v[50:53], v[182:185], v[78:81]
	v_mfma_i32_16x16x64_i8 v[66:69], v[34:37], v[204:207], v[66:69]
	v_mfma_i32_16x16x64_i8 v[62:65], v[50:53], v[204:207], v[62:65]
	v_mfma_i32_16x16x64_i8 v[42:45], v[34:37], v[230:233], v[42:45]
	v_mfma_i32_16x16x64_i8 v[38:41], v[50:53], v[230:233], v[38:41]
	v_mfma_i32_16x16x64_i8 v[18:21], v[34:37], v[238:241], v[18:21]
	v_mfma_i32_16x16x64_i8 v[14:17], v[50:53], v[238:241], v[14:17]
	v_mfma_i32_16x16x64_i8 v[26:29], v[162:165], v[208:211], v[26:29]
	v_mfma_i32_16x16x64_i8 v[22:25], v[170:173], v[208:211], v[22:25]
	v_mfma_i32_16x16x64_i8 v[10:13], v[162:165], v[234:237], v[10:13]
	v_mfma_i32_16x16x64_i8 v[4:7], v[170:173], v[234:237], v[6:9]
	v_mfma_i32_16x16x64_i8 v[30:33], v[162:165], v[178:181], v[74:77]
	v_mfma_i32_16x16x64_i8 v[34:37], v[170:173], v[178:181], v[70:73]
	v_mfma_i32_16x16x64_i8 v[46:49], v[162:165], v[186:189], v[58:61]
	v_mfma_i32_16x16x64_i8 v[50:53], v[170:173], v[186:189], v[54:57]
	v_mfma_i32_16x16x64_i8 v[26:29], v[166:169], v[230:233], v[26:29]
	v_mfma_i32_16x16x64_i8 v[22:25], v[174:177], v[230:233], v[22:25]
	v_mfma_i32_16x16x64_i8 v[10:13], v[166:169], v[238:241], v[10:13]
	v_mfma_i32_16x16x64_i8 v[4:7], v[174:177], v[238:241], v[4:7]
	v_mfma_i32_16x16x64_i8 v[30:33], v[166:169], v[182:185], v[30:33]
	v_mfma_i32_16x16x64_i8 v[34:37], v[174:177], v[182:185], v[34:37]
	v_mfma_i32_16x16x64_i8 v[46:49], v[166:169], v[204:207], v[46:49]
	v_mfma_i32_16x16x64_i8 v[50:53], v[174:177], v[204:207], v[50:53]
	s_barrier
	s_add_i32 s45, 0, 0x18000
	v_add_u32_e32 v2, s45, v194
	s_add_i32 s48, 0, 0x1c000
	ds_read_b128 v[54:57], v2
	ds_read_b128 v[58:61], v2 offset:1024
	ds_read_b128 v[70:73], v2 offset:2048
	ds_read_b128 v[74:77], v2 offset:3072
	v_add_u32_e32 v2, s48, v194
	ds_read_b128 v[162:165], v2
	ds_read_b128 v[166:169], v2 offset:1024
	ds_read_b128 v[170:173], v2 offset:2048
	ds_read_b128 v[174:177], v2 offset:3072
	s_add_u32 s10, s10, 0x80000
	s_addc_u32 s11, s11, 0
	s_mov_b32 m0, s55
	v_lshl_add_u64 v[8:9], s[10:11], 0, v[156:157]
	ds_read_b128 v[178:181], v195 offset:32768
	ds_read_b128 v[182:185], v195 offset:33792
	ds_read_b128 v[186:189], v195 offset:34816
	ds_read_b128 v[204:207], v195 offset:35840
	ds_read_b128 v[208:211], v195 offset:36864
	ds_read_b128 v[230:233], v195 offset:37888
	ds_read_b128 v[234:237], v195 offset:38912
	ds_read_b128 v[238:241], v195 offset:39936
	global_load_lds_dwordx4 v[8:9], off
	v_lshl_add_u64 v[8:9], s[10:11], 0, v[152:153]
	s_mov_b32 m0, s56
	s_nop 0
	global_load_lds_dwordx4 v[8:9], off
	s_waitcnt vmcnt(8)
	s_waitcnt lgkmcnt(0)
	s_barrier
	v_mfma_i32_16x16x64_i8 v[146:149], v[54:57], v[178:181], v[146:149]
	v_mfma_i32_16x16x64_i8 v[142:145], v[70:73], v[178:181], v[142:145]
	v_mfma_i32_16x16x64_i8 v[130:133], v[54:57], v[186:189], v[130:133]
	v_mfma_i32_16x16x64_i8 v[126:129], v[70:73], v[186:189], v[126:129]
	v_mfma_i32_16x16x64_i8 v[114:117], v[54:57], v[208:211], v[114:117]
	v_mfma_i32_16x16x64_i8 v[110:113], v[70:73], v[208:211], v[110:113]
	v_mfma_i32_16x16x64_i8 v[98:101], v[54:57], v[234:237], v[98:101]
	v_mfma_i32_16x16x64_i8 v[94:97], v[70:73], v[234:237], v[94:97]
	v_mfma_i32_16x16x64_i8 v[146:149], v[58:61], v[182:185], v[146:149]
	v_mfma_i32_16x16x64_i8 v[142:145], v[74:77], v[182:185], v[142:145]
	v_mfma_i32_16x16x64_i8 v[130:133], v[58:61], v[204:207], v[130:133]
	v_mfma_i32_16x16x64_i8 v[126:129], v[74:77], v[204:207], v[126:129]
	v_mfma_i32_16x16x64_i8 v[114:117], v[58:61], v[230:233], v[114:117]
	v_mfma_i32_16x16x64_i8 v[110:113], v[74:77], v[230:233], v[110:113]
	v_mfma_i32_16x16x64_i8 v[98:101], v[58:61], v[238:241], v[98:101]
	v_mfma_i32_16x16x64_i8 v[94:97], v[74:77], v[238:241], v[94:97]
	v_mfma_i32_16x16x64_i8 v[138:141], v[162:165], v[178:181], v[138:141]
	v_mfma_i32_16x16x64_i8 v[134:137], v[170:173], v[178:181], v[134:137]
	v_mfma_i32_16x16x64_i8 v[122:125], v[162:165], v[186:189], v[122:125]
	v_mfma_i32_16x16x64_i8 v[118:121], v[170:173], v[186:189], v[118:121]
	v_mfma_i32_16x16x64_i8 v[106:109], v[162:165], v[208:211], v[106:109]
	v_mfma_i32_16x16x64_i8 v[102:105], v[170:173], v[208:211], v[102:105]
	v_mfma_i32_16x16x64_i8 v[90:93], v[162:165], v[234:237], v[90:93]
	v_mfma_i32_16x16x64_i8 v[86:89], v[170:173], v[234:237], v[86:89]
	v_mfma_i32_16x16x64_i8 v[138:141], v[166:169], v[182:185], v[138:141]
	v_mfma_i32_16x16x64_i8 v[134:137], v[174:177], v[182:185], v[134:137]
	v_mfma_i32_16x16x64_i8 v[122:125], v[166:169], v[204:207], v[122:125]
	v_mfma_i32_16x16x64_i8 v[118:121], v[174:177], v[204:207], v[118:121]
	v_mfma_i32_16x16x64_i8 v[106:109], v[166:169], v[230:233], v[106:109]
	v_mfma_i32_16x16x64_i8 v[102:105], v[174:177], v[230:233], v[102:105]
	v_mfma_i32_16x16x64_i8 v[90:93], v[166:169], v[238:241], v[90:93]
	v_mfma_i32_16x16x64_i8 v[86:89], v[174:177], v[238:241], v[86:89]
	s_barrier
	s_add_i32 s10, s45, s52
	v_lshl_add_u64 v[8:9], v[190:191], 0, s[94:95]
	s_mov_b32 m0, s10
	ds_read_b128 v[178:181], v195 offset:49152
	ds_read_b128 v[182:185], v195 offset:50176
	ds_read_b128 v[186:189], v195 offset:51200
	ds_read_b128 v[204:207], v195 offset:52224
	ds_read_b128 v[208:211], v195 offset:53248
	ds_read_b128 v[230:233], v195 offset:54272
	ds_read_b128 v[234:237], v195 offset:55296
	ds_read_b128 v[238:241], v195 offset:56320
	global_load_lds_dwordx4 v[8:9], off
	s_add_i32 m0, s10, 0x2000
	s_add_u32 s8, s8, 0x80080
	v_lshl_add_u64 v[8:9], v[196:197], 0, s[94:95]
	s_addc_u32 s9, s9, 0
	s_add_i32 s10, s48, s52
	global_load_lds_dwordx4 v[8:9], off
	v_lshl_add_u64 v[8:9], s[8:9], 0, v[154:155]
	s_mov_b32 m0, s10
	s_nop 0
	global_load_lds_dwordx4 v[8:9], off
	v_lshl_add_u64 v[8:9], s[8:9], 0, v[150:151]
	s_add_i32 m0, s10, 0x2000
	s_nop 0
	global_load_lds_dwordx4 v[8:9], off
	v_lshl_add_u64 v[8:9], v[198:199], 0, s[94:95]
	s_mov_b32 m0, s71
	s_nop 0
	global_load_lds_dwordx4 v[8:9], off
	v_lshl_add_u64 v[8:9], v[212:213], 0, s[94:95]
	s_mov_b32 m0, s74
	s_nop 0
	global_load_lds_dwordx4 v[8:9], off
	s_waitcnt vmcnt(8)
	s_waitcnt lgkmcnt(0)
	s_barrier
	v_mfma_i32_16x16x64_i8 v[82:85], v[54:57], v[178:181], v[82:85]
	v_mfma_i32_16x16x64_i8 v[78:81], v[70:73], v[178:181], v[78:81]
	v_mfma_i32_16x16x64_i8 v[66:69], v[54:57], v[186:189], v[66:69]
	v_mfma_i32_16x16x64_i8 v[62:65], v[70:73], v[186:189], v[62:65]
	v_mfma_i32_16x16x64_i8 v[42:45], v[54:57], v[208:211], v[42:45]
	v_mfma_i32_16x16x64_i8 v[38:41], v[70:73], v[208:211], v[38:41]
	v_mfma_i32_16x16x64_i8 v[18:21], v[54:57], v[234:237], v[18:21]
	v_mfma_i32_16x16x64_i8 v[14:17], v[70:73], v[234:237], v[14:17]
	v_mfma_i32_16x16x64_i8 v[82:85], v[58:61], v[182:185], v[82:85]
	v_mfma_i32_16x16x64_i8 v[78:81], v[74:77], v[182:185], v[78:81]
	v_mfma_i32_16x16x64_i8 v[66:69], v[58:61], v[204:207], v[66:69]
	v_mfma_i32_16x16x64_i8 v[62:65], v[74:77], v[204:207], v[62:65]
	v_mfma_i32_16x16x64_i8 v[42:45], v[58:61], v[230:233], v[42:45]
	v_mfma_i32_16x16x64_i8 v[38:41], v[74:77], v[230:233], v[38:41]
	v_mfma_i32_16x16x64_i8 v[18:21], v[58:61], v[238:241], v[18:21]
	v_mfma_i32_16x16x64_i8 v[14:17], v[74:77], v[238:241], v[14:17]
	v_mfma_i32_16x16x64_i8 v[30:33], v[162:165], v[178:181], v[30:33]
	v_mfma_i32_16x16x64_i8 v[74:77], v[166:169], v[182:185], v[30:33]
	v_mfma_i32_16x16x64_i8 v[30:33], v[170:173], v[178:181], v[34:37]
	v_mfma_i32_16x16x64_i8 v[70:73], v[174:177], v[182:185], v[30:33]
	v_mfma_i32_16x16x64_i8 v[30:33], v[162:165], v[186:189], v[46:49]
	v_mfma_i32_16x16x64_i8 v[58:61], v[166:169], v[204:207], v[30:33]
	v_mfma_i32_16x16x64_i8 v[30:33], v[170:173], v[186:189], v[50:53]
	v_mfma_i32_16x16x64_i8 v[26:29], v[162:165], v[208:211], v[26:29]
	v_mfma_i32_16x16x64_i8 v[22:25], v[170:173], v[208:211], v[22:25]
	v_mfma_i32_16x16x64_i8 v[8:11], v[162:165], v[234:237], v[10:13]
	v_mfma_i32_16x16x64_i8 v[4:7], v[170:173], v[234:237], v[4:7]
	v_mfma_i32_16x16x64_i8 v[54:57], v[174:177], v[204:207], v[30:33]
	v_mfma_i32_16x16x64_i8 v[26:29], v[166:169], v[230:233], v[26:29]
	v_mfma_i32_16x16x64_i8 v[22:25], v[174:177], v[230:233], v[22:25]
	v_mfma_i32_16x16x64_i8 v[10:13], v[166:169], v[238:241], v[8:11]
	v_mfma_i32_16x16x64_i8 v[6:9], v[174:177], v[238:241], v[4:7]
	s_barrier
	s_add_i32 s44, s44, 2
	s_add_u32 s6, s6, 0x100
	s_addc_u32 s7, s7, 0
	s_add_u32 s42, s42, 0x100
	s_addc_u32 s43, s43, 0
	s_cmp_gt_u32 s44, 29
	s_cbranch_scc0 .LBB0_839
	s_and_b64 vcc, exec, s[20:21]
	s_cbranch_vccz .LBB0_842
	s_barrier

.LBB0_1151:
	s_add_u32 s6, s26, 0x100
	s_addc_u32 s7, s27, 0
	s_add_i32 s53, 0, 0x10000
	s_cmp_eq_u32 s52, 20
	s_cselect_b32 s31, s23, s7
	s_cselect_b32 s30, s22, s6
	v_add_u32_e32 v2, s53, v232
	s_cselect_b32 s29, s25, s51
	s_cselect_b32 s28, s24, s49
	s_add_i32 s54, 0, 0x14000
	ds_read_b128 v[108:111], v2
	ds_read_b128 v[112:115], v2 offset:1024
	ds_read_b128 v[120:123], v2 offset:2048
	ds_read_b128 v[128:131], v2 offset:3072
	v_add_u32_e32 v2, s54, v232
	ds_read_b128 v[136:139], v2
	ds_read_b128 v[140:143], v2 offset:1024
	ds_read_b128 v[148:151], v2 offset:2048
	ds_read_b128 v[152:155], v2 offset:3072
	v_lshl_add_u64 v[196:197], s[26:27], 0, v[172:173]
	s_add_i32 m0, s34, 0xc000
	ds_read_b128 v[176:179], v233
	ds_read_b128 v[180:183], v233 offset:1024
	ds_read_b128 v[184:187], v233 offset:2048
	ds_read_b128 v[188:191], v233 offset:3072
	ds_read_b128 v[192:195], v233 offset:4096
	ds_read_b128 v[204:207], v233 offset:5120
	ds_read_b128 v[208:211], v233 offset:6144
	ds_read_b128 v[234:237], v233 offset:7168
	global_load_lds_dwordx4 v[196:197], off
	v_lshl_add_u64 v[196:197], s[26:27], 0, v[174:175]
	s_add_i32 m0, s34, 0xe000
	s_nop 0
	global_load_lds_dwordx4 v[196:197], off
	s_waitcnt vmcnt(8)
	s_waitcnt lgkmcnt(0)
	s_barrier
	v_mfma_f32_16x16x32_bf16 v[160:163], v[108:111], v[176:179], v[160:163]
	v_mfma_f32_16x16x32_bf16 v[156:159], v[120:123], v[176:179], v[156:159]
	v_mfma_f32_16x16x32_bf16 v[124:127], v[108:111], v[184:187], v[124:127]
	v_mfma_f32_16x16x32_bf16 v[116:119], v[120:123], v[184:187], v[116:119]
	v_mfma_f32_16x16x32_bf16 v[96:99], v[108:111], v[192:195], v[96:99]
	v_mfma_f32_16x16x32_bf16 v[92:95], v[120:123], v[192:195], v[92:95]
	v_mfma_f32_16x16x32_bf16 v[80:83], v[108:111], v[208:211], v[80:83]
	v_mfma_f32_16x16x32_bf16 v[76:79], v[120:123], v[208:211], v[76:79]
	v_mfma_f32_16x16x32_bf16 v[160:163], v[112:115], v[180:183], v[160:163]
	v_mfma_f32_16x16x32_bf16 v[156:159], v[128:131], v[180:183], v[156:159]
	v_mfma_f32_16x16x32_bf16 v[124:127], v[112:115], v[188:191], v[124:127]
	v_mfma_f32_16x16x32_bf16 v[116:119], v[128:131], v[188:191], v[116:119]
	v_mfma_f32_16x16x32_bf16 v[96:99], v[112:115], v[204:207], v[96:99]
	v_mfma_f32_16x16x32_bf16 v[92:95], v[128:131], v[204:207], v[92:95]
	v_mfma_f32_16x16x32_bf16 v[80:83], v[112:115], v[234:237], v[80:83]
	v_mfma_f32_16x16x32_bf16 v[76:79], v[128:131], v[234:237], v[76:79]
	v_mfma_f32_16x16x32_bf16 v[144:147], v[136:139], v[176:179], v[144:147]
	v_mfma_f32_16x16x32_bf16 v[132:135], v[148:151], v[176:179], v[132:135]
	v_mfma_f32_16x16x32_bf16 v[104:107], v[136:139], v[184:187], v[104:107]
	v_mfma_f32_16x16x32_bf16 v[100:103], v[148:151], v[184:187], v[100:103]
	v_mfma_f32_16x16x32_bf16 v[88:91], v[136:139], v[192:195], v[88:91]
	v_mfma_f32_16x16x32_bf16 v[84:87], v[148:151], v[192:195], v[84:87]
	v_mfma_f32_16x16x32_bf16 v[72:75], v[136:139], v[208:211], v[72:75]
	v_mfma_f32_16x16x32_bf16 v[68:71], v[148:151], v[208:211], v[68:71]
	v_mfma_f32_16x16x32_bf16 v[144:147], v[140:143], v[180:183], v[144:147]
	v_mfma_f32_16x16x32_bf16 v[132:135], v[152:155], v[180:183], v[132:135]
	v_mfma_f32_16x16x32_bf16 v[104:107], v[140:143], v[188:191], v[104:107]
	v_mfma_f32_16x16x32_bf16 v[100:103], v[152:155], v[188:191], v[100:103]
	v_mfma_f32_16x16x32_bf16 v[88:91], v[140:143], v[204:207], v[88:91]
	v_mfma_f32_16x16x32_bf16 v[84:87], v[152:155], v[204:207], v[84:87]
	v_mfma_f32_16x16x32_bf16 v[72:75], v[140:143], v[234:237], v[72:75]
	v_mfma_f32_16x16x32_bf16 v[68:71], v[152:155], v[234:237], v[68:71]
	s_barrier
	s_add_i32 s26, s53, s33
	v_lshl_add_u64 v[196:197], s[28:29], 0, v[168:169]
	s_mov_b32 m0, s26
	ds_read_b128 v[176:179], v233 offset:16384
	ds_read_b128 v[180:183], v233 offset:17408
	ds_read_b128 v[184:187], v233 offset:18432
	ds_read_b128 v[188:191], v233 offset:19456
	ds_read_b128 v[192:195], v233 offset:20480
	ds_read_b128 v[204:207], v233 offset:21504
	ds_read_b128 v[208:211], v233 offset:22528
	ds_read_b128 v[234:237], v233 offset:23552
	global_load_lds_dwordx4 v[196:197], off
	s_add_i32 m0, s26, 0x2000
	s_add_u32 s26, s28, 0x60000
	v_lshl_add_u64 v[198:199], s[28:29], 0, v[164:165]
	s_addc_u32 s27, s29, 0
	s_add_i32 s53, s54, s33
	global_load_lds_dwordx4 v[198:199], off
	v_lshl_add_u64 v[212:213], s[26:27], 0, v[168:169]
	s_mov_b32 m0, s53
	v_lshl_add_u64 v[214:215], s[30:31], 0, v[166:167]
	global_load_lds_dwordx4 v[212:213], off
	v_lshl_add_u64 v[212:213], s[26:27], 0, v[164:165]
	s_add_i32 m0, s53, 0x2000
	s_nop 0
	global_load_lds_dwordx4 v[212:213], off
	v_lshl_add_u64 v[212:213], s[30:31], 0, v[170:171]
	s_mov_b32 m0, s34
	s_nop 0
	global_load_lds_dwordx4 v[212:213], off
	s_mov_b32 m0, s35
	s_nop 0
	global_load_lds_dwordx4 v[214:215], off
	s_waitcnt vmcnt(8)
	s_waitcnt lgkmcnt(0)
	s_barrier
	v_mfma_f32_16x16x32_bf16 v[64:67], v[108:111], v[176:179], v[64:67]
	v_mfma_f32_16x16x32_bf16 v[60:63], v[120:123], v[176:179], v[60:63]
	v_mfma_f32_16x16x32_bf16 v[48:51], v[108:111], v[184:187], v[48:51]
	v_mfma_f32_16x16x32_bf16 v[44:47], v[120:123], v[184:187], v[44:47]
	v_mfma_f32_16x16x32_bf16 v[32:35], v[108:111], v[192:195], v[32:35]
	v_mfma_f32_16x16x32_bf16 v[28:31], v[120:123], v[192:195], v[28:31]
	v_mfma_f32_16x16x32_bf16 v[16:19], v[108:111], v[208:211], v[16:19]
	v_mfma_f32_16x16x32_bf16 v[12:15], v[120:123], v[208:211], v[12:15]
	v_mfma_f32_16x16x32_bf16 v[64:67], v[112:115], v[180:183], v[64:67]
	v_mfma_f32_16x16x32_bf16 v[60:63], v[128:131], v[180:183], v[60:63]
	v_mfma_f32_16x16x32_bf16 v[48:51], v[112:115], v[188:191], v[48:51]
	v_mfma_f32_16x16x32_bf16 v[44:47], v[128:131], v[188:191], v[44:47]
	v_mfma_f32_16x16x32_bf16 v[32:35], v[112:115], v[204:207], v[32:35]
	v_mfma_f32_16x16x32_bf16 v[28:31], v[128:131], v[204:207], v[28:31]
	v_mfma_f32_16x16x32_bf16 v[16:19], v[112:115], v[234:237], v[16:19]
	v_mfma_f32_16x16x32_bf16 v[12:15], v[128:131], v[234:237], v[12:15]
	v_mfma_f32_16x16x32_bf16 v[56:59], v[136:139], v[176:179], v[56:59]
	v_mfma_f32_16x16x32_bf16 v[52:55], v[148:151], v[176:179], v[52:55]
	v_mfma_f32_16x16x32_bf16 v[40:43], v[136:139], v[184:187], v[40:43]
	v_mfma_f32_16x16x32_bf16 v[36:39], v[148:151], v[184:187], v[36:39]
	v_mfma_f32_16x16x32_bf16 v[24:27], v[136:139], v[192:195], v[24:27]
	v_mfma_f32_16x16x32_bf16 v[20:23], v[148:151], v[192:195], v[20:23]
	v_mfma_f32_16x16x32_bf16 v[8:11], v[136:139], v[208:211], v[8:11]
	v_mfma_f32_16x16x32_bf16 v[4:7], v[148:151], v[208:211], v[4:7]
	v_mfma_f32_16x16x32_bf16 v[56:59], v[140:143], v[180:183], v[56:59]
	v_mfma_f32_16x16x32_bf16 v[52:55], v[152:155], v[180:183], v[52:55]
	v_mfma_f32_16x16x32_bf16 v[40:43], v[140:143], v[188:191], v[40:43]
	v_mfma_f32_16x16x32_bf16 v[36:39], v[152:155], v[188:191], v[36:39]
	v_mfma_f32_16x16x32_bf16 v[24:27], v[140:143], v[204:207], v[24:27]
	v_mfma_f32_16x16x32_bf16 v[20:23], v[152:155], v[204:207], v[20:23]
	v_mfma_f32_16x16x32_bf16 v[8:11], v[140:143], v[234:237], v[8:11]
	v_mfma_f32_16x16x32_bf16 v[4:7], v[152:155], v[234:237], v[4:7]
	s_barrier
	s_add_i32 s53, 0, 0x18000
	v_add_u32_e32 v2, s53, v232
	s_add_i32 s54, 0, 0x1c000
	ds_read_b128 v[108:111], v2
	ds_read_b128 v[112:115], v2 offset:1024
	ds_read_b128 v[120:123], v2 offset:2048
	ds_read_b128 v[128:131], v2 offset:3072
	v_add_u32_e32 v2, s54, v232
	ds_read_b128 v[136:139], v2
	ds_read_b128 v[140:143], v2 offset:1024
	ds_read_b128 v[148:151], v2 offset:2048
	ds_read_b128 v[152:155], v2 offset:3072
	s_add_u32 s26, s30, 0x60000
	s_addc_u32 s27, s31, 0
	s_mov_b32 m0, s36
	v_lshl_add_u64 v[226:227], s[26:27], 0, v[170:171]
	ds_read_b128 v[176:179], v233 offset:32768
	ds_read_b128 v[180:183], v233 offset:33792
	ds_read_b128 v[184:187], v233 offset:34816
	ds_read_b128 v[188:191], v233 offset:35840
	ds_read_b128 v[192:195], v233 offset:36864
	ds_read_b128 v[204:207], v233 offset:37888
	ds_read_b128 v[208:211], v233 offset:38912
	ds_read_b128 v[234:237], v233 offset:39936
	global_load_lds_dwordx4 v[226:227], off
	v_lshl_add_u64 v[226:227], s[26:27], 0, v[166:167]
	s_mov_b32 m0, s37
	s_nop 0
	global_load_lds_dwordx4 v[226:227], off
	s_waitcnt vmcnt(8)
	s_waitcnt lgkmcnt(0)
	s_barrier
	v_mfma_f32_16x16x32_bf16 v[160:163], v[108:111], v[176:179], v[160:163]
	v_mfma_f32_16x16x32_bf16 v[156:159], v[120:123], v[176:179], v[156:159]
	v_mfma_f32_16x16x32_bf16 v[124:127], v[108:111], v[184:187], v[124:127]
	v_mfma_f32_16x16x32_bf16 v[116:119], v[120:123], v[184:187], v[116:119]
	v_mfma_f32_16x16x32_bf16 v[96:99], v[108:111], v[192:195], v[96:99]
	v_mfma_f32_16x16x32_bf16 v[92:95], v[120:123], v[192:195], v[92:95]
	v_mfma_f32_16x16x32_bf16 v[80:83], v[108:111], v[208:211], v[80:83]
	v_mfma_f32_16x16x32_bf16 v[76:79], v[120:123], v[208:211], v[76:79]
	v_mfma_f32_16x16x32_bf16 v[160:163], v[112:115], v[180:183], v[160:163]
	v_mfma_f32_16x16x32_bf16 v[156:159], v[128:131], v[180:183], v[156:159]
	v_mfma_f32_16x16x32_bf16 v[124:127], v[112:115], v[188:191], v[124:127]
	v_mfma_f32_16x16x32_bf16 v[116:119], v[128:131], v[188:191], v[116:119]
	v_mfma_f32_16x16x32_bf16 v[96:99], v[112:115], v[204:207], v[96:99]
	v_mfma_f32_16x16x32_bf16 v[92:95], v[128:131], v[204:207], v[92:95]
	v_mfma_f32_16x16x32_bf16 v[80:83], v[112:115], v[234:237], v[80:83]
	v_mfma_f32_16x16x32_bf16 v[76:79], v[128:131], v[234:237], v[76:79]
	v_mfma_f32_16x16x32_bf16 v[144:147], v[136:139], v[176:179], v[144:147]
	v_mfma_f32_16x16x32_bf16 v[132:135], v[148:151], v[176:179], v[132:135]
	v_mfma_f32_16x16x32_bf16 v[104:107], v[136:139], v[184:187], v[104:107]
	v_mfma_f32_16x16x32_bf16 v[100:103], v[148:151], v[184:187], v[100:103]
	v_mfma_f32_16x16x32_bf16 v[88:91], v[136:139], v[192:195], v[88:91]
	v_mfma_f32_16x16x32_bf16 v[84:87], v[148:151], v[192:195], v[84:87]
	v_mfma_f32_16x16x32_bf16 v[72:75], v[136:139], v[208:211], v[72:75]
	v_mfma_f32_16x16x32_bf16 v[68:71], v[148:151], v[208:211], v[68:71]
	v_mfma_f32_16x16x32_bf16 v[144:147], v[140:143], v[180:183], v[144:147]
	v_mfma_f32_16x16x32_bf16 v[132:135], v[152:155], v[180:183], v[132:135]
	v_mfma_f32_16x16x32_bf16 v[104:107], v[140:143], v[188:191], v[104:107]
	v_mfma_f32_16x16x32_bf16 v[100:103], v[152:155], v[188:191], v[100:103]
	v_mfma_f32_16x16x32_bf16 v[88:91], v[140:143], v[204:207], v[88:91]
	v_mfma_f32_16x16x32_bf16 v[84:87], v[152:155], v[204:207], v[84:87]
	v_mfma_f32_16x16x32_bf16 v[72:75], v[140:143], v[234:237], v[72:75]
	v_mfma_f32_16x16x32_bf16 v[68:71], v[152:155], v[234:237], v[68:71]
	s_barrier
	s_add_i32 s26, s53, s33
	v_lshl_add_u64 v[196:197], v[196:197], 0, s[94:95]
	s_mov_b32 m0, s26
	ds_read_b128 v[176:179], v233 offset:49152
	ds_read_b128 v[180:183], v233 offset:50176
	ds_read_b128 v[184:187], v233 offset:51200
	ds_read_b128 v[188:191], v233 offset:52224
	ds_read_b128 v[192:195], v233 offset:53248
	ds_read_b128 v[204:207], v233 offset:54272
	ds_read_b128 v[208:211], v233 offset:55296
	ds_read_b128 v[234:237], v233 offset:56320
	global_load_lds_dwordx4 v[196:197], off
	s_add_i32 m0, s26, 0x2000
	s_add_u32 s26, s28, 0x60080
	v_lshl_add_u64 v[196:197], v[198:199], 0, s[94:95]
	s_addc_u32 s27, s29, 0
	s_add_i32 s28, s54, s33
	global_load_lds_dwordx4 v[196:197], off
	v_lshl_add_u64 v[196:197], s[26:27], 0, v[168:169]
	s_mov_b32 m0, s28
	s_nop 0
	global_load_lds_dwordx4 v[196:197], off
	v_lshl_add_u64 v[196:197], s[26:27], 0, v[164:165]
	s_add_i32 m0, s28, 0x2000
	s_nop 0
	global_load_lds_dwordx4 v[196:197], off
	v_lshl_add_u64 v[196:197], v[212:213], 0, s[94:95]
	s_mov_b32 m0, s42
	s_nop 0
	global_load_lds_dwordx4 v[196:197], off
	v_lshl_add_u64 v[196:197], v[214:215], 0, s[94:95]
	s_mov_b32 m0, s43
	s_nop 0
	global_load_lds_dwordx4 v[196:197], off
	s_waitcnt vmcnt(8)
	s_waitcnt lgkmcnt(0)
	s_barrier
	v_mfma_f32_16x16x32_bf16 v[64:67], v[108:111], v[176:179], v[64:67]
	v_mfma_f32_16x16x32_bf16 v[60:63], v[120:123], v[176:179], v[60:63]
	v_mfma_f32_16x16x32_bf16 v[48:51], v[108:111], v[184:187], v[48:51]
	v_mfma_f32_16x16x32_bf16 v[44:47], v[120:123], v[184:187], v[44:47]
	v_mfma_f32_16x16x32_bf16 v[32:35], v[108:111], v[192:195], v[32:35]
	v_mfma_f32_16x16x32_bf16 v[28:31], v[120:123], v[192:195], v[28:31]
	v_mfma_f32_16x16x32_bf16 v[16:19], v[108:111], v[208:211], v[16:19]
	v_mfma_f32_16x16x32_bf16 v[12:15], v[120:123], v[208:211], v[12:15]
	v_mfma_f32_16x16x32_bf16 v[64:67], v[112:115], v[180:183], v[64:67]
	v_mfma_f32_16x16x32_bf16 v[60:63], v[128:131], v[180:183], v[60:63]
	v_mfma_f32_16x16x32_bf16 v[48:51], v[112:115], v[188:191], v[48:51]
	v_mfma_f32_16x16x32_bf16 v[44:47], v[128:131], v[188:191], v[44:47]
	v_mfma_f32_16x16x32_bf16 v[32:35], v[112:115], v[204:207], v[32:35]
	v_mfma_f32_16x16x32_bf16 v[28:31], v[128:131], v[204:207], v[28:31]
	v_mfma_f32_16x16x32_bf16 v[16:19], v[112:115], v[234:237], v[16:19]
	v_mfma_f32_16x16x32_bf16 v[12:15], v[128:131], v[234:237], v[12:15]
	v_mfma_f32_16x16x32_bf16 v[56:59], v[136:139], v[176:179], v[56:59]
	v_mfma_f32_16x16x32_bf16 v[52:55], v[148:151], v[176:179], v[52:55]
	v_mfma_f32_16x16x32_bf16 v[40:43], v[136:139], v[184:187], v[40:43]
	v_mfma_f32_16x16x32_bf16 v[36:39], v[148:151], v[184:187], v[36:39]
	v_mfma_f32_16x16x32_bf16 v[24:27], v[136:139], v[192:195], v[24:27]
	v_mfma_f32_16x16x32_bf16 v[20:23], v[148:151], v[192:195], v[20:23]
	v_mfma_f32_16x16x32_bf16 v[8:11], v[136:139], v[208:211], v[8:11]
	v_mfma_f32_16x16x32_bf16 v[4:7], v[148:151], v[208:211], v[4:7]
	v_mfma_f32_16x16x32_bf16 v[56:59], v[140:143], v[180:183], v[56:59]
	v_mfma_f32_16x16x32_bf16 v[52:55], v[152:155], v[180:183], v[52:55]
	v_mfma_f32_16x16x32_bf16 v[40:43], v[140:143], v[188:191], v[40:43]
	v_mfma_f32_16x16x32_bf16 v[36:39], v[152:155], v[188:191], v[36:39]
	v_mfma_f32_16x16x32_bf16 v[24:27], v[140:143], v[204:207], v[24:27]
	v_mfma_f32_16x16x32_bf16 v[20:23], v[152:155], v[204:207], v[20:23]
	v_mfma_f32_16x16x32_bf16 v[8:11], v[140:143], v[234:237], v[8:11]
	v_mfma_f32_16x16x32_bf16 v[4:7], v[152:155], v[234:237], v[4:7]
	s_barrier
	s_add_i32 s52, s52, 2
	s_add_u32 s49, s49, 0x100
	s_addc_u32 s51, s51, 0
	s_cmp_gt_u32 s52, 21
	s_mov_b64 s[26:27], s[6:7]
	s_cbranch_scc0 .LBB0_1151
	s_and_b64 vcc, exec, s[10:11]
	s_cbranch_vccz .LBB0_1154
	s_barrier

.LBB0_1203:
	s_add_u32 s26, s24, 0xfffe0080
	s_addc_u32 s27, s25, -1
	s_add_i32 s51, 0, 0x10000
	s_cmp_eq_u32 s49, 4
	s_cselect_b32 s29, s19, s27
	s_cselect_b32 s28, s45, s26
	v_add_u32_e32 v154, s51, v158
	s_cselect_b32 s27, s17, s48
	s_cselect_b32 s26, s46, s47
	s_add_i32 s54, 0, 0x14000
	ds_read_b128 v[142:145], v154
	ds_read_b128 v[146:149], v154 offset:1024
	ds_read_b128 v[150:153], v154 offset:2048
	ds_read_b128 v[160:163], v154 offset:3072
	v_add_u32_e32 v154, s54, v158
	ds_read_b128 v[164:167], v154
	ds_read_b128 v[168:171], v154 offset:1024
	ds_read_b128 v[172:175], v154 offset:2048
	ds_read_b128 v[176:179], v154 offset:3072
	v_lshl_add_u64 v[154:155], s[24:25], 0, v[138:139]
	s_add_i32 m0, s31, 0xc000
	ds_read_b128 v[180:183], v159
	ds_read_b128 v[184:187], v159 offset:1024
	ds_read_b128 v[188:191], v159 offset:2048
	ds_read_b128 v[192:195], v159 offset:3072
	ds_read_b128 v[204:207], v159 offset:4096
	ds_read_b128 v[208:211], v159 offset:5120
	ds_read_b128 v[230:233], v159 offset:6144
	ds_read_b128 v[234:237], v159 offset:7168
	global_load_lds_dwordx4 v[154:155], off
	v_lshl_add_u64 v[154:155], s[24:25], 0, v[140:141]
	s_add_i32 m0, s31, 0xe000
	s_nop 0
	global_load_lds_dwordx4 v[154:155], off
	s_waitcnt vmcnt(8)
	s_waitcnt lgkmcnt(0)
	s_barrier
	v_mfma_f32_16x16x32_bf16 v[128:131], v[142:145], v[180:183], v[128:131]
	v_mfma_f32_16x16x32_bf16 v[124:127], v[150:153], v[180:183], v[124:127]
	v_mfma_f32_16x16x32_bf16 v[112:115], v[142:145], v[188:191], v[112:115]
	v_mfma_f32_16x16x32_bf16 v[108:111], v[150:153], v[188:191], v[108:111]
	v_mfma_f32_16x16x32_bf16 v[96:99], v[142:145], v[204:207], v[96:99]
	v_mfma_f32_16x16x32_bf16 v[92:95], v[150:153], v[204:207], v[92:95]
	v_mfma_f32_16x16x32_bf16 v[80:83], v[142:145], v[230:233], v[80:83]
	v_mfma_f32_16x16x32_bf16 v[76:79], v[150:153], v[230:233], v[76:79]
	v_mfma_f32_16x16x32_bf16 v[128:131], v[146:149], v[184:187], v[128:131]
	v_mfma_f32_16x16x32_bf16 v[124:127], v[160:163], v[184:187], v[124:127]
	v_mfma_f32_16x16x32_bf16 v[112:115], v[146:149], v[192:195], v[112:115]
	v_mfma_f32_16x16x32_bf16 v[108:111], v[160:163], v[192:195], v[108:111]
	v_mfma_f32_16x16x32_bf16 v[96:99], v[146:149], v[208:211], v[96:99]
	v_mfma_f32_16x16x32_bf16 v[92:95], v[160:163], v[208:211], v[92:95]
	v_mfma_f32_16x16x32_bf16 v[80:83], v[146:149], v[234:237], v[80:83]
	v_mfma_f32_16x16x32_bf16 v[76:79], v[160:163], v[234:237], v[76:79]
	v_mfma_f32_16x16x32_bf16 v[120:123], v[164:167], v[180:183], v[120:123]
	v_mfma_f32_16x16x32_bf16 v[116:119], v[172:175], v[180:183], v[116:119]
	v_mfma_f32_16x16x32_bf16 v[104:107], v[164:167], v[188:191], v[104:107]
	v_mfma_f32_16x16x32_bf16 v[100:103], v[172:175], v[188:191], v[100:103]
	v_mfma_f32_16x16x32_bf16 v[88:91], v[164:167], v[204:207], v[88:91]
	v_mfma_f32_16x16x32_bf16 v[84:87], v[172:175], v[204:207], v[84:87]
	v_mfma_f32_16x16x32_bf16 v[72:75], v[164:167], v[230:233], v[72:75]
	v_mfma_f32_16x16x32_bf16 v[68:71], v[172:175], v[230:233], v[68:71]
	v_mfma_f32_16x16x32_bf16 v[120:123], v[168:171], v[184:187], v[120:123]
	v_mfma_f32_16x16x32_bf16 v[116:119], v[176:179], v[184:187], v[116:119]
	v_mfma_f32_16x16x32_bf16 v[104:107], v[168:171], v[192:195], v[104:107]
	v_mfma_f32_16x16x32_bf16 v[100:103], v[176:179], v[192:195], v[100:103]
	v_mfma_f32_16x16x32_bf16 v[88:91], v[168:171], v[208:211], v[88:91]
	v_mfma_f32_16x16x32_bf16 v[84:87], v[176:179], v[208:211], v[84:87]
	v_mfma_f32_16x16x32_bf16 v[72:75], v[168:171], v[234:237], v[72:75]
	v_mfma_f32_16x16x32_bf16 v[68:71], v[176:179], v[234:237], v[68:71]
	s_barrier
	s_add_i32 s51, s51, s30
	v_lshl_add_u64 v[154:155], s[26:27], 0, v[2:3]
	s_mov_b32 m0, s51
	ds_read_b128 v[180:183], v159 offset:16384
	ds_read_b128 v[184:187], v159 offset:17408
	ds_read_b128 v[188:191], v159 offset:18432
	ds_read_b128 v[192:195], v159 offset:19456
	ds_read_b128 v[204:207], v159 offset:20480
	ds_read_b128 v[208:211], v159 offset:21504
	ds_read_b128 v[230:233], v159 offset:22528
	ds_read_b128 v[234:237], v159 offset:23552
	global_load_lds_dwordx4 v[154:155], off
	s_add_i32 m0, s51, 0x2000
	s_add_u32 s52, s26, 0x20000
	v_lshl_add_u64 v[196:197], s[26:27], 0, v[132:133]
	s_addc_u32 s53, s27, 0
	s_add_i32 s51, s54, s30
	global_load_lds_dwordx4 v[196:197], off
	v_lshl_add_u64 v[198:199], s[52:53], 0, v[2:3]
	s_mov_b32 m0, s51
	v_lshl_add_u64 v[212:213], s[28:29], 0, v[134:135]
	global_load_lds_dwordx4 v[198:199], off
	v_lshl_add_u64 v[198:199], s[52:53], 0, v[132:133]
	s_add_i32 m0, s51, 0x2000
	s_nop 0
	global_load_lds_dwordx4 v[198:199], off
	v_lshl_add_u64 v[198:199], s[28:29], 0, v[136:137]
	s_mov_b32 m0, s31
	s_nop 0
	global_load_lds_dwordx4 v[198:199], off
	s_mov_b32 m0, s33
	s_nop 0
	global_load_lds_dwordx4 v[212:213], off
	s_waitcnt vmcnt(8)
	s_waitcnt lgkmcnt(0)
	s_barrier
	v_mfma_f32_16x16x32_bf16 v[64:67], v[142:145], v[180:183], v[64:67]
	v_mfma_f32_16x16x32_bf16 v[60:63], v[150:153], v[180:183], v[60:63]
	v_mfma_f32_16x16x32_bf16 v[48:51], v[142:145], v[188:191], v[48:51]
	v_mfma_f32_16x16x32_bf16 v[44:47], v[150:153], v[188:191], v[44:47]
	v_mfma_f32_16x16x32_bf16 v[32:35], v[142:145], v[204:207], v[32:35]
	v_mfma_f32_16x16x32_bf16 v[28:31], v[150:153], v[204:207], v[28:31]
	v_mfma_f32_16x16x32_bf16 v[16:19], v[142:145], v[230:233], v[16:19]
	v_mfma_f32_16x16x32_bf16 v[12:15], v[150:153], v[230:233], v[12:15]
	v_mfma_f32_16x16x32_bf16 v[64:67], v[146:149], v[184:187], v[64:67]
	v_mfma_f32_16x16x32_bf16 v[60:63], v[160:163], v[184:187], v[60:63]
	v_mfma_f32_16x16x32_bf16 v[48:51], v[146:149], v[192:195], v[48:51]
	v_mfma_f32_16x16x32_bf16 v[44:47], v[160:163], v[192:195], v[44:47]
	v_mfma_f32_16x16x32_bf16 v[32:35], v[146:149], v[208:211], v[32:35]
	v_mfma_f32_16x16x32_bf16 v[28:31], v[160:163], v[208:211], v[28:31]
	v_mfma_f32_16x16x32_bf16 v[16:19], v[146:149], v[234:237], v[16:19]
	v_mfma_f32_16x16x32_bf16 v[12:15], v[160:163], v[234:237], v[12:15]
	v_mfma_f32_16x16x32_bf16 v[56:59], v[164:167], v[180:183], v[56:59]
	v_mfma_f32_16x16x32_bf16 v[52:55], v[172:175], v[180:183], v[52:55]
	v_mfma_f32_16x16x32_bf16 v[40:43], v[164:167], v[188:191], v[40:43]
	v_mfma_f32_16x16x32_bf16 v[36:39], v[172:175], v[188:191], v[36:39]
	v_mfma_f32_16x16x32_bf16 v[24:27], v[164:167], v[204:207], v[24:27]
	v_mfma_f32_16x16x32_bf16 v[20:23], v[172:175], v[204:207], v[20:23]
	v_mfma_f32_16x16x32_bf16 v[8:11], v[164:167], v[230:233], v[8:11]
	v_mfma_f32_16x16x32_bf16 v[4:7], v[172:175], v[230:233], v[4:7]
	v_mfma_f32_16x16x32_bf16 v[56:59], v[168:171], v[184:187], v[56:59]
	v_mfma_f32_16x16x32_bf16 v[52:55], v[176:179], v[184:187], v[52:55]
	v_mfma_f32_16x16x32_bf16 v[40:43], v[168:171], v[192:195], v[40:43]
	v_mfma_f32_16x16x32_bf16 v[36:39], v[176:179], v[192:195], v[36:39]
	v_mfma_f32_16x16x32_bf16 v[24:27], v[168:171], v[208:211], v[24:27]
	v_mfma_f32_16x16x32_bf16 v[20:23], v[176:179], v[208:211], v[20:23]
	v_mfma_f32_16x16x32_bf16 v[8:11], v[168:171], v[234:237], v[8:11]
	v_mfma_f32_16x16x32_bf16 v[4:7], v[176:179], v[234:237], v[4:7]
	s_barrier
	s_add_i32 s51, 0, 0x18000
	s_add_i32 s52, 0, 0x1c000
	v_add_u32_e32 v160, s51, v158
	v_add_u32_e32 v176, s52, v158
	ds_read_b128 v[142:145], v160
	ds_read_b128 v[146:149], v160 offset:1024
	ds_read_b128 v[150:153], v160 offset:2048
	ds_read_b128 v[160:163], v160 offset:3072
	ds_read_b128 v[164:167], v176
	ds_read_b128 v[168:171], v176 offset:1024
	ds_read_b128 v[172:175], v176 offset:2048
	ds_read_b128 v[176:179], v176 offset:3072
	s_add_u32 s28, s28, 0x20000
	s_addc_u32 s29, s29, 0
	s_mov_b32 m0, s34
	v_lshl_add_u64 v[214:215], s[28:29], 0, v[136:137]
	ds_read_b128 v[180:183], v159 offset:32768
	ds_read_b128 v[184:187], v159 offset:33792
	ds_read_b128 v[188:191], v159 offset:34816
	ds_read_b128 v[192:195], v159 offset:35840
	ds_read_b128 v[204:207], v159 offset:36864
	ds_read_b128 v[208:211], v159 offset:37888
	ds_read_b128 v[230:233], v159 offset:38912
	ds_read_b128 v[234:237], v159 offset:39936
	global_load_lds_dwordx4 v[214:215], off
	v_lshl_add_u64 v[214:215], s[28:29], 0, v[134:135]
	s_mov_b32 m0, s35
	s_nop 0
	global_load_lds_dwordx4 v[214:215], off
	s_waitcnt vmcnt(8)
	s_waitcnt lgkmcnt(0)
	s_barrier
	v_mfma_f32_16x16x32_bf16 v[128:131], v[142:145], v[180:183], v[128:131]
	v_mfma_f32_16x16x32_bf16 v[124:127], v[150:153], v[180:183], v[124:127]
	v_mfma_f32_16x16x32_bf16 v[112:115], v[142:145], v[188:191], v[112:115]
	v_mfma_f32_16x16x32_bf16 v[108:111], v[150:153], v[188:191], v[108:111]
	v_mfma_f32_16x16x32_bf16 v[96:99], v[142:145], v[204:207], v[96:99]
	v_mfma_f32_16x16x32_bf16 v[92:95], v[150:153], v[204:207], v[92:95]
	v_mfma_f32_16x16x32_bf16 v[80:83], v[142:145], v[230:233], v[80:83]
	v_mfma_f32_16x16x32_bf16 v[76:79], v[150:153], v[230:233], v[76:79]
	v_mfma_f32_16x16x32_bf16 v[128:131], v[146:149], v[184:187], v[128:131]
	v_mfma_f32_16x16x32_bf16 v[124:127], v[160:163], v[184:187], v[124:127]
	v_mfma_f32_16x16x32_bf16 v[112:115], v[146:149], v[192:195], v[112:115]
	v_mfma_f32_16x16x32_bf16 v[108:111], v[160:163], v[192:195], v[108:111]
	v_mfma_f32_16x16x32_bf16 v[96:99], v[146:149], v[208:211], v[96:99]
	v_mfma_f32_16x16x32_bf16 v[92:95], v[160:163], v[208:211], v[92:95]
	v_mfma_f32_16x16x32_bf16 v[80:83], v[146:149], v[234:237], v[80:83]
	v_mfma_f32_16x16x32_bf16 v[76:79], v[160:163], v[234:237], v[76:79]
	v_mfma_f32_16x16x32_bf16 v[120:123], v[164:167], v[180:183], v[120:123]
	v_mfma_f32_16x16x32_bf16 v[116:119], v[172:175], v[180:183], v[116:119]
	v_mfma_f32_16x16x32_bf16 v[104:107], v[164:167], v[188:191], v[104:107]
	v_mfma_f32_16x16x32_bf16 v[100:103], v[172:175], v[188:191], v[100:103]
	v_mfma_f32_16x16x32_bf16 v[88:91], v[164:167], v[204:207], v[88:91]
	v_mfma_f32_16x16x32_bf16 v[84:87], v[172:175], v[204:207], v[84:87]
	v_mfma_f32_16x16x32_bf16 v[72:75], v[164:167], v[230:233], v[72:75]
	v_mfma_f32_16x16x32_bf16 v[68:71], v[172:175], v[230:233], v[68:71]
	v_mfma_f32_16x16x32_bf16 v[120:123], v[168:171], v[184:187], v[120:123]
	v_mfma_f32_16x16x32_bf16 v[116:119], v[176:179], v[184:187], v[116:119]
	v_mfma_f32_16x16x32_bf16 v[104:107], v[168:171], v[192:195], v[104:107]
	v_mfma_f32_16x16x32_bf16 v[100:103], v[176:179], v[192:195], v[100:103]
	v_mfma_f32_16x16x32_bf16 v[88:91], v[168:171], v[208:211], v[88:91]
	v_mfma_f32_16x16x32_bf16 v[84:87], v[176:179], v[208:211], v[84:87]
	v_mfma_f32_16x16x32_bf16 v[72:75], v[168:171], v[234:237], v[72:75]
	v_mfma_f32_16x16x32_bf16 v[68:71], v[176:179], v[234:237], v[68:71]
	s_barrier
	s_add_i32 s28, s51, s30
	v_lshl_add_u64 v[154:155], v[154:155], 0, s[94:95]
	s_mov_b32 m0, s28
	ds_read_b128 v[180:183], v159 offset:49152
	ds_read_b128 v[184:187], v159 offset:50176
	ds_read_b128 v[188:191], v159 offset:51200
	ds_read_b128 v[192:195], v159 offset:52224
	ds_read_b128 v[204:207], v159 offset:53248
	ds_read_b128 v[208:211], v159 offset:54272
	ds_read_b128 v[230:233], v159 offset:55296
	ds_read_b128 v[234:237], v159 offset:56320
	global_load_lds_dwordx4 v[154:155], off
	s_add_i32 m0, s28, 0x2000
	s_add_u32 s26, s26, 0x20080
	v_lshl_add_u64 v[154:155], v[196:197], 0, s[94:95]
	s_addc_u32 s27, s27, 0
	s_add_i32 s28, s52, s30
	global_load_lds_dwordx4 v[154:155], off
	v_lshl_add_u64 v[154:155], s[26:27], 0, v[2:3]
	s_mov_b32 m0, s28
	s_nop 0
	global_load_lds_dwordx4 v[154:155], off
	v_lshl_add_u64 v[154:155], s[26:27], 0, v[132:133]
	s_add_i32 m0, s28, 0x2000
	s_nop 0
	global_load_lds_dwordx4 v[154:155], off
	v_lshl_add_u64 v[154:155], v[198:199], 0, s[94:95]
	s_mov_b32 m0, s39
	s_nop 0
	global_load_lds_dwordx4 v[154:155], off
	v_lshl_add_u64 v[154:155], v[212:213], 0, s[94:95]
	s_mov_b32 m0, s40
	s_nop 0
	global_load_lds_dwordx4 v[154:155], off
	s_waitcnt vmcnt(8)
	s_waitcnt lgkmcnt(0)
	s_barrier
	v_mfma_f32_16x16x32_bf16 v[64:67], v[142:145], v[180:183], v[64:67]
	v_mfma_f32_16x16x32_bf16 v[60:63], v[150:153], v[180:183], v[60:63]
	v_mfma_f32_16x16x32_bf16 v[48:51], v[142:145], v[188:191], v[48:51]
	v_mfma_f32_16x16x32_bf16 v[44:47], v[150:153], v[188:191], v[44:47]
	v_mfma_f32_16x16x32_bf16 v[32:35], v[142:145], v[204:207], v[32:35]
	v_mfma_f32_16x16x32_bf16 v[28:31], v[150:153], v[204:207], v[28:31]
	v_mfma_f32_16x16x32_bf16 v[16:19], v[142:145], v[230:233], v[16:19]
	v_mfma_f32_16x16x32_bf16 v[12:15], v[150:153], v[230:233], v[12:15]
	v_mfma_f32_16x16x32_bf16 v[64:67], v[146:149], v[184:187], v[64:67]
	v_mfma_f32_16x16x32_bf16 v[60:63], v[160:163], v[184:187], v[60:63]
	v_mfma_f32_16x16x32_bf16 v[48:51], v[146:149], v[192:195], v[48:51]
	v_mfma_f32_16x16x32_bf16 v[44:47], v[160:163], v[192:195], v[44:47]
	v_mfma_f32_16x16x32_bf16 v[32:35], v[146:149], v[208:211], v[32:35]
	v_mfma_f32_16x16x32_bf16 v[28:31], v[160:163], v[208:211], v[28:31]
	v_mfma_f32_16x16x32_bf16 v[16:19], v[146:149], v[234:237], v[16:19]
	v_mfma_f32_16x16x32_bf16 v[12:15], v[160:163], v[234:237], v[12:15]
	v_mfma_f32_16x16x32_bf16 v[56:59], v[164:167], v[180:183], v[56:59]
	v_mfma_f32_16x16x32_bf16 v[52:55], v[172:175], v[180:183], v[52:55]
	v_mfma_f32_16x16x32_bf16 v[40:43], v[164:167], v[188:191], v[40:43]
	v_mfma_f32_16x16x32_bf16 v[36:39], v[172:175], v[188:191], v[36:39]
	v_mfma_f32_16x16x32_bf16 v[24:27], v[164:167], v[204:207], v[24:27]
	v_mfma_f32_16x16x32_bf16 v[20:23], v[172:175], v[204:207], v[20:23]
	v_mfma_f32_16x16x32_bf16 v[8:11], v[164:167], v[230:233], v[8:11]
	v_mfma_f32_16x16x32_bf16 v[4:7], v[172:175], v[230:233], v[4:7]
	v_mfma_f32_16x16x32_bf16 v[56:59], v[168:171], v[184:187], v[56:59]
	v_mfma_f32_16x16x32_bf16 v[52:55], v[176:179], v[184:187], v[52:55]
	v_mfma_f32_16x16x32_bf16 v[40:43], v[168:171], v[192:195], v[40:43]
	v_mfma_f32_16x16x32_bf16 v[36:39], v[176:179], v[192:195], v[36:39]
	v_mfma_f32_16x16x32_bf16 v[24:27], v[168:171], v[208:211], v[24:27]
	v_mfma_f32_16x16x32_bf16 v[20:23], v[176:179], v[208:211], v[20:23]
	v_mfma_f32_16x16x32_bf16 v[8:11], v[168:171], v[234:237], v[8:11]
	v_mfma_f32_16x16x32_bf16 v[4:7], v[176:179], v[234:237], v[4:7]
	s_barrier
	s_add_i32 s49, s49, 2
	s_add_u32 s24, s24, 0x100
	s_addc_u32 s25, s25, 0
	s_add_u32 s47, s47, 0x100
	s_addc_u32 s48, s48, 0
	s_cmp_gt_u32 s49, 5
	s_cbranch_scc0 .LBB0_1203
	s_and_b64 vcc, exec, s[10:11]
	s_cbranch_vccz .LBB0_1206
	s_barrier

.LBB0_1923:
	s_or_b64 exec, exec, s[6:7]
	s_waitcnt lgkmcnt(0)
	v_lshl_add_u32 v2, v191, 4, s47
	ds_read_b128 v[68:71], v2
	ds_read_b128 v[72:75], v2 offset:32
	s_or_b32 s1, s34, s87
	s_ashr_i32 s6, s48, 31
	s_add_u32 s8, s1, s48
	s_addc_u32 s9, s35, s6
	s_mul_i32 s1, s9, 0x3000
	s_mul_hi_u32 s6, s8, 0x3000
	s_waitcnt lgkmcnt(1)
	v_rcp_f32_e32 v87, v68
	v_rcp_f32_e32 v85, v69
	v_rcp_f32_e32 v84, v70
	v_rcp_f32_e32 v83, v71
	ds_read_b128 v[68:71], v2 offset:64
	s_add_i32 s6, s6, s1
	s_mul_i32 s1, s8, 0x3000
	s_add_u32 s1, s52, s1
	s_addc_u32 s7, s4, s6
	s_add_u32 s6, s1, s0
	s_addc_u32 s7, s7, 0
	s_lshl_b64 s[8:9], s[8:9], 12
	s_waitcnt lgkmcnt(1)
	v_rcp_f32_e32 v77, v75
	s_waitcnt lgkmcnt(0)
	v_rcp_f32_e32 v80, v68
	v_rcp_f32_e32 v78, v69
	v_rcp_f32_e32 v76, v70
	v_rcp_f32_e32 v75, v71
	ds_read_b128 v[68:71], v2 offset:96
	s_add_u32 s1, s36, s8
	s_addc_u32 s9, s37, s9
	s_add_u32 s8, s1, s0
	v_and_b32_e32 v2, 56, v190
	s_addc_u32 s9, s9, 0
	s_mulk_i32 s46, 0x2200
	v_lshlrev_b32_e32 v89, 2, v2
	v_lshlrev_b32_e32 v2, 1, v2
	s_add_i32 s0, s46, 0
	v_rcp_f32_e32 v82, v72
	v_rcp_f32_e32 v81, v73
	v_rcp_f32_e32 v79, v74
	s_waitcnt lgkmcnt(0)
	v_rcp_f32_e32 v86, v68
	v_rcp_f32_e32 v74, v69
	v_rcp_f32_e32 v73, v70
	v_rcp_f32_e32 v72, v71
	v_lshlrev_b32_e32 v88, 2, v189
	v_lshl_add_u64 v[70:71], s[8:9], 0, v[2:3]
	v_lshl_add_u64 v[68:69], s[6:7], 0, v[2:3]
	v_mul_f32_e32 v2, v52, v87
	v_mul_u32_u24_e32 v52, 0x440, v191
	v_add3_u32 v88, s0, v88, v52
	v_mul_f32_e32 v36, v36, v87
	v_mul_f32_e32 v52, v53, v85
	ds_write2_b32 v88, v2, v36 offset1:32
	v_mul_f32_e32 v2, v37, v85
	v_mul_f32_e32 v53, v54, v84
	ds_write2_b32 v88, v52, v2 offset0:68 offset1:100
	v_mul_f32_e32 v2, v38, v84
	v_mul_f32_e32 v54, v55, v83
	ds_write2_b32 v88, v53, v2 offset0:136 offset1:168
	v_mul_f32_e32 v2, v39, v83
	v_mul_f32_e32 v55, v56, v82
	v_mul_f32_e32 v91, v64, v86
	ds_write2_b32 v88, v54, v2 offset0:204 offset1:236
	v_mul_f32_e32 v2, v40, v82
	v_add_u32_e32 v64, 0x800, v88
	v_mul_f32_e32 v56, v57, v81
	ds_write2_b32 v64, v55, v2 offset0:32 offset1:64
	v_mul_f32_e32 v2, v41, v81
	v_mul_f32_e32 v57, v58, v79
	ds_write2_b32 v64, v56, v2 offset0:100 offset1:132
	v_mul_f32_e32 v2, v42, v79
	v_mul_f32_e32 v58, v59, v77
	v_mul_f32_e32 v92, v65, v74
	ds_write2_b32 v64, v57, v2 offset0:168 offset1:200
	v_mul_f32_e32 v2, v43, v77
	v_add_u32_e32 v65, 0xa00, v88
	v_mul_f32_e32 v59, v60, v80
	v_mul_f32_e32 v60, v61, v78
	v_mul_f32_e32 v61, v62, v76
	ds_write2_b32 v65, v58, v2 offset0:108 offset1:140
	v_mul_f32_e32 v2, v44, v80
	v_add_u32_e32 v62, 0x1000, v88
	ds_write2_b32 v62, v59, v2 offset0:64 offset1:96
	v_mul_f32_e32 v2, v45, v78
	ds_write2_b32 v62, v60, v2 offset0:132 offset1:164
	v_mul_f32_e32 v2, v46, v76
	v_mul_f32_e32 v90, v63, v75
	ds_write2_b32 v62, v61, v2 offset0:200 offset1:232
	v_mul_f32_e32 v2, v47, v75
	v_add_u32_e32 v63, 0x1400, v88
	ds_write2_b32 v63, v90, v2 offset0:12 offset1:44
	v_mul_f32_e32 v2, v48, v86
	v_add_u32_e32 v59, 0x1800, v88
	ds_write2_b32 v59, v91, v2 offset0:96 offset1:128
	v_mul_f32_e32 v2, v49, v74
	v_mul_f32_e32 v66, v66, v73
	ds_write2_b32 v59, v92, v2 offset0:164 offset1:196
	v_mul_f32_e32 v2, v50, v73
	v_add_u32_e32 v60, 0x1a00, v88
	v_mul_f32_e32 v67, v67, v72
	ds_write2_b32 v60, v66, v2 offset0:104 offset1:136
	v_mul_f32_e32 v2, v51, v72
	v_add_u32_e32 v61, 0x1c00, v88
	v_lshrrev_b32_e32 v46, 3, v188
	ds_write2_b32 v61, v67, v2 offset0:44 offset1:76
	v_mul_u32_u24_e32 v2, 0x110, v46
	v_add3_u32 v58, s0, v89, v2
	v_lshlrev_b32_e32 v2, 12, v46
	s_waitcnt lgkmcnt(0)
	v_lshl_add_u64 v[56:57], v[70:71], 0, v[2:3]
	ds_read_b128 v[36:39], v58
	ds_read_b128 v[40:43], v58 offset:16
	s_mov_b64 s[98:99], 0x8000
	v_lshl_add_u64 v[164:165], v[56:57], 0, s[98:99]
	v_lshl_add_u64 v[166:167], v[164:165], 0, s[98:99]
	v_lshl_add_u64 v[168:169], v[166:167], 0, s[98:99]
	global_load_dwordx4 v[132:135], v[56:57], off
	global_load_dwordx4 v[136:139], v[164:165], off
	global_load_dwordx4 v[140:143], v[166:167], off
	global_load_dwordx4 v[144:147], v[168:169], off
	global_load_dwordx4 v[148:151], v[56:57], off offset:128
	global_load_dwordx4 v[152:155], v[164:165], off offset:128
	global_load_dwordx4 v[156:159], v[166:167], off offset:128
	global_load_dwordx4 v[160:163], v[168:169], off offset:128
	v_or_b32_e32 v47, 8, v46
	v_mul_f32_e32 v4, v4, v87
	s_waitcnt vmcnt(7)
	v_lshlrev_b32_e32 v44, 16, v132
	v_mul_f32_e32 v2, 0xbfb8aa3b, v44
	v_exp_f32_e32 v2, v2
	v_and_b32_e32 v45, 0xffff0000, v132
	s_waitcnt lgkmcnt(1)
	v_pk_mul_f32 v[36:37], v[36:37], v[44:45]
	v_lshlrev_b32_e32 v44, 16, v133
	v_add_f32_e32 v2, 1.0, v2
	v_rcp_f32_e32 v52, v2
	v_mul_f32_e32 v2, 0xbfb8aa3b, v45
	v_exp_f32_e32 v2, v2
	v_and_b32_e32 v45, 0xffff0000, v133
	v_pk_mul_f32 v[38:39], v[38:39], v[44:45]
	v_add_f32_e32 v2, 1.0, v2
	v_rcp_f32_e32 v53, v2
	v_mul_f32_e32 v2, 0xbfb8aa3b, v44
	v_exp_f32_e32 v2, v2
	v_lshlrev_b32_e32 v44, 16, v134
	v_pk_mul_f32 v[36:37], v[36:37], v[52:53]
	v_mad_u64_u32 v[52:53], s[0:1], v46, s91, v[68:69]
	v_add_f32_e32 v2, 1.0, v2
	v_rcp_f32_e32 v48, v2
	v_mul_f32_e32 v2, 0xbfb8aa3b, v45
	v_exp_f32_e32 v2, v2
	v_and_b32_e32 v45, 0xffff0000, v134
	s_waitcnt lgkmcnt(0)
	v_pk_mul_f32 v[40:41], v[40:41], v[44:45]
	v_cvt_pk_bf16_f32 v36, v36, v37
	v_add_f32_e32 v2, 1.0, v2
	v_rcp_f32_e32 v49, v2
	v_mul_f32_e32 v2, 0xbfb8aa3b, v44
	v_exp_f32_e32 v2, v2
	v_lshlrev_b32_e32 v44, 16, v135
	v_pk_mul_f32 v[38:39], v[38:39], v[48:49]
	v_add_f32_e32 v2, 1.0, v2
	v_rcp_f32_e32 v48, v2
	v_mul_f32_e32 v2, 0xbfb8aa3b, v45
	v_exp_f32_e32 v2, v2
	v_and_b32_e32 v45, 0xffff0000, v135
	v_pk_mul_f32 v[42:43], v[42:43], v[44:45]
	v_cvt_pk_bf16_f32 v37, v38, v39
	v_add_f32_e32 v2, 1.0, v2
	v_rcp_f32_e32 v49, v2
	v_mul_f32_e32 v2, 0xbfb8aa3b, v44
	v_exp_f32_e32 v2, v2
	v_pk_mul_f32 v[40:41], v[40:41], v[48:49]
	s_nop 0
	v_cvt_pk_bf16_f32 v38, v40, v41
	v_add_f32_e32 v2, 1.0, v2
	v_rcp_f32_e32 v48, v2
	v_mul_f32_e32 v2, 0xbfb8aa3b, v45
	v_exp_f32_e32 v2, v2
	s_nop 0
	v_add_f32_e32 v2, 1.0, v2
	v_rcp_f32_e32 v49, v2
	v_lshlrev_b32_e32 v2, 12, v47
	v_lshl_add_u64 v[54:55], v[70:71], 0, v[2:3]
	v_pk_mul_f32 v[42:43], v[42:43], v[48:49]
	s_nop 0
	v_cvt_pk_bf16_f32 v39, v42, v43
	global_store_dwordx4 v[52:53], v[36:39], off
	ds_read_b128 v[48:51], v58 offset:2176
	ds_read_b128 v[36:39], v58 offset:2192
	s_waitcnt vmcnt(7)
	v_lshlrev_b32_e32 v44, 16, v136
	v_mul_f32_e32 v2, 0xbfb8aa3b, v44
	v_exp_f32_e32 v2, v2
	v_and_b32_e32 v45, 0xffff0000, v136
	v_lshlrev_b32_e32 v40, 16, v137
	s_waitcnt lgkmcnt(1)
	v_pk_mul_f32 v[48:49], v[48:49], v[44:45]
	v_add_f32_e32 v2, 1.0, v2
	v_rcp_f32_e32 v66, v2
	v_mul_f32_e32 v2, 0xbfb8aa3b, v45
	v_exp_f32_e32 v2, v2
	v_and_b32_e32 v41, 0xffff0000, v137
	v_pk_mul_f32 v[50:51], v[50:51], v[40:41]
	v_add_f32_e32 v2, 1.0, v2
	v_rcp_f32_e32 v67, v2
	v_mul_f32_e32 v2, 0xbfb8aa3b, v40
	v_exp_f32_e32 v2, v2
	v_pk_mul_f32 v[44:45], v[48:49], v[66:67]
	v_add_f32_e32 v2, 1.0, v2
	v_rcp_f32_e32 v48, v2
	v_mul_f32_e32 v2, 0xbfb8aa3b, v41
	v_exp_f32_e32 v2, v2
	s_nop 0
	v_add_f32_e32 v2, 1.0, v2
	v_rcp_f32_e32 v49, v2
	s_nop 0
	v_pk_mul_f32 v[40:41], v[50:51], v[48:49]
	v_lshlrev_b32_e32 v48, 16, v138
	v_mul_f32_e32 v2, 0xbfb8aa3b, v48
	v_exp_f32_e32 v2, v2
	v_and_b32_e32 v49, 0xffff0000, v138
	s_waitcnt lgkmcnt(0)
	v_pk_mul_f32 v[36:37], v[36:37], v[48:49]
	v_add_f32_e32 v2, 1.0, v2
	v_rcp_f32_e32 v50, v2
	v_mul_f32_e32 v2, 0xbfb8aa3b, v49
	v_exp_f32_e32 v2, v2
	s_nop 0
	v_add_f32_e32 v2, 1.0, v2
	v_rcp_f32_e32 v51, v2
	s_nop 0
	v_pk_mul_f32 v[48:49], v[36:37], v[50:51]
	v_lshlrev_b32_e32 v36, 16, v139
	v_mul_f32_e32 v2, 0xbfb8aa3b, v36
	v_exp_f32_e32 v2, v2
	v_and_b32_e32 v37, 0xffff0000, v139
	v_pk_mul_f32 v[38:39], v[38:39], v[36:37]
	v_cvt_pk_bf16_f32 v36, v44, v45
	v_add_f32_e32 v2, 1.0, v2
	v_rcp_f32_e32 v42, v2
	v_mul_f32_e32 v2, 0xbfb8aa3b, v37
	v_exp_f32_e32 v2, v2
	v_cvt_pk_bf16_f32 v37, v40, v41
	v_add_f32_e32 v2, 1.0, v2
	v_rcp_f32_e32 v43, v2
	s_nop 0
	v_pk_mul_f32 v[42:43], v[38:39], v[42:43]
	v_cvt_pk_bf16_f32 v38, v48, v49
	v_mad_u64_u32 v[48:49], s[0:1], v47, s91, v[68:69]
	v_or_b32_e32 v47, 16, v46
	v_cvt_pk_bf16_f32 v39, v42, v43
	v_lshlrev_b32_e32 v2, 12, v47
	global_store_dwordx4 v[48:49], v[36:39], off
	v_lshl_add_u64 v[50:51], v[70:71], 0, v[2:3]
	ds_read_b128 v[36:39], v58 offset:4352
	ds_read_b128 v[40:43], v58 offset:4368
	s_waitcnt vmcnt(7)
	v_lshlrev_b32_e32 v44, 16, v140
	v_mul_f32_e32 v2, 0xbfb8aa3b, v44
	v_exp_f32_e32 v2, v2
	v_and_b32_e32 v45, 0xffff0000, v140
	s_waitcnt lgkmcnt(1)
	v_pk_mul_f32 v[36:37], v[36:37], v[44:45]
	v_lshlrev_b32_e32 v44, 16, v141
	v_add_f32_e32 v2, 1.0, v2
	v_rcp_f32_e32 v66, v2
	v_mul_f32_e32 v2, 0xbfb8aa3b, v45
	v_exp_f32_e32 v2, v2
	v_and_b32_e32 v45, 0xffff0000, v141
	v_pk_mul_f32 v[38:39], v[38:39], v[44:45]
	v_add_f32_e32 v2, 1.0, v2
	v_rcp_f32_e32 v67, v2
	v_mul_f32_e32 v2, 0xbfb8aa3b, v44
	v_exp_f32_e32 v2, v2
	v_lshlrev_b32_e32 v44, 16, v142
	v_pk_mul_f32 v[36:37], v[36:37], v[66:67]
	v_add_f32_e32 v2, 1.0, v2
	v_rcp_f32_e32 v66, v2
	v_mul_f32_e32 v2, 0xbfb8aa3b, v45
	v_exp_f32_e32 v2, v2
	v_and_b32_e32 v45, 0xffff0000, v142
	s_waitcnt lgkmcnt(0)
	v_pk_mul_f32 v[40:41], v[40:41], v[44:45]
	v_cvt_pk_bf16_f32 v36, v36, v37
	v_add_f32_e32 v2, 1.0, v2
	v_rcp_f32_e32 v67, v2
	v_mul_f32_e32 v2, 0xbfb8aa3b, v44
	v_exp_f32_e32 v2, v2
	v_lshlrev_b32_e32 v44, 16, v143
	v_pk_mul_f32 v[38:39], v[38:39], v[66:67]
	v_add_f32_e32 v2, 1.0, v2
	v_rcp_f32_e32 v66, v2
	v_mul_f32_e32 v2, 0xbfb8aa3b, v45
	v_exp_f32_e32 v2, v2
	v_and_b32_e32 v45, 0xffff0000, v143
	v_pk_mul_f32 v[42:43], v[42:43], v[44:45]
	v_cvt_pk_bf16_f32 v37, v38, v39
	v_add_f32_e32 v2, 1.0, v2
	v_rcp_f32_e32 v67, v2
	v_mul_f32_e32 v2, 0xbfb8aa3b, v44
	v_exp_f32_e32 v2, v2
	v_pk_mul_f32 v[40:41], v[40:41], v[66:67]
	s_nop 0
	v_cvt_pk_bf16_f32 v38, v40, v41
	v_add_f32_e32 v2, 1.0, v2
	v_rcp_f32_e32 v66, v2
	v_mul_f32_e32 v2, 0xbfb8aa3b, v45
	v_exp_f32_e32 v2, v2
	v_mad_u64_u32 v[44:45], s[0:1], v47, s91, v[68:69]
	v_add_f32_e32 v2, 1.0, v2
	v_rcp_f32_e32 v67, v2
	s_nop 0
	v_pk_mul_f32 v[42:43], v[42:43], v[66:67]
	v_or_b32_e32 v66, 24, v46
	v_cvt_pk_bf16_f32 v39, v42, v43
	v_lshlrev_b32_e32 v2, 12, v66
	global_store_dwordx4 v[44:45], v[36:39], off
	v_lshl_add_u64 v[46:47], v[70:71], 0, v[2:3]
	ds_read_b128 v[40:43], v58 offset:6528
	ds_read_b128 v[36:39], v58 offset:6544
	s_waitcnt vmcnt(7)
	v_lshlrev_b32_e32 v70, 16, v144
	v_mul_f32_e32 v2, 0xbfb8aa3b, v70
	v_exp_f32_e32 v2, v2
	v_and_b32_e32 v71, 0xffff0000, v144
	s_waitcnt lgkmcnt(1)
	v_pk_mul_f32 v[40:41], v[40:41], v[70:71]
	v_lshlrev_b32_e32 v70, 16, v145
	v_add_f32_e32 v2, 1.0, v2
	v_rcp_f32_e32 v94, v2
	v_mul_f32_e32 v2, 0xbfb8aa3b, v71
	v_exp_f32_e32 v2, v2
	v_and_b32_e32 v71, 0xffff0000, v145
	v_pk_mul_f32 v[42:43], v[42:43], v[70:71]
	v_add_f32_e32 v2, 1.0, v2
	v_rcp_f32_e32 v95, v2
	v_mul_f32_e32 v2, 0xbfb8aa3b, v70
	v_exp_f32_e32 v2, v2
	v_lshlrev_b32_e32 v70, 16, v146
	v_pk_mul_f32 v[40:41], v[40:41], v[94:95]
	v_add_f32_e32 v2, 1.0, v2
	v_rcp_f32_e32 v90, v2
	v_mul_f32_e32 v2, 0xbfb8aa3b, v71
	v_exp_f32_e32 v2, v2
	v_and_b32_e32 v71, 0xffff0000, v146
	s_waitcnt lgkmcnt(0)
	v_pk_mul_f32 v[36:37], v[36:37], v[70:71]
	v_add_f32_e32 v2, 1.0, v2
	v_rcp_f32_e32 v91, v2
	v_mul_f32_e32 v2, 0xbfb8aa3b, v70
	v_exp_f32_e32 v2, v2
	v_lshlrev_b32_e32 v70, 16, v147
	v_pk_mul_f32 v[42:43], v[42:43], v[90:91]
	v_add_f32_e32 v2, 1.0, v2
	v_rcp_f32_e32 v90, v2
	v_mul_f32_e32 v2, 0xbfb8aa3b, v71
	v_exp_f32_e32 v2, v2
	v_and_b32_e32 v71, 0xffff0000, v147
	v_pk_mul_f32 v[38:39], v[38:39], v[70:71]
	v_add_f32_e32 v2, 1.0, v2
	v_rcp_f32_e32 v91, v2
	v_mul_f32_e32 v2, 0xbfb8aa3b, v70
	v_exp_f32_e32 v2, v2
	v_pk_mul_f32 v[36:37], v[36:37], v[90:91]
	v_add_f32_e32 v2, 1.0, v2
	v_rcp_f32_e32 v90, v2
	v_mul_f32_e32 v2, 0xbfb8aa3b, v71
	v_exp_f32_e32 v2, v2
	s_nop 0
	v_add_f32_e32 v2, 1.0, v2
	v_rcp_f32_e32 v91, v2
	v_mul_f32_e32 v2, v20, v87
	v_mul_f32_e32 v20, v21, v85
	v_mul_f32_e32 v21, v22, v84
	v_pk_mul_f32 v[70:71], v[38:39], v[90:91]
	v_cvt_pk_bf16_f32 v38, v40, v41
	v_cvt_pk_bf16_f32 v39, v42, v43
	v_cvt_pk_bf16_f32 v40, v36, v37
	v_cvt_pk_bf16_f32 v41, v70, v71
	v_mad_u64_u32 v[36:37], s[0:1], v66, s91, v[68:69]
	global_store_dwordx4 v[36:37], v[38:41], off
	s_waitcnt lgkmcnt(0)
	ds_write2_b32 v88, v2, v4 offset1:32
	v_mul_f32_e32 v2, v5, v85
	ds_write2_b32 v88, v20, v2 offset0:68 offset1:100
	v_mul_f32_e32 v2, v6, v84
	v_mul_f32_e32 v22, v23, v83
	ds_write2_b32 v88, v21, v2 offset0:136 offset1:168
	v_mul_f32_e32 v2, v7, v83
	v_mul_f32_e32 v23, v24, v82
	ds_write2_b32 v88, v22, v2 offset0:204 offset1:236
	v_mul_f32_e32 v2, v8, v82
	v_mul_f32_e32 v24, v25, v81
	ds_write2_b32 v64, v23, v2 offset0:32 offset1:64
	v_mul_f32_e32 v2, v9, v81
	v_mul_f32_e32 v25, v26, v79
	ds_write2_b32 v64, v24, v2 offset0:100 offset1:132
	v_mul_f32_e32 v2, v10, v79
	v_mul_f32_e32 v26, v27, v77
	ds_write2_b32 v64, v25, v2 offset0:168 offset1:200
	v_mul_f32_e32 v2, v11, v77
	v_mul_f32_e32 v27, v28, v80
	ds_write2_b32 v65, v26, v2 offset0:108 offset1:140
	v_mul_f32_e32 v2, v12, v80
	v_mul_f32_e32 v28, v29, v78
	ds_write2_b32 v62, v27, v2 offset0:64 offset1:96
	v_mul_f32_e32 v2, v13, v78
	v_mul_f32_e32 v29, v30, v76
	ds_write2_b32 v62, v28, v2 offset0:132 offset1:164
	v_mul_f32_e32 v2, v14, v76
	v_mul_f32_e32 v30, v31, v75
	ds_write2_b32 v62, v29, v2 offset0:200 offset1:232
	v_mul_f32_e32 v2, v15, v75
	v_mul_f32_e32 v31, v32, v86
	ds_write2_b32 v63, v30, v2 offset0:12 offset1:44
	v_mul_f32_e32 v2, v16, v86
	v_mul_f32_e32 v32, v33, v74
	ds_write2_b32 v59, v31, v2 offset0:96 offset1:128
	v_mul_f32_e32 v2, v17, v74
	v_mul_f32_e32 v33, v34, v73
	ds_write2_b32 v59, v32, v2 offset0:164 offset1:196
	v_mul_f32_e32 v2, v18, v73
	v_mul_f32_e32 v34, v35, v72
	ds_write2_b32 v60, v33, v2 offset0:104 offset1:136
	v_mul_f32_e32 v2, v19, v72
	ds_write2_b32 v61, v34, v2 offset0:44 offset1:76
	s_waitcnt lgkmcnt(0)
	ds_read_b128 v[4:7], v58
	ds_read_b128 v[8:11], v58 offset:16
	s_waitcnt vmcnt(7)
	v_lshlrev_b32_e32 v16, 16, v148
	v_mul_f32_e32 v2, 0xbfb8aa3b, v16
	v_exp_f32_e32 v2, v2
	v_and_b32_e32 v17, 0xffff0000, v148
	v_lshlrev_b32_e32 v12, 16, v149
	v_and_b32_e32 v13, 0xffff0000, v149
	v_add_f32_e32 v2, 1.0, v2
	v_rcp_f32_e32 v18, v2
	v_mul_f32_e32 v2, 0xbfb8aa3b, v17
	v_exp_f32_e32 v2, v2
	s_waitcnt lgkmcnt(1)
	v_pk_mul_f32 v[4:5], v[4:5], v[16:17]
	v_pk_mul_f32 v[6:7], v[6:7], v[12:13]
	v_add_f32_e32 v2, 1.0, v2
	v_rcp_f32_e32 v19, v2
	v_mul_f32_e32 v2, 0xbfb8aa3b, v12
	v_exp_f32_e32 v2, v2
	v_lshlrev_b32_e32 v12, 16, v150
	v_pk_mul_f32 v[4:5], v[4:5], v[18:19]
	v_add_f32_e32 v2, 1.0, v2
	v_rcp_f32_e32 v16, v2
	v_mul_f32_e32 v2, 0xbfb8aa3b, v13
	v_exp_f32_e32 v2, v2
	v_and_b32_e32 v13, 0xffff0000, v150
	s_waitcnt lgkmcnt(0)
	v_pk_mul_f32 v[8:9], v[8:9], v[12:13]
	v_cvt_pk_bf16_f32 v4, v4, v5
	v_add_f32_e32 v2, 1.0, v2
	v_rcp_f32_e32 v17, v2
	v_mul_f32_e32 v2, 0xbfb8aa3b, v12
	v_exp_f32_e32 v2, v2
	v_lshlrev_b32_e32 v12, 16, v151
	v_pk_mul_f32 v[6:7], v[6:7], v[16:17]
	v_add_f32_e32 v2, 1.0, v2
	v_rcp_f32_e32 v16, v2
	v_mul_f32_e32 v2, 0xbfb8aa3b, v13
	v_exp_f32_e32 v2, v2
	v_and_b32_e32 v13, 0xffff0000, v151
	v_pk_mul_f32 v[10:11], v[10:11], v[12:13]
	v_cvt_pk_bf16_f32 v5, v6, v7
	v_add_f32_e32 v2, 1.0, v2
	v_rcp_f32_e32 v17, v2
	v_mul_f32_e32 v2, 0xbfb8aa3b, v12
	v_exp_f32_e32 v2, v2
	v_pk_mul_f32 v[8:9], v[8:9], v[16:17]
	s_nop 0
	v_cvt_pk_bf16_f32 v6, v8, v9
	v_add_f32_e32 v2, 1.0, v2
	v_rcp_f32_e32 v14, v2
	v_mul_f32_e32 v2, 0xbfb8aa3b, v13
	v_exp_f32_e32 v2, v2
	s_nop 0
	v_add_f32_e32 v2, 1.0, v2
	v_rcp_f32_e32 v15, v2
	s_nop 0
	v_pk_mul_f32 v[10:11], v[10:11], v[14:15]
	s_nop 0
	v_cvt_pk_bf16_f32 v7, v10, v11
	global_store_dwordx4 v[52:53], v[4:7], off offset:128
	ds_read_b128 v[4:7], v58 offset:2176
	ds_read_b128 v[8:11], v58 offset:2192
	s_waitcnt vmcnt(7)
	v_lshlrev_b32_e32 v16, 16, v152
	v_mul_f32_e32 v2, 0xbfb8aa3b, v16
	v_exp_f32_e32 v2, v2
	v_and_b32_e32 v17, 0xffff0000, v152
	v_lshlrev_b32_e32 v12, 16, v153
	v_and_b32_e32 v13, 0xffff0000, v153
	v_add_f32_e32 v2, 1.0, v2
	v_rcp_f32_e32 v18, v2
	v_mul_f32_e32 v2, 0xbfb8aa3b, v17
	v_exp_f32_e32 v2, v2
	s_waitcnt lgkmcnt(1)
	v_pk_mul_f32 v[4:5], v[4:5], v[16:17]
	v_pk_mul_f32 v[6:7], v[6:7], v[12:13]
	v_add_f32_e32 v2, 1.0, v2
	v_rcp_f32_e32 v19, v2
	v_mul_f32_e32 v2, 0xbfb8aa3b, v12
	v_exp_f32_e32 v2, v2
	v_lshlrev_b32_e32 v12, 16, v154
	v_pk_mul_f32 v[4:5], v[4:5], v[18:19]
	v_add_f32_e32 v2, 1.0, v2
	v_rcp_f32_e32 v16, v2
	v_mul_f32_e32 v2, 0xbfb8aa3b, v13
	v_exp_f32_e32 v2, v2
	v_and_b32_e32 v13, 0xffff0000, v154
	s_waitcnt lgkmcnt(0)
	v_pk_mul_f32 v[8:9], v[8:9], v[12:13]
	v_cvt_pk_bf16_f32 v4, v4, v5
	v_add_f32_e32 v2, 1.0, v2
	v_rcp_f32_e32 v17, v2
	v_mul_f32_e32 v2, 0xbfb8aa3b, v12
	v_exp_f32_e32 v2, v2
	v_lshlrev_b32_e32 v12, 16, v155
	v_pk_mul_f32 v[6:7], v[6:7], v[16:17]
	v_add_f32_e32 v2, 1.0, v2
	v_rcp_f32_e32 v16, v2
	v_mul_f32_e32 v2, 0xbfb8aa3b, v13
	v_exp_f32_e32 v2, v2
	v_and_b32_e32 v13, 0xffff0000, v155
	v_pk_mul_f32 v[10:11], v[10:11], v[12:13]
	v_cvt_pk_bf16_f32 v5, v6, v7
	v_add_f32_e32 v2, 1.0, v2
	v_rcp_f32_e32 v17, v2
	v_mul_f32_e32 v2, 0xbfb8aa3b, v12
	v_exp_f32_e32 v2, v2
	v_pk_mul_f32 v[8:9], v[8:9], v[16:17]
	s_nop 0
	v_cvt_pk_bf16_f32 v6, v8, v9
	v_add_f32_e32 v2, 1.0, v2
	v_rcp_f32_e32 v14, v2
	v_mul_f32_e32 v2, 0xbfb8aa3b, v13
	v_exp_f32_e32 v2, v2
	s_nop 0
	v_add_f32_e32 v2, 1.0, v2
	v_rcp_f32_e32 v15, v2
	s_nop 0
	v_pk_mul_f32 v[10:11], v[10:11], v[14:15]
	s_nop 0
	v_cvt_pk_bf16_f32 v7, v10, v11
	global_store_dwordx4 v[48:49], v[4:7], off offset:128
	ds_read_b128 v[4:7], v58 offset:4352
	ds_read_b128 v[8:11], v58 offset:4368
	s_waitcnt vmcnt(7)
	v_lshlrev_b32_e32 v16, 16, v156
	v_mul_f32_e32 v2, 0xbfb8aa3b, v16
	v_exp_f32_e32 v2, v2
	v_and_b32_e32 v17, 0xffff0000, v156
	v_lshlrev_b32_e32 v12, 16, v157
	v_and_b32_e32 v13, 0xffff0000, v157
	v_add_f32_e32 v2, 1.0, v2
	v_rcp_f32_e32 v18, v2
	v_mul_f32_e32 v2, 0xbfb8aa3b, v17
	v_exp_f32_e32 v2, v2
	s_waitcnt lgkmcnt(1)
	v_pk_mul_f32 v[4:5], v[4:5], v[16:17]
	v_pk_mul_f32 v[6:7], v[6:7], v[12:13]
	v_add_f32_e32 v2, 1.0, v2
	v_rcp_f32_e32 v19, v2
	v_mul_f32_e32 v2, 0xbfb8aa3b, v12
	v_exp_f32_e32 v2, v2
	v_lshlrev_b32_e32 v12, 16, v158
	v_pk_mul_f32 v[4:5], v[4:5], v[18:19]
	v_add_f32_e32 v2, 1.0, v2
	v_rcp_f32_e32 v16, v2
	v_mul_f32_e32 v2, 0xbfb8aa3b, v13
	v_exp_f32_e32 v2, v2
	v_and_b32_e32 v13, 0xffff0000, v158
	s_waitcnt lgkmcnt(0)
	v_pk_mul_f32 v[8:9], v[8:9], v[12:13]
	v_cvt_pk_bf16_f32 v4, v4, v5
	v_add_f32_e32 v2, 1.0, v2
	v_rcp_f32_e32 v17, v2
	v_mul_f32_e32 v2, 0xbfb8aa3b, v12
	v_exp_f32_e32 v2, v2
	v_lshlrev_b32_e32 v12, 16, v159
	v_pk_mul_f32 v[6:7], v[6:7], v[16:17]
	v_add_f32_e32 v2, 1.0, v2
	v_rcp_f32_e32 v16, v2
	v_mul_f32_e32 v2, 0xbfb8aa3b, v13
	v_exp_f32_e32 v2, v2
	v_and_b32_e32 v13, 0xffff0000, v159
	v_pk_mul_f32 v[10:11], v[10:11], v[12:13]
	v_cvt_pk_bf16_f32 v5, v6, v7
	v_add_f32_e32 v2, 1.0, v2
	v_rcp_f32_e32 v17, v2
	v_mul_f32_e32 v2, 0xbfb8aa3b, v12
	v_exp_f32_e32 v2, v2
	v_pk_mul_f32 v[8:9], v[8:9], v[16:17]
	s_nop 0
	v_cvt_pk_bf16_f32 v6, v8, v9
	v_add_f32_e32 v2, 1.0, v2
	v_rcp_f32_e32 v14, v2
	v_mul_f32_e32 v2, 0xbfb8aa3b, v13
	v_exp_f32_e32 v2, v2
	s_nop 0
	v_add_f32_e32 v2, 1.0, v2
	v_rcp_f32_e32 v15, v2
	s_nop 0
	v_pk_mul_f32 v[10:11], v[10:11], v[14:15]
	s_nop 0
	v_cvt_pk_bf16_f32 v7, v10, v11
	global_store_dwordx4 v[44:45], v[4:7], off offset:128
	ds_read_b128 v[4:7], v58 offset:6528
	ds_read_b128 v[8:11], v58 offset:6544
	s_waitcnt vmcnt(7)
	v_lshlrev_b32_e32 v16, 16, v160
	v_mul_f32_e32 v2, 0xbfb8aa3b, v16
	v_exp_f32_e32 v2, v2
	v_and_b32_e32 v17, 0xffff0000, v160
	v_lshlrev_b32_e32 v12, 16, v161
	v_and_b32_e32 v13, 0xffff0000, v161
	v_add_f32_e32 v2, 1.0, v2
	v_rcp_f32_e32 v18, v2
	v_mul_f32_e32 v2, 0xbfb8aa3b, v17
	v_exp_f32_e32 v2, v2
	s_waitcnt lgkmcnt(1)
	v_pk_mul_f32 v[4:5], v[4:5], v[16:17]
	v_pk_mul_f32 v[6:7], v[6:7], v[12:13]
	v_add_f32_e32 v2, 1.0, v2
	v_rcp_f32_e32 v19, v2
	v_mul_f32_e32 v2, 0xbfb8aa3b, v12
	v_exp_f32_e32 v2, v2
	v_lshlrev_b32_e32 v12, 16, v162
	v_pk_mul_f32 v[4:5], v[4:5], v[18:19]
	v_add_f32_e32 v2, 1.0, v2
	v_rcp_f32_e32 v16, v2
	v_mul_f32_e32 v2, 0xbfb8aa3b, v13
	v_exp_f32_e32 v2, v2
	v_and_b32_e32 v13, 0xffff0000, v162
	s_waitcnt lgkmcnt(0)
	v_pk_mul_f32 v[8:9], v[8:9], v[12:13]
	v_cvt_pk_bf16_f32 v4, v4, v5
	v_add_f32_e32 v2, 1.0, v2
	v_rcp_f32_e32 v17, v2
	v_mul_f32_e32 v2, 0xbfb8aa3b, v12
	v_exp_f32_e32 v2, v2
	v_lshlrev_b32_e32 v12, 16, v163
	v_pk_mul_f32 v[6:7], v[6:7], v[16:17]
	v_add_f32_e32 v2, 1.0, v2
	v_rcp_f32_e32 v16, v2
	v_mul_f32_e32 v2, 0xbfb8aa3b, v13
	v_exp_f32_e32 v2, v2
	v_and_b32_e32 v13, 0xffff0000, v163
	v_pk_mul_f32 v[10:11], v[10:11], v[12:13]
	v_cvt_pk_bf16_f32 v5, v6, v7
	v_add_f32_e32 v2, 1.0, v2
	v_rcp_f32_e32 v17, v2
	v_mul_f32_e32 v2, 0xbfb8aa3b, v12
	v_exp_f32_e32 v2, v2
	v_pk_mul_f32 v[8:9], v[8:9], v[16:17]
	s_nop 0
	v_cvt_pk_bf16_f32 v6, v8, v9
	v_add_f32_e32 v2, 1.0, v2
	v_rcp_f32_e32 v14, v2
	v_mul_f32_e32 v2, 0xbfb8aa3b, v13
	v_exp_f32_e32 v2, v2
	s_nop 0
	v_add_f32_e32 v2, 1.0, v2
	v_rcp_f32_e32 v15, v2
	s_nop 0
	v_pk_mul_f32 v[10:11], v[10:11], v[14:15]
	s_nop 0
	v_cvt_pk_bf16_f32 v7, v10, v11
	global_store_dwordx4 v[36:37], v[4:7], off offset:128
	s_waitcnt lgkmcnt(0)
	s_barrier

.LBB0_1962:
	s_waitcnt vmcnt(0)
	s_waitcnt vmcnt(0) lgkmcnt(0)
	s_barrier
	s_and_saveexec_b64 s[6:7], s[12:13]
	ds_write_b32 v206, v212
	s_or_b64 exec, exec, s[6:7]
	s_waitcnt lgkmcnt(0)
	v_lshl_add_u32 v2, v191, 4, s47
	ds_read_b128 v[68:71], v2
	ds_read_b128 v[72:75], v2 offset:32
	s_or_b32 s6, s48, s87
	s_ashr_i32 s7, s51, 31
	s_add_u32 s8, s6, s51
	s_addc_u32 s9, s49, s7
	s_mul_i32 s6, s9, 0x3000
	s_mul_hi_u32 s7, s8, 0x3000
	s_waitcnt lgkmcnt(1)
	v_rcp_f32_e32 v87, v68
	v_rcp_f32_e32 v85, v69
	v_rcp_f32_e32 v84, v70
	v_rcp_f32_e32 v83, v71
	ds_read_b128 v[68:71], v2 offset:64
	s_add_i32 s7, s7, s6
	s_mul_i32 s6, s8, 0x3000
	s_add_u32 s6, s52, s6
	s_addc_u32 s7, s4, s7
	s_add_u32 s6, s6, s92
	s_addc_u32 s7, s7, 0
	s_lshl_b64 s[8:9], s[8:9], 12
	s_waitcnt lgkmcnt(1)
	v_rcp_f32_e32 v77, v75
	s_waitcnt lgkmcnt(0)
	v_rcp_f32_e32 v80, v68
	v_rcp_f32_e32 v78, v69
	v_rcp_f32_e32 v76, v70
	v_rcp_f32_e32 v75, v71
	ds_read_b128 v[68:71], v2 offset:96
	s_add_u32 s8, s36, s8
	s_addc_u32 s9, s37, s9
	s_add_u32 s8, s8, s92
	v_and_b32_e32 v2, 56, v190
	s_addc_u32 s9, s9, 0
	s_mulk_i32 s67, 0x2200
	v_lshlrev_b32_e32 v89, 2, v2
	v_lshlrev_b32_e32 v2, 1, v2
	s_add_i32 s10, s67, 0
	v_rcp_f32_e32 v82, v72
	v_rcp_f32_e32 v81, v73
	v_rcp_f32_e32 v79, v74
	s_waitcnt lgkmcnt(0)
	v_rcp_f32_e32 v86, v68
	v_rcp_f32_e32 v74, v69
	v_rcp_f32_e32 v73, v70
	v_rcp_f32_e32 v72, v71
	v_lshlrev_b32_e32 v88, 2, v189
	v_lshl_add_u64 v[70:71], s[8:9], 0, v[2:3]
	v_lshl_add_u64 v[68:69], s[6:7], 0, v[2:3]
	v_mul_f32_e32 v2, v52, v87
	v_mul_u32_u24_e32 v52, 0x440, v191
	v_add3_u32 v88, s10, v88, v52
	v_mul_f32_e32 v36, v36, v87
	v_mul_f32_e32 v52, v53, v85
	ds_write2_b32 v88, v2, v36 offset1:32
	v_mul_f32_e32 v2, v37, v85
	v_mul_f32_e32 v53, v54, v84
	ds_write2_b32 v88, v52, v2 offset0:68 offset1:100
	v_mul_f32_e32 v2, v38, v84
	v_mul_f32_e32 v54, v55, v83
	ds_write2_b32 v88, v53, v2 offset0:136 offset1:168
	v_mul_f32_e32 v2, v39, v83
	v_mul_f32_e32 v55, v56, v82
	v_mul_f32_e32 v91, v64, v86
	ds_write2_b32 v88, v54, v2 offset0:204 offset1:236
	v_mul_f32_e32 v2, v40, v82
	v_add_u32_e32 v64, 0x800, v88
	v_mul_f32_e32 v56, v57, v81
	ds_write2_b32 v64, v55, v2 offset0:32 offset1:64
	v_mul_f32_e32 v2, v41, v81
	v_mul_f32_e32 v57, v58, v79
	ds_write2_b32 v64, v56, v2 offset0:100 offset1:132
	v_mul_f32_e32 v2, v42, v79
	v_mul_f32_e32 v58, v59, v77
	v_mul_f32_e32 v92, v65, v74
	ds_write2_b32 v64, v57, v2 offset0:168 offset1:200
	v_mul_f32_e32 v2, v43, v77
	v_add_u32_e32 v65, 0xa00, v88
	v_mul_f32_e32 v59, v60, v80
	v_mul_f32_e32 v60, v61, v78
	v_mul_f32_e32 v61, v62, v76
	ds_write2_b32 v65, v58, v2 offset0:108 offset1:140
	v_mul_f32_e32 v2, v44, v80
	v_add_u32_e32 v62, 0x1000, v88
	ds_write2_b32 v62, v59, v2 offset0:64 offset1:96
	v_mul_f32_e32 v2, v45, v78
	ds_write2_b32 v62, v60, v2 offset0:132 offset1:164
	v_mul_f32_e32 v2, v46, v76
	v_mul_f32_e32 v90, v63, v75
	ds_write2_b32 v62, v61, v2 offset0:200 offset1:232
	v_mul_f32_e32 v2, v47, v75
	v_add_u32_e32 v63, 0x1400, v88
	ds_write2_b32 v63, v90, v2 offset0:12 offset1:44
	v_mul_f32_e32 v2, v48, v86
	v_add_u32_e32 v59, 0x1800, v88
	ds_write2_b32 v59, v91, v2 offset0:96 offset1:128
	v_mul_f32_e32 v2, v49, v74
	v_mul_f32_e32 v66, v66, v73
	ds_write2_b32 v59, v92, v2 offset0:164 offset1:196
	v_mul_f32_e32 v2, v50, v73
	v_add_u32_e32 v60, 0x1a00, v88
	v_mul_f32_e32 v67, v67, v72
	ds_write2_b32 v60, v66, v2 offset0:104 offset1:136
	v_mul_f32_e32 v2, v51, v72
	v_add_u32_e32 v61, 0x1c00, v88
	v_lshrrev_b32_e32 v46, 3, v188
	ds_write2_b32 v61, v67, v2 offset0:44 offset1:76
	v_mul_u32_u24_e32 v2, 0x110, v46
	v_add3_u32 v58, s10, v89, v2
	v_lshlrev_b32_e32 v2, 12, v46
	s_waitcnt lgkmcnt(0)
	v_lshl_add_u64 v[56:57], v[70:71], 0, v[2:3]
	ds_read_b128 v[36:39], v58
	ds_read_b128 v[40:43], v58 offset:16
	s_mov_b64 s[98:99], 0x8000
	v_lshl_add_u64 v[164:165], v[56:57], 0, s[98:99]
	v_lshl_add_u64 v[166:167], v[164:165], 0, s[98:99]
	v_lshl_add_u64 v[168:169], v[166:167], 0, s[98:99]
	global_load_dwordx4 v[132:135], v[56:57], off
	global_load_dwordx4 v[136:139], v[164:165], off
	global_load_dwordx4 v[140:143], v[166:167], off
	global_load_dwordx4 v[144:147], v[168:169], off
	global_load_dwordx4 v[148:151], v[56:57], off offset:128
	global_load_dwordx4 v[152:155], v[164:165], off offset:128
	global_load_dwordx4 v[156:159], v[166:167], off offset:128
	global_load_dwordx4 v[160:163], v[168:169], off offset:128
	v_or_b32_e32 v47, 8, v46
	v_mul_f32_e32 v4, v4, v87
	s_movk_i32 s90, 0x1800
	s_waitcnt vmcnt(7)
	v_lshlrev_b32_e32 v44, 16, v132
	v_mul_f32_e32 v2, 0xbfb8aa3b, v44
	v_exp_f32_e32 v2, v2
	v_and_b32_e32 v45, 0xffff0000, v132
	s_waitcnt lgkmcnt(1)
	v_pk_mul_f32 v[36:37], v[36:37], v[44:45]
	v_lshlrev_b32_e32 v44, 16, v133
	v_add_f32_e32 v2, 1.0, v2
	v_rcp_f32_e32 v52, v2
	v_mul_f32_e32 v2, 0xbfb8aa3b, v45
	v_exp_f32_e32 v2, v2
	v_and_b32_e32 v45, 0xffff0000, v133
	v_pk_mul_f32 v[38:39], v[38:39], v[44:45]
	v_add_f32_e32 v2, 1.0, v2
	v_rcp_f32_e32 v53, v2
	v_mul_f32_e32 v2, 0xbfb8aa3b, v44
	v_exp_f32_e32 v2, v2
	v_lshlrev_b32_e32 v44, 16, v134
	v_pk_mul_f32 v[36:37], v[36:37], v[52:53]
	v_mad_u64_u32 v[52:53], s[6:7], v46, s91, v[68:69]
	v_add_f32_e32 v2, 1.0, v2
	v_rcp_f32_e32 v48, v2
	v_mul_f32_e32 v2, 0xbfb8aa3b, v45
	v_exp_f32_e32 v2, v2
	v_and_b32_e32 v45, 0xffff0000, v134
	s_waitcnt lgkmcnt(0)
	v_pk_mul_f32 v[40:41], v[40:41], v[44:45]
	v_cvt_pk_bf16_f32 v36, v36, v37
	v_add_f32_e32 v2, 1.0, v2
	v_rcp_f32_e32 v49, v2
	v_mul_f32_e32 v2, 0xbfb8aa3b, v44
	v_exp_f32_e32 v2, v2
	v_lshlrev_b32_e32 v44, 16, v135
	v_pk_mul_f32 v[38:39], v[38:39], v[48:49]
	v_add_f32_e32 v2, 1.0, v2
	v_rcp_f32_e32 v48, v2
	v_mul_f32_e32 v2, 0xbfb8aa3b, v45
	v_exp_f32_e32 v2, v2
	v_and_b32_e32 v45, 0xffff0000, v135
	v_pk_mul_f32 v[42:43], v[42:43], v[44:45]
	v_cvt_pk_bf16_f32 v37, v38, v39
	v_add_f32_e32 v2, 1.0, v2
	v_rcp_f32_e32 v49, v2
	v_mul_f32_e32 v2, 0xbfb8aa3b, v44
	v_exp_f32_e32 v2, v2
	v_pk_mul_f32 v[40:41], v[40:41], v[48:49]
	s_nop 0
	v_cvt_pk_bf16_f32 v38, v40, v41
	v_add_f32_e32 v2, 1.0, v2
	v_rcp_f32_e32 v48, v2
	v_mul_f32_e32 v2, 0xbfb8aa3b, v45
	v_exp_f32_e32 v2, v2
	s_nop 0
	v_add_f32_e32 v2, 1.0, v2
	v_rcp_f32_e32 v49, v2
	v_lshlrev_b32_e32 v2, 12, v47
	v_lshl_add_u64 v[54:55], v[70:71], 0, v[2:3]
	v_pk_mul_f32 v[42:43], v[42:43], v[48:49]
	s_nop 0
	v_cvt_pk_bf16_f32 v39, v42, v43
	global_store_dwordx4 v[52:53], v[36:39], off
	ds_read_b128 v[48:51], v58 offset:2176
	ds_read_b128 v[36:39], v58 offset:2192
	s_waitcnt vmcnt(7)
	v_lshlrev_b32_e32 v44, 16, v136
	v_mul_f32_e32 v2, 0xbfb8aa3b, v44
	v_exp_f32_e32 v2, v2
	v_and_b32_e32 v45, 0xffff0000, v136
	v_lshlrev_b32_e32 v40, 16, v137
	s_waitcnt lgkmcnt(1)
	v_pk_mul_f32 v[48:49], v[48:49], v[44:45]
	v_add_f32_e32 v2, 1.0, v2
	v_rcp_f32_e32 v66, v2
	v_mul_f32_e32 v2, 0xbfb8aa3b, v45
	v_exp_f32_e32 v2, v2
	v_and_b32_e32 v41, 0xffff0000, v137
	v_pk_mul_f32 v[50:51], v[50:51], v[40:41]
	v_add_f32_e32 v2, 1.0, v2
	v_rcp_f32_e32 v67, v2
	v_mul_f32_e32 v2, 0xbfb8aa3b, v40
	v_exp_f32_e32 v2, v2
	v_pk_mul_f32 v[44:45], v[48:49], v[66:67]
	v_add_f32_e32 v2, 1.0, v2
	v_rcp_f32_e32 v48, v2
	v_mul_f32_e32 v2, 0xbfb8aa3b, v41
	v_exp_f32_e32 v2, v2
	s_nop 0
	v_add_f32_e32 v2, 1.0, v2
	v_rcp_f32_e32 v49, v2
	s_nop 0
	v_pk_mul_f32 v[40:41], v[50:51], v[48:49]
	v_lshlrev_b32_e32 v48, 16, v138
	v_mul_f32_e32 v2, 0xbfb8aa3b, v48
	v_exp_f32_e32 v2, v2
	v_and_b32_e32 v49, 0xffff0000, v138
	s_waitcnt lgkmcnt(0)
	v_pk_mul_f32 v[36:37], v[36:37], v[48:49]
	v_add_f32_e32 v2, 1.0, v2
	v_rcp_f32_e32 v50, v2
	v_mul_f32_e32 v2, 0xbfb8aa3b, v49
	v_exp_f32_e32 v2, v2
	s_nop 0
	v_add_f32_e32 v2, 1.0, v2
	v_rcp_f32_e32 v51, v2
	s_nop 0
	v_pk_mul_f32 v[48:49], v[36:37], v[50:51]
	v_lshlrev_b32_e32 v36, 16, v139
	v_mul_f32_e32 v2, 0xbfb8aa3b, v36
	v_exp_f32_e32 v2, v2
	v_and_b32_e32 v37, 0xffff0000, v139
	v_pk_mul_f32 v[38:39], v[38:39], v[36:37]
	v_cvt_pk_bf16_f32 v36, v44, v45
	v_add_f32_e32 v2, 1.0, v2
	v_rcp_f32_e32 v42, v2
	v_mul_f32_e32 v2, 0xbfb8aa3b, v37
	v_exp_f32_e32 v2, v2
	v_cvt_pk_bf16_f32 v37, v40, v41
	v_add_f32_e32 v2, 1.0, v2
	v_rcp_f32_e32 v43, v2
	s_nop 0
	v_pk_mul_f32 v[42:43], v[38:39], v[42:43]
	v_cvt_pk_bf16_f32 v38, v48, v49
	v_mad_u64_u32 v[48:49], s[6:7], v47, s91, v[68:69]
	v_or_b32_e32 v47, 16, v46
	v_cvt_pk_bf16_f32 v39, v42, v43
	v_lshlrev_b32_e32 v2, 12, v47
	global_store_dwordx4 v[48:49], v[36:39], off
	v_lshl_add_u64 v[50:51], v[70:71], 0, v[2:3]
	ds_read_b128 v[36:39], v58 offset:4352
	ds_read_b128 v[40:43], v58 offset:4368
	s_waitcnt vmcnt(7)
	v_lshlrev_b32_e32 v44, 16, v140
	v_mul_f32_e32 v2, 0xbfb8aa3b, v44
	v_exp_f32_e32 v2, v2
	v_and_b32_e32 v45, 0xffff0000, v140
	s_waitcnt lgkmcnt(1)
	v_pk_mul_f32 v[36:37], v[36:37], v[44:45]
	v_lshlrev_b32_e32 v44, 16, v141
	v_add_f32_e32 v2, 1.0, v2
	v_rcp_f32_e32 v66, v2
	v_mul_f32_e32 v2, 0xbfb8aa3b, v45
	v_exp_f32_e32 v2, v2
	v_and_b32_e32 v45, 0xffff0000, v141
	v_pk_mul_f32 v[38:39], v[38:39], v[44:45]
	v_add_f32_e32 v2, 1.0, v2
	v_rcp_f32_e32 v67, v2
	v_mul_f32_e32 v2, 0xbfb8aa3b, v44
	v_exp_f32_e32 v2, v2
	v_lshlrev_b32_e32 v44, 16, v142
	v_pk_mul_f32 v[36:37], v[36:37], v[66:67]
	v_add_f32_e32 v2, 1.0, v2
	v_rcp_f32_e32 v66, v2
	v_mul_f32_e32 v2, 0xbfb8aa3b, v45
	v_exp_f32_e32 v2, v2
	v_and_b32_e32 v45, 0xffff0000, v142
	s_waitcnt lgkmcnt(0)
	v_pk_mul_f32 v[40:41], v[40:41], v[44:45]
	v_cvt_pk_bf16_f32 v36, v36, v37
	v_add_f32_e32 v2, 1.0, v2
	v_rcp_f32_e32 v67, v2
	v_mul_f32_e32 v2, 0xbfb8aa3b, v44
	v_exp_f32_e32 v2, v2
	v_lshlrev_b32_e32 v44, 16, v143
	v_pk_mul_f32 v[38:39], v[38:39], v[66:67]
	v_add_f32_e32 v2, 1.0, v2
	v_rcp_f32_e32 v66, v2
	v_mul_f32_e32 v2, 0xbfb8aa3b, v45
	v_exp_f32_e32 v2, v2
	v_and_b32_e32 v45, 0xffff0000, v143
	v_pk_mul_f32 v[42:43], v[42:43], v[44:45]
	v_cvt_pk_bf16_f32 v37, v38, v39
	v_add_f32_e32 v2, 1.0, v2
	v_rcp_f32_e32 v67, v2
	v_mul_f32_e32 v2, 0xbfb8aa3b, v44
	v_exp_f32_e32 v2, v2
	v_pk_mul_f32 v[40:41], v[40:41], v[66:67]
	s_nop 0
	v_cvt_pk_bf16_f32 v38, v40, v41
	v_add_f32_e32 v2, 1.0, v2
	v_rcp_f32_e32 v66, v2
	v_mul_f32_e32 v2, 0xbfb8aa3b, v45
	v_exp_f32_e32 v2, v2
	v_mad_u64_u32 v[44:45], s[6:7], v47, s91, v[68:69]
	v_add_f32_e32 v2, 1.0, v2
	v_rcp_f32_e32 v67, v2
	s_nop 0
	v_pk_mul_f32 v[42:43], v[42:43], v[66:67]
	v_or_b32_e32 v66, 24, v46
	v_cvt_pk_bf16_f32 v39, v42, v43
	v_lshlrev_b32_e32 v2, 12, v66
	global_store_dwordx4 v[44:45], v[36:39], off
	v_lshl_add_u64 v[46:47], v[70:71], 0, v[2:3]
	ds_read_b128 v[40:43], v58 offset:6528
	ds_read_b128 v[36:39], v58 offset:6544
	s_waitcnt vmcnt(7)
	v_lshlrev_b32_e32 v70, 16, v144
	v_mul_f32_e32 v2, 0xbfb8aa3b, v70
	v_exp_f32_e32 v2, v2
	v_and_b32_e32 v71, 0xffff0000, v144
	s_waitcnt lgkmcnt(1)
	v_pk_mul_f32 v[40:41], v[40:41], v[70:71]
	v_lshlrev_b32_e32 v70, 16, v145
	v_add_f32_e32 v2, 1.0, v2
	v_rcp_f32_e32 v94, v2
	v_mul_f32_e32 v2, 0xbfb8aa3b, v71
	v_exp_f32_e32 v2, v2
	v_and_b32_e32 v71, 0xffff0000, v145
	v_pk_mul_f32 v[42:43], v[42:43], v[70:71]
	v_add_f32_e32 v2, 1.0, v2
	v_rcp_f32_e32 v95, v2
	v_mul_f32_e32 v2, 0xbfb8aa3b, v70
	v_exp_f32_e32 v2, v2
	v_lshlrev_b32_e32 v70, 16, v146
	v_pk_mul_f32 v[40:41], v[40:41], v[94:95]
	v_add_f32_e32 v2, 1.0, v2
	v_rcp_f32_e32 v90, v2
	v_mul_f32_e32 v2, 0xbfb8aa3b, v71
	v_exp_f32_e32 v2, v2
	v_and_b32_e32 v71, 0xffff0000, v146
	s_waitcnt lgkmcnt(0)
	v_pk_mul_f32 v[36:37], v[36:37], v[70:71]
	v_add_f32_e32 v2, 1.0, v2
	v_rcp_f32_e32 v91, v2
	v_mul_f32_e32 v2, 0xbfb8aa3b, v70
	v_exp_f32_e32 v2, v2
	v_lshlrev_b32_e32 v70, 16, v147
	v_pk_mul_f32 v[42:43], v[42:43], v[90:91]
	v_add_f32_e32 v2, 1.0, v2
	v_rcp_f32_e32 v90, v2
	v_mul_f32_e32 v2, 0xbfb8aa3b, v71
	v_exp_f32_e32 v2, v2
	v_and_b32_e32 v71, 0xffff0000, v147
	v_pk_mul_f32 v[38:39], v[38:39], v[70:71]
	v_add_f32_e32 v2, 1.0, v2
	v_rcp_f32_e32 v91, v2
	v_mul_f32_e32 v2, 0xbfb8aa3b, v70
	v_exp_f32_e32 v2, v2
	v_pk_mul_f32 v[36:37], v[36:37], v[90:91]
	v_add_f32_e32 v2, 1.0, v2
	v_rcp_f32_e32 v90, v2
	v_mul_f32_e32 v2, 0xbfb8aa3b, v71
	v_exp_f32_e32 v2, v2
	s_nop 0
	v_add_f32_e32 v2, 1.0, v2
	v_rcp_f32_e32 v91, v2
	v_mul_f32_e32 v2, v20, v87
	v_mul_f32_e32 v20, v21, v85
	v_mul_f32_e32 v21, v22, v84
	v_pk_mul_f32 v[70:71], v[38:39], v[90:91]
	v_cvt_pk_bf16_f32 v38, v40, v41
	v_cvt_pk_bf16_f32 v39, v42, v43
	v_cvt_pk_bf16_f32 v40, v36, v37
	v_cvt_pk_bf16_f32 v41, v70, v71
	v_mad_u64_u32 v[36:37], s[6:7], v66, s91, v[68:69]
	global_store_dwordx4 v[36:37], v[38:41], off
	s_waitcnt lgkmcnt(0)
	ds_write2_b32 v88, v2, v4 offset1:32
	v_mul_f32_e32 v2, v5, v85
	ds_write2_b32 v88, v20, v2 offset0:68 offset1:100
	v_mul_f32_e32 v2, v6, v84
	v_mul_f32_e32 v22, v23, v83
	ds_write2_b32 v88, v21, v2 offset0:136 offset1:168
	v_mul_f32_e32 v2, v7, v83
	v_mul_f32_e32 v23, v24, v82
	ds_write2_b32 v88, v22, v2 offset0:204 offset1:236
	v_mul_f32_e32 v2, v8, v82
	v_mul_f32_e32 v24, v25, v81
	ds_write2_b32 v64, v23, v2 offset0:32 offset1:64
	v_mul_f32_e32 v2, v9, v81
	v_mul_f32_e32 v25, v26, v79
	ds_write2_b32 v64, v24, v2 offset0:100 offset1:132
	v_mul_f32_e32 v2, v10, v79
	v_mul_f32_e32 v26, v27, v77
	ds_write2_b32 v64, v25, v2 offset0:168 offset1:200
	v_mul_f32_e32 v2, v11, v77
	v_mul_f32_e32 v27, v28, v80
	ds_write2_b32 v65, v26, v2 offset0:108 offset1:140
	v_mul_f32_e32 v2, v12, v80
	v_mul_f32_e32 v28, v29, v78
	ds_write2_b32 v62, v27, v2 offset0:64 offset1:96
	v_mul_f32_e32 v2, v13, v78
	v_mul_f32_e32 v29, v30, v76
	ds_write2_b32 v62, v28, v2 offset0:132 offset1:164
	v_mul_f32_e32 v2, v14, v76
	v_mul_f32_e32 v30, v31, v75
	ds_write2_b32 v62, v29, v2 offset0:200 offset1:232
	v_mul_f32_e32 v2, v15, v75
	v_mul_f32_e32 v31, v32, v86
	ds_write2_b32 v63, v30, v2 offset0:12 offset1:44
	v_mul_f32_e32 v2, v16, v86
	v_mul_f32_e32 v32, v33, v74
	ds_write2_b32 v59, v31, v2 offset0:96 offset1:128
	v_mul_f32_e32 v2, v17, v74
	v_mul_f32_e32 v33, v34, v73
	ds_write2_b32 v59, v32, v2 offset0:164 offset1:196
	v_mul_f32_e32 v2, v18, v73
	v_mul_f32_e32 v34, v35, v72
	ds_write2_b32 v60, v33, v2 offset0:104 offset1:136
	v_mul_f32_e32 v2, v19, v72
	ds_write2_b32 v61, v34, v2 offset0:44 offset1:76
	s_waitcnt lgkmcnt(0)
	ds_read_b128 v[4:7], v58
	ds_read_b128 v[8:11], v58 offset:16
	s_mov_b64 s[6:7], 0
	s_waitcnt vmcnt(7)
	v_lshlrev_b32_e32 v16, 16, v148
	v_mul_f32_e32 v2, 0xbfb8aa3b, v16
	v_exp_f32_e32 v2, v2
	v_and_b32_e32 v17, 0xffff0000, v148
	v_lshlrev_b32_e32 v12, 16, v149
	v_and_b32_e32 v13, 0xffff0000, v149
	v_add_f32_e32 v2, 1.0, v2
	v_rcp_f32_e32 v18, v2
	v_mul_f32_e32 v2, 0xbfb8aa3b, v17
	v_exp_f32_e32 v2, v2
	s_waitcnt lgkmcnt(1)
	v_pk_mul_f32 v[4:5], v[4:5], v[16:17]
	v_pk_mul_f32 v[6:7], v[6:7], v[12:13]
	v_add_f32_e32 v2, 1.0, v2
	v_rcp_f32_e32 v19, v2
	v_mul_f32_e32 v2, 0xbfb8aa3b, v12
	v_exp_f32_e32 v2, v2
	v_lshlrev_b32_e32 v12, 16, v150
	v_pk_mul_f32 v[4:5], v[4:5], v[18:19]
	v_add_f32_e32 v2, 1.0, v2
	v_rcp_f32_e32 v16, v2
	v_mul_f32_e32 v2, 0xbfb8aa3b, v13
	v_exp_f32_e32 v2, v2
	v_and_b32_e32 v13, 0xffff0000, v150
	s_waitcnt lgkmcnt(0)
	v_pk_mul_f32 v[8:9], v[8:9], v[12:13]
	v_cvt_pk_bf16_f32 v4, v4, v5
	v_add_f32_e32 v2, 1.0, v2
	v_rcp_f32_e32 v17, v2
	v_mul_f32_e32 v2, 0xbfb8aa3b, v12
	v_exp_f32_e32 v2, v2
	v_lshlrev_b32_e32 v12, 16, v151
	v_pk_mul_f32 v[6:7], v[6:7], v[16:17]
	v_add_f32_e32 v2, 1.0, v2
	v_rcp_f32_e32 v16, v2
	v_mul_f32_e32 v2, 0xbfb8aa3b, v13
	v_exp_f32_e32 v2, v2
	v_and_b32_e32 v13, 0xffff0000, v151
	v_pk_mul_f32 v[10:11], v[10:11], v[12:13]
	v_cvt_pk_bf16_f32 v5, v6, v7
	v_add_f32_e32 v2, 1.0, v2
	v_rcp_f32_e32 v17, v2
	v_mul_f32_e32 v2, 0xbfb8aa3b, v12
	v_exp_f32_e32 v2, v2
	v_pk_mul_f32 v[8:9], v[8:9], v[16:17]
	s_nop 0
	v_cvt_pk_bf16_f32 v6, v8, v9
	v_add_f32_e32 v2, 1.0, v2
	v_rcp_f32_e32 v14, v2
	v_mul_f32_e32 v2, 0xbfb8aa3b, v13
	v_exp_f32_e32 v2, v2
	s_nop 0
	v_add_f32_e32 v2, 1.0, v2
	v_rcp_f32_e32 v15, v2
	s_nop 0
	v_pk_mul_f32 v[10:11], v[10:11], v[14:15]
	s_nop 0
	v_cvt_pk_bf16_f32 v7, v10, v11
	global_store_dwordx4 v[52:53], v[4:7], off offset:128
	ds_read_b128 v[4:7], v58 offset:2176
	ds_read_b128 v[8:11], v58 offset:2192
	s_waitcnt vmcnt(7)
	v_lshlrev_b32_e32 v16, 16, v152
	v_mul_f32_e32 v2, 0xbfb8aa3b, v16
	v_exp_f32_e32 v2, v2
	v_and_b32_e32 v17, 0xffff0000, v152
	v_lshlrev_b32_e32 v12, 16, v153
	v_and_b32_e32 v13, 0xffff0000, v153
	v_add_f32_e32 v2, 1.0, v2
	v_rcp_f32_e32 v18, v2
	v_mul_f32_e32 v2, 0xbfb8aa3b, v17
	v_exp_f32_e32 v2, v2
	s_waitcnt lgkmcnt(1)
	v_pk_mul_f32 v[4:5], v[4:5], v[16:17]
	v_pk_mul_f32 v[6:7], v[6:7], v[12:13]
	v_add_f32_e32 v2, 1.0, v2
	v_rcp_f32_e32 v19, v2
	v_mul_f32_e32 v2, 0xbfb8aa3b, v12
	v_exp_f32_e32 v2, v2
	v_lshlrev_b32_e32 v12, 16, v154
	v_pk_mul_f32 v[4:5], v[4:5], v[18:19]
	v_add_f32_e32 v2, 1.0, v2
	v_rcp_f32_e32 v16, v2
	v_mul_f32_e32 v2, 0xbfb8aa3b, v13
	v_exp_f32_e32 v2, v2
	v_and_b32_e32 v13, 0xffff0000, v154
	s_waitcnt lgkmcnt(0)
	v_pk_mul_f32 v[8:9], v[8:9], v[12:13]
	v_cvt_pk_bf16_f32 v4, v4, v5
	v_add_f32_e32 v2, 1.0, v2
	v_rcp_f32_e32 v17, v2
	v_mul_f32_e32 v2, 0xbfb8aa3b, v12
	v_exp_f32_e32 v2, v2
	v_lshlrev_b32_e32 v12, 16, v155
	v_pk_mul_f32 v[6:7], v[6:7], v[16:17]
	v_add_f32_e32 v2, 1.0, v2
	v_rcp_f32_e32 v16, v2
	v_mul_f32_e32 v2, 0xbfb8aa3b, v13
	v_exp_f32_e32 v2, v2
	v_and_b32_e32 v13, 0xffff0000, v155
	v_pk_mul_f32 v[10:11], v[10:11], v[12:13]
	v_cvt_pk_bf16_f32 v5, v6, v7
	v_add_f32_e32 v2, 1.0, v2
	v_rcp_f32_e32 v17, v2
	v_mul_f32_e32 v2, 0xbfb8aa3b, v12
	v_exp_f32_e32 v2, v2
	v_pk_mul_f32 v[8:9], v[8:9], v[16:17]
	s_nop 0
	v_cvt_pk_bf16_f32 v6, v8, v9
	v_add_f32_e32 v2, 1.0, v2
	v_rcp_f32_e32 v14, v2
	v_mul_f32_e32 v2, 0xbfb8aa3b, v13
	v_exp_f32_e32 v2, v2
	s_nop 0
	v_add_f32_e32 v2, 1.0, v2
	v_rcp_f32_e32 v15, v2
	s_nop 0
	v_pk_mul_f32 v[10:11], v[10:11], v[14:15]
	s_nop 0
	v_cvt_pk_bf16_f32 v7, v10, v11
	global_store_dwordx4 v[48:49], v[4:7], off offset:128
	ds_read_b128 v[4:7], v58 offset:4352
	ds_read_b128 v[8:11], v58 offset:4368
	s_waitcnt vmcnt(7)
	v_lshlrev_b32_e32 v16, 16, v156
	v_mul_f32_e32 v2, 0xbfb8aa3b, v16
	v_exp_f32_e32 v2, v2
	v_and_b32_e32 v17, 0xffff0000, v156
	v_lshlrev_b32_e32 v12, 16, v157
	v_and_b32_e32 v13, 0xffff0000, v157
	v_add_f32_e32 v2, 1.0, v2
	v_rcp_f32_e32 v18, v2
	v_mul_f32_e32 v2, 0xbfb8aa3b, v17
	v_exp_f32_e32 v2, v2
	s_waitcnt lgkmcnt(1)
	v_pk_mul_f32 v[4:5], v[4:5], v[16:17]
	v_pk_mul_f32 v[6:7], v[6:7], v[12:13]
	v_add_f32_e32 v2, 1.0, v2
	v_rcp_f32_e32 v19, v2
	v_mul_f32_e32 v2, 0xbfb8aa3b, v12
	v_exp_f32_e32 v2, v2
	v_lshlrev_b32_e32 v12, 16, v158
	v_pk_mul_f32 v[4:5], v[4:5], v[18:19]
	v_add_f32_e32 v2, 1.0, v2
	v_rcp_f32_e32 v16, v2
	v_mul_f32_e32 v2, 0xbfb8aa3b, v13
	v_exp_f32_e32 v2, v2
	v_and_b32_e32 v13, 0xffff0000, v158
	s_waitcnt lgkmcnt(0)
	v_pk_mul_f32 v[8:9], v[8:9], v[12:13]
	v_cvt_pk_bf16_f32 v4, v4, v5
	v_add_f32_e32 v2, 1.0, v2
	v_rcp_f32_e32 v17, v2
	v_mul_f32_e32 v2, 0xbfb8aa3b, v12
	v_exp_f32_e32 v2, v2
	v_lshlrev_b32_e32 v12, 16, v159
	v_pk_mul_f32 v[6:7], v[6:7], v[16:17]
	v_add_f32_e32 v2, 1.0, v2
	v_rcp_f32_e32 v16, v2
	v_mul_f32_e32 v2, 0xbfb8aa3b, v13
	v_exp_f32_e32 v2, v2
	v_and_b32_e32 v13, 0xffff0000, v159
	v_pk_mul_f32 v[10:11], v[10:11], v[12:13]
	v_cvt_pk_bf16_f32 v5, v6, v7
	v_add_f32_e32 v2, 1.0, v2
	v_rcp_f32_e32 v17, v2
	v_mul_f32_e32 v2, 0xbfb8aa3b, v12
	v_exp_f32_e32 v2, v2
	v_pk_mul_f32 v[8:9], v[8:9], v[16:17]
	s_nop 0
	v_cvt_pk_bf16_f32 v6, v8, v9
	v_add_f32_e32 v2, 1.0, v2
	v_rcp_f32_e32 v14, v2
	v_mul_f32_e32 v2, 0xbfb8aa3b, v13
	v_exp_f32_e32 v2, v2
	s_nop 0
	v_add_f32_e32 v2, 1.0, v2
	v_rcp_f32_e32 v15, v2
	s_nop 0
	v_pk_mul_f32 v[10:11], v[10:11], v[14:15]
	s_nop 0
	v_cvt_pk_bf16_f32 v7, v10, v11
	global_store_dwordx4 v[44:45], v[4:7], off offset:128
	ds_read_b128 v[4:7], v58 offset:6528
	ds_read_b128 v[8:11], v58 offset:6544
	s_waitcnt vmcnt(7)
	v_lshlrev_b32_e32 v16, 16, v160
	v_mul_f32_e32 v2, 0xbfb8aa3b, v16
	v_exp_f32_e32 v2, v2
	v_and_b32_e32 v17, 0xffff0000, v160
	v_lshlrev_b32_e32 v12, 16, v161
	v_and_b32_e32 v13, 0xffff0000, v161
	v_add_f32_e32 v2, 1.0, v2
	v_rcp_f32_e32 v18, v2
	v_mul_f32_e32 v2, 0xbfb8aa3b, v17
	v_exp_f32_e32 v2, v2
	s_waitcnt lgkmcnt(1)
	v_pk_mul_f32 v[4:5], v[4:5], v[16:17]
	v_pk_mul_f32 v[6:7], v[6:7], v[12:13]
	v_add_f32_e32 v2, 1.0, v2
	v_rcp_f32_e32 v19, v2
	v_mul_f32_e32 v2, 0xbfb8aa3b, v12
	v_exp_f32_e32 v2, v2
	v_lshlrev_b32_e32 v12, 16, v162
	v_pk_mul_f32 v[4:5], v[4:5], v[18:19]
	v_add_f32_e32 v2, 1.0, v2
	v_rcp_f32_e32 v16, v2
	v_mul_f32_e32 v2, 0xbfb8aa3b, v13
	v_exp_f32_e32 v2, v2
	v_and_b32_e32 v13, 0xffff0000, v162
	s_waitcnt lgkmcnt(0)
	v_pk_mul_f32 v[8:9], v[8:9], v[12:13]
	v_cvt_pk_bf16_f32 v4, v4, v5
	v_add_f32_e32 v2, 1.0, v2
	v_rcp_f32_e32 v17, v2
	v_mul_f32_e32 v2, 0xbfb8aa3b, v12
	v_exp_f32_e32 v2, v2
	v_lshlrev_b32_e32 v12, 16, v163
	v_pk_mul_f32 v[6:7], v[6:7], v[16:17]
	v_add_f32_e32 v2, 1.0, v2
	v_rcp_f32_e32 v16, v2
	v_mul_f32_e32 v2, 0xbfb8aa3b, v13
	v_exp_f32_e32 v2, v2
	v_and_b32_e32 v13, 0xffff0000, v163
	v_pk_mul_f32 v[10:11], v[10:11], v[12:13]
	v_cvt_pk_bf16_f32 v5, v6, v7
	v_add_f32_e32 v2, 1.0, v2
	v_rcp_f32_e32 v17, v2
	v_mul_f32_e32 v2, 0xbfb8aa3b, v12
	v_exp_f32_e32 v2, v2
	v_pk_mul_f32 v[8:9], v[8:9], v[16:17]
	s_nop 0
	v_cvt_pk_bf16_f32 v6, v8, v9
	v_add_f32_e32 v2, 1.0, v2
	v_rcp_f32_e32 v14, v2
	v_mul_f32_e32 v2, 0xbfb8aa3b, v13
	v_exp_f32_e32 v2, v2
	s_nop 0
	v_add_f32_e32 v2, 1.0, v2
	v_rcp_f32_e32 v15, v2
	s_nop 0
	v_pk_mul_f32 v[10:11], v[10:11], v[14:15]
	s_nop 0
	v_cvt_pk_bf16_f32 v7, v10, v11
	global_store_dwordx4 v[36:37], v[4:7], off offset:128
	s_waitcnt lgkmcnt(0)
	s_barrier

.LBB0_2664:
	s_or_b64 exec, exec, s[10:11]
	s_waitcnt lgkmcnt(0)
	ds_read_b128 v[4:7], v190
	ds_read_b128 v[8:11], v190 offset:32
	s_or_b32 s0, s12, s43
	s_ashr_i32 s1, s25, 31
	s_add_u32 s0, s0, s25
	s_addc_u32 s1, s13, s1
	s_waitcnt lgkmcnt(1)
	v_rcp_f32_e32 v79, v4
	v_rcp_f32_e32 v77, v5
	v_rcp_f32_e32 v76, v6
	v_rcp_f32_e32 v75, v7
	ds_read_b128 v[4:7], v190 offset:64
	s_mul_i32 s6, s1, 0x3000
	s_mul_hi_u32 s7, s0, 0x3000
	s_add_i32 s7, s7, s6
	s_mul_i32 s6, s0, 0x3000
	s_add_u32 s6, s34, s6
	s_addc_u32 s7, s35, s7
	s_lshl_b32 s10, s42, 8
	s_add_u32 s6, s6, s10
	s_waitcnt lgkmcnt(0)
	v_rcp_f32_e32 v72, v4
	v_rcp_f32_e32 v70, v5
	v_rcp_f32_e32 v68, v6
	v_rcp_f32_e32 v67, v7
	ds_read_b128 v[4:7], v190 offset:96
	s_addc_u32 s7, s7, 0
	s_lshl_b64 s[0:1], s[0:1], 12
	s_add_u32 s0, s30, s0
	s_addc_u32 s1, s31, s1
	s_add_u32 s10, s0, s10
	s_mulk_i32 s24, 0x2200
	v_and_b32_e32 v2, 56, v188
	s_addc_u32 s11, s1, 0
	s_add_i32 s0, s24, 0
	s_waitcnt lgkmcnt(0)
	v_rcp_f32_e32 v78, v4
	v_rcp_f32_e32 v63, v5
	v_rcp_f32_e32 v62, v6
	v_lshlrev_b32_e32 v4, 2, v186
	v_lshlrev_b32_e32 v5, 2, v2
	v_lshlrev_b32_e32 v2, 1, v2
	v_mul_u32_u24_e32 v6, 0x440, v187
	v_rcp_f32_e32 v74, v8
	v_lshl_add_u64 v[14:15], s[10:11], 0, v[2:3]
	v_lshl_add_u64 v[58:59], s[6:7], 0, v[2:3]
	v_mul_f32_e32 v2, v98, v79
	v_add3_u32 v98, s0, v4, v6
	v_mul_f32_e32 v54, v82, v79
	v_rcp_f32_e32 v73, v9
	v_mul_f32_e32 v4, v99, v77
	ds_write2_b32 v98, v2, v54 offset1:32
	v_mul_f32_e32 v2, v83, v77
	v_rcp_f32_e32 v71, v10
	v_mul_f32_e32 v6, v100, v76
	ds_write2_b32 v98, v4, v2 offset0:68 offset1:100
	v_mul_f32_e32 v2, v84, v76
	v_rcp_f32_e32 v69, v11
	v_rcp_f32_e32 v61, v7
	v_mul_f32_e32 v7, v101, v75
	ds_write2_b32 v98, v6, v2 offset0:136 offset1:168
	v_mul_f32_e32 v2, v85, v75
	v_mul_f32_e32 v8, v102, v74
	ds_write2_b32 v98, v7, v2 offset0:204 offset1:236
	v_mul_f32_e32 v2, v86, v74
	v_add_u32_e32 v82, 0x800, v98
	v_mul_f32_e32 v9, v103, v73
	ds_write2_b32 v82, v8, v2 offset0:32 offset1:64
	v_mul_f32_e32 v2, v87, v73
	v_mul_f32_e32 v10, v104, v71
	ds_write2_b32 v82, v9, v2 offset0:100 offset1:132
	v_mul_f32_e32 v2, v88, v71
	v_mul_f32_e32 v11, v105, v69
	ds_write2_b32 v82, v10, v2 offset0:168 offset1:200
	v_mul_f32_e32 v2, v89, v69
	v_add_u32_e32 v83, 0xa00, v98
	v_mul_f32_e32 v12, v106, v72
	ds_write2_b32 v83, v11, v2 offset0:108 offset1:140
	v_mul_f32_e32 v2, v90, v72
	v_add_u32_e32 v80, 0x1000, v98
	v_mul_f32_e32 v13, v107, v70
	ds_write2_b32 v80, v12, v2 offset0:64 offset1:96
	v_mul_f32_e32 v2, v91, v70
	v_mul_f32_e32 v16, v108, v68
	ds_write2_b32 v80, v13, v2 offset0:132 offset1:164
	v_mul_f32_e32 v2, v92, v68
	v_mul_f32_e32 v17, v109, v67
	ds_write2_b32 v80, v16, v2 offset0:200 offset1:232
	v_mul_f32_e32 v2, v93, v67
	v_add_u32_e32 v81, 0x1400, v98
	v_mul_f32_e32 v50, v110, v78
	ds_write2_b32 v81, v17, v2 offset0:12 offset1:44
	v_mul_f32_e32 v2, v94, v78
	v_add_u32_e32 v64, 0x1800, v98
	v_mul_f32_e32 v51, v111, v63
	ds_write2_b32 v64, v50, v2 offset0:96 offset1:128
	v_mul_f32_e32 v2, v95, v63
	v_mul_f32_e32 v52, v112, v62
	ds_write2_b32 v64, v51, v2 offset0:164 offset1:196
	v_mul_f32_e32 v2, v96, v62
	v_add_u32_e32 v65, 0x1a00, v98
	v_mul_f32_e32 v53, v113, v61
	ds_write2_b32 v65, v52, v2 offset0:104 offset1:136
	v_mul_f32_e32 v2, v97, v61
	v_add_u32_e32 v66, 0x1c00, v98
	v_lshrrev_b32_e32 v84, 3, v185
	ds_write2_b32 v66, v53, v2 offset0:44 offset1:76
	v_mul_u32_u24_e32 v2, 0x110, v84
	v_add3_u32 v60, s0, v5, v2
	v_lshlrev_b32_e32 v2, 12, v84
	s_waitcnt lgkmcnt(0)
	v_lshl_add_u64 v[56:57], v[14:15], 0, v[2:3]
	ds_read_b128 v[4:7], v60
	ds_read_b128 v[8:11], v60 offset:16
	s_mov_b64 s[98:99], 0x8000
	v_lshl_add_u64 v[164:165], v[56:57], 0, s[98:99]
	v_lshl_add_u64 v[166:167], v[164:165], 0, s[98:99]
	v_lshl_add_u64 v[168:169], v[166:167], 0, s[98:99]
	global_load_dwordx4 v[132:135], v[56:57], off
	global_load_dwordx4 v[136:139], v[164:165], off
	global_load_dwordx4 v[140:143], v[166:167], off
	global_load_dwordx4 v[144:147], v[168:169], off
	global_load_dwordx4 v[148:151], v[56:57], off offset:128
	global_load_dwordx4 v[152:155], v[164:165], off offset:128
	global_load_dwordx4 v[156:159], v[166:167], off offset:128
	global_load_dwordx4 v[160:163], v[168:169], off offset:128
	v_or_b32_e32 v85, 8, v84
	v_mul_f32_e32 v18, v18, v79
	s_waitcnt vmcnt(7)
	v_lshlrev_b32_e32 v12, 16, v132
	v_mul_f32_e32 v2, 0xbfb8aa3b, v12
	v_exp_f32_e32 v2, v2
	v_and_b32_e32 v13, 0xffff0000, v132
	s_waitcnt lgkmcnt(1)
	v_pk_mul_f32 v[4:5], v[4:5], v[12:13]
	v_lshlrev_b32_e32 v12, 16, v133
	v_add_f32_e32 v2, 1.0, v2
	v_rcp_f32_e32 v16, v2
	v_mul_f32_e32 v2, 0xbfb8aa3b, v13
	v_exp_f32_e32 v2, v2
	v_and_b32_e32 v13, 0xffff0000, v133
	v_pk_mul_f32 v[6:7], v[6:7], v[12:13]
	v_add_f32_e32 v2, 1.0, v2
	v_rcp_f32_e32 v17, v2
	v_mul_f32_e32 v2, 0xbfb8aa3b, v12
	v_exp_f32_e32 v2, v2
	v_lshlrev_b32_e32 v12, 16, v134
	v_pk_mul_f32 v[4:5], v[4:5], v[16:17]
	v_add_f32_e32 v2, 1.0, v2
	v_rcp_f32_e32 v16, v2
	v_mul_f32_e32 v2, 0xbfb8aa3b, v13
	v_exp_f32_e32 v2, v2
	v_and_b32_e32 v13, 0xffff0000, v134
	s_waitcnt lgkmcnt(0)
	v_pk_mul_f32 v[8:9], v[8:9], v[12:13]
	v_cvt_pk_bf16_f32 v4, v4, v5
	v_add_f32_e32 v2, 1.0, v2
	v_rcp_f32_e32 v17, v2
	v_mul_f32_e32 v2, 0xbfb8aa3b, v12
	v_exp_f32_e32 v2, v2
	v_lshlrev_b32_e32 v12, 16, v135
	v_pk_mul_f32 v[6:7], v[6:7], v[16:17]
	v_add_f32_e32 v2, 1.0, v2
	v_rcp_f32_e32 v16, v2
	v_mul_f32_e32 v2, 0xbfb8aa3b, v13
	v_exp_f32_e32 v2, v2
	v_and_b32_e32 v13, 0xffff0000, v135
	v_pk_mul_f32 v[10:11], v[10:11], v[12:13]
	v_cvt_pk_bf16_f32 v5, v6, v7
	v_add_f32_e32 v2, 1.0, v2
	v_rcp_f32_e32 v17, v2
	v_mul_f32_e32 v2, 0xbfb8aa3b, v12
	v_exp_f32_e32 v2, v2
	v_mad_u64_u32 v[52:53], s[0:1], v84, s91, v[58:59]
	v_pk_mul_f32 v[8:9], v[8:9], v[16:17]
	v_add_f32_e32 v2, 1.0, v2
	v_rcp_f32_e32 v16, v2
	v_mul_f32_e32 v2, 0xbfb8aa3b, v13
	v_exp_f32_e32 v2, v2
	v_cvt_pk_bf16_f32 v6, v8, v9
	v_add_f32_e32 v2, 1.0, v2
	v_rcp_f32_e32 v17, v2
	v_lshlrev_b32_e32 v2, 12, v85
	v_lshl_add_u64 v[54:55], v[14:15], 0, v[2:3]
	v_pk_mul_f32 v[10:11], v[10:11], v[16:17]
	s_nop 0
	v_cvt_pk_bf16_f32 v7, v10, v11
	global_store_dwordx4 v[52:53], v[4:7], off
	ds_read_b128 v[86:89], v60 offset:2176
	ds_read_b128 v[4:7], v60 offset:2192
	s_waitcnt vmcnt(7)
	v_lshlrev_b32_e32 v12, 16, v136
	v_mul_f32_e32 v2, 0xbfb8aa3b, v12
	v_exp_f32_e32 v2, v2
	v_and_b32_e32 v13, 0xffff0000, v136
	v_lshlrev_b32_e32 v8, 16, v137
	s_waitcnt lgkmcnt(1)
	v_pk_mul_f32 v[50:51], v[86:87], v[12:13]
	v_add_f32_e32 v2, 1.0, v2
	v_rcp_f32_e32 v16, v2
	v_mul_f32_e32 v2, 0xbfb8aa3b, v13
	v_exp_f32_e32 v2, v2
	v_and_b32_e32 v9, 0xffff0000, v137
	v_add_f32_e32 v2, 1.0, v2
	v_rcp_f32_e32 v17, v2
	v_mul_f32_e32 v2, 0xbfb8aa3b, v8
	v_exp_f32_e32 v2, v2
	v_pk_mul_f32 v[12:13], v[50:51], v[16:17]
	v_pk_mul_f32 v[50:51], v[88:89], v[8:9]
	v_add_f32_e32 v2, 1.0, v2
	v_rcp_f32_e32 v16, v2
	v_mul_f32_e32 v2, 0xbfb8aa3b, v9
	v_exp_f32_e32 v2, v2
	s_nop 0
	v_add_f32_e32 v2, 1.0, v2
	v_rcp_f32_e32 v17, v2
	s_nop 0
	v_pk_mul_f32 v[8:9], v[50:51], v[16:17]
	v_lshlrev_b32_e32 v16, 16, v138
	v_mul_f32_e32 v2, 0xbfb8aa3b, v16
	v_exp_f32_e32 v2, v2
	v_and_b32_e32 v17, 0xffff0000, v138
	s_waitcnt lgkmcnt(0)
	v_pk_mul_f32 v[4:5], v[4:5], v[16:17]
	v_add_f32_e32 v2, 1.0, v2
	v_rcp_f32_e32 v50, v2
	v_mul_f32_e32 v2, 0xbfb8aa3b, v17
	v_exp_f32_e32 v2, v2
	s_nop 0
	v_add_f32_e32 v2, 1.0, v2
	v_rcp_f32_e32 v51, v2
	s_nop 0
	v_pk_mul_f32 v[16:17], v[4:5], v[50:51]
	v_lshlrev_b32_e32 v4, 16, v139
	v_mul_f32_e32 v2, 0xbfb8aa3b, v4
	v_exp_f32_e32 v2, v2
	v_and_b32_e32 v5, 0xffff0000, v139
	v_pk_mul_f32 v[6:7], v[6:7], v[4:5]
	v_cvt_pk_bf16_f32 v4, v12, v13
	v_add_f32_e32 v2, 1.0, v2
	v_rcp_f32_e32 v10, v2
	v_mul_f32_e32 v2, 0xbfb8aa3b, v5
	v_exp_f32_e32 v2, v2
	v_cvt_pk_bf16_f32 v5, v8, v9
	v_add_f32_e32 v2, 1.0, v2
	v_rcp_f32_e32 v11, v2
	s_nop 0
	v_pk_mul_f32 v[10:11], v[6:7], v[10:11]
	v_cvt_pk_bf16_f32 v6, v16, v17
	v_mad_u64_u32 v[16:17], s[0:1], v85, s91, v[58:59]
	v_or_b32_e32 v85, 16, v84
	v_cvt_pk_bf16_f32 v7, v10, v11
	v_lshlrev_b32_e32 v2, 12, v85
	global_store_dwordx4 v[16:17], v[4:7], off
	v_lshl_add_u64 v[50:51], v[14:15], 0, v[2:3]
	ds_read_b128 v[4:7], v60 offset:4352
	ds_read_b128 v[8:11], v60 offset:4368
	v_or_b32_e32 v84, 24, v84
	s_waitcnt vmcnt(7)
	v_lshlrev_b32_e32 v12, 16, v140
	v_mul_f32_e32 v2, 0xbfb8aa3b, v12
	v_exp_f32_e32 v2, v2
	v_and_b32_e32 v13, 0xffff0000, v140
	s_waitcnt lgkmcnt(1)
	v_pk_mul_f32 v[4:5], v[4:5], v[12:13]
	v_lshlrev_b32_e32 v12, 16, v141
	v_add_f32_e32 v2, 1.0, v2
	v_rcp_f32_e32 v90, v2
	v_mul_f32_e32 v2, 0xbfb8aa3b, v13
	v_exp_f32_e32 v2, v2
	v_and_b32_e32 v13, 0xffff0000, v141
	v_pk_mul_f32 v[6:7], v[6:7], v[12:13]
	v_add_f32_e32 v2, 1.0, v2
	v_rcp_f32_e32 v91, v2
	v_mul_f32_e32 v2, 0xbfb8aa3b, v12
	v_exp_f32_e32 v2, v2
	v_lshlrev_b32_e32 v12, 16, v142
	v_pk_mul_f32 v[4:5], v[4:5], v[90:91]
	v_add_f32_e32 v2, 1.0, v2
	v_rcp_f32_e32 v86, v2
	v_mul_f32_e32 v2, 0xbfb8aa3b, v13
	v_exp_f32_e32 v2, v2
	v_and_b32_e32 v13, 0xffff0000, v142
	s_waitcnt lgkmcnt(0)
	v_pk_mul_f32 v[8:9], v[8:9], v[12:13]
	v_cvt_pk_bf16_f32 v4, v4, v5
	v_add_f32_e32 v2, 1.0, v2
	v_rcp_f32_e32 v87, v2
	v_mul_f32_e32 v2, 0xbfb8aa3b, v12
	v_exp_f32_e32 v2, v2
	v_lshlrev_b32_e32 v12, 16, v143
	v_pk_mul_f32 v[6:7], v[6:7], v[86:87]
	v_add_f32_e32 v2, 1.0, v2
	v_rcp_f32_e32 v86, v2
	v_mul_f32_e32 v2, 0xbfb8aa3b, v13
	v_exp_f32_e32 v2, v2
	v_and_b32_e32 v13, 0xffff0000, v143
	v_pk_mul_f32 v[10:11], v[10:11], v[12:13]
	v_cvt_pk_bf16_f32 v5, v6, v7
	v_add_f32_e32 v2, 1.0, v2
	v_rcp_f32_e32 v87, v2
	v_mul_f32_e32 v2, 0xbfb8aa3b, v12
	v_exp_f32_e32 v2, v2
	v_pk_mul_f32 v[8:9], v[8:9], v[86:87]
	s_nop 0
	v_cvt_pk_bf16_f32 v6, v8, v9
	v_add_f32_e32 v2, 1.0, v2
	v_rcp_f32_e32 v86, v2
	v_mul_f32_e32 v2, 0xbfb8aa3b, v13
	v_exp_f32_e32 v2, v2
	v_mad_u64_u32 v[12:13], s[0:1], v85, s91, v[58:59]
	v_add_f32_e32 v2, 1.0, v2
	v_rcp_f32_e32 v87, v2
	v_lshlrev_b32_e32 v2, 12, v84
	v_lshl_add_u64 v[14:15], v[14:15], 0, v[2:3]
	v_pk_mul_f32 v[10:11], v[10:11], v[86:87]
	s_nop 0
	v_cvt_pk_bf16_f32 v7, v10, v11
	global_store_dwordx4 v[12:13], v[4:7], off
	ds_read_b128 v[8:11], v60 offset:6528
	ds_read_b128 v[4:7], v60 offset:6544
	s_waitcnt vmcnt(7)
	v_lshlrev_b32_e32 v90, 16, v144
	v_mul_f32_e32 v2, 0xbfb8aa3b, v90
	v_exp_f32_e32 v2, v2
	v_and_b32_e32 v91, 0xffff0000, v144
	v_lshlrev_b32_e32 v86, 16, v145
	v_and_b32_e32 v87, 0xffff0000, v145
	v_add_f32_e32 v2, 1.0, v2
	v_rcp_f32_e32 v92, v2
	v_mul_f32_e32 v2, 0xbfb8aa3b, v91
	v_exp_f32_e32 v2, v2
	s_waitcnt lgkmcnt(1)
	v_pk_mul_f32 v[8:9], v[8:9], v[90:91]
	v_pk_mul_f32 v[10:11], v[10:11], v[86:87]
	v_add_f32_e32 v2, 1.0, v2
	v_rcp_f32_e32 v93, v2
	v_mul_f32_e32 v2, 0xbfb8aa3b, v86
	v_exp_f32_e32 v2, v2
	v_lshlrev_b32_e32 v86, 16, v146
	v_pk_mul_f32 v[8:9], v[8:9], v[92:93]
	v_add_f32_e32 v2, 1.0, v2
	v_rcp_f32_e32 v90, v2
	v_mul_f32_e32 v2, 0xbfb8aa3b, v87
	v_exp_f32_e32 v2, v2
	v_and_b32_e32 v87, 0xffff0000, v146
	s_waitcnt lgkmcnt(0)
	v_pk_mul_f32 v[4:5], v[4:5], v[86:87]
	v_add_f32_e32 v2, 1.0, v2
	v_rcp_f32_e32 v91, v2
	v_mul_f32_e32 v2, 0xbfb8aa3b, v86
	v_exp_f32_e32 v2, v2
	v_lshlrev_b32_e32 v86, 16, v147
	v_pk_mul_f32 v[10:11], v[10:11], v[90:91]
	v_add_f32_e32 v2, 1.0, v2
	v_rcp_f32_e32 v90, v2
	v_mul_f32_e32 v2, 0xbfb8aa3b, v87
	v_exp_f32_e32 v2, v2
	v_and_b32_e32 v87, 0xffff0000, v147
	v_pk_mul_f32 v[6:7], v[6:7], v[86:87]
	v_add_f32_e32 v2, 1.0, v2
	v_rcp_f32_e32 v91, v2
	v_mul_f32_e32 v2, 0xbfb8aa3b, v86
	v_exp_f32_e32 v2, v2
	v_pk_mul_f32 v[4:5], v[4:5], v[90:91]
	v_add_f32_e32 v2, 1.0, v2
	v_rcp_f32_e32 v88, v2
	v_mul_f32_e32 v2, 0xbfb8aa3b, v87
	v_exp_f32_e32 v2, v2
	s_nop 0
	v_add_f32_e32 v2, 1.0, v2
	v_rcp_f32_e32 v89, v2
	v_mul_f32_e32 v2, v34, v79
	v_mul_f32_e32 v34, v41, v69
	v_mul_f32_e32 v41, v48, v62
	v_pk_mul_f32 v[86:87], v[6:7], v[88:89]
	v_cvt_pk_bf16_f32 v6, v8, v9
	v_cvt_pk_bf16_f32 v7, v10, v11
	v_cvt_pk_bf16_f32 v8, v4, v5
	v_cvt_pk_bf16_f32 v9, v86, v87
	v_mad_u64_u32 v[4:5], s[0:1], v84, s91, v[58:59]
	global_store_dwordx4 v[4:5], v[6:9], off
	s_waitcnt lgkmcnt(0)
	ds_write2_b32 v98, v2, v18 offset1:32
	v_mul_f32_e32 v2, v19, v77
	v_mul_f32_e32 v6, v35, v77
	v_mul_f32_e32 v7, v36, v76
	ds_write2_b32 v98, v6, v2 offset0:68 offset1:100
	v_mul_f32_e32 v2, v20, v76
	v_mul_f32_e32 v8, v37, v75
	ds_write2_b32 v98, v7, v2 offset0:136 offset1:168
	v_mul_f32_e32 v2, v21, v75
	v_mul_f32_e32 v9, v38, v74
	ds_write2_b32 v98, v8, v2 offset0:204 offset1:236
	v_mul_f32_e32 v2, v22, v74
	v_mul_f32_e32 v10, v39, v73
	ds_write2_b32 v82, v9, v2 offset0:32 offset1:64
	v_mul_f32_e32 v2, v23, v73
	v_mul_f32_e32 v11, v40, v71
	ds_write2_b32 v82, v10, v2 offset0:100 offset1:132
	v_mul_f32_e32 v2, v24, v71
	ds_write2_b32 v82, v11, v2 offset0:168 offset1:200
	v_mul_f32_e32 v2, v25, v69
	v_mul_f32_e32 v35, v42, v72
	ds_write2_b32 v83, v34, v2 offset0:108 offset1:140
	v_mul_f32_e32 v2, v26, v72
	v_mul_f32_e32 v36, v43, v70
	ds_write2_b32 v80, v35, v2 offset0:64 offset1:96
	v_mul_f32_e32 v2, v27, v70
	v_mul_f32_e32 v37, v44, v68
	ds_write2_b32 v80, v36, v2 offset0:132 offset1:164
	v_mul_f32_e32 v2, v28, v68
	v_mul_f32_e32 v38, v45, v67
	ds_write2_b32 v80, v37, v2 offset0:200 offset1:232
	v_mul_f32_e32 v2, v29, v67
	v_mul_f32_e32 v39, v46, v78
	ds_write2_b32 v81, v38, v2 offset0:12 offset1:44
	v_mul_f32_e32 v2, v30, v78
	v_mul_f32_e32 v40, v47, v63
	ds_write2_b32 v64, v39, v2 offset0:96 offset1:128
	v_mul_f32_e32 v2, v31, v63
	ds_write2_b32 v64, v40, v2 offset0:164 offset1:196
	v_mul_f32_e32 v2, v32, v62
	v_mul_f32_e32 v42, v49, v61
	ds_write2_b32 v65, v41, v2 offset0:104 offset1:136
	v_mul_f32_e32 v2, v33, v61
	ds_write2_b32 v66, v42, v2 offset0:44 offset1:76
	s_waitcnt lgkmcnt(0)
	ds_read_b128 v[6:9], v60
	ds_read_b128 v[18:21], v60 offset:16
	s_waitcnt vmcnt(7)
	v_lshlrev_b32_e32 v10, 16, v148
	v_mul_f32_e32 v2, 0xbfb8aa3b, v10
	v_exp_f32_e32 v2, v2
	v_and_b32_e32 v11, 0xffff0000, v148
	s_waitcnt lgkmcnt(1)
	v_pk_mul_f32 v[6:7], v[6:7], v[10:11]
	v_lshlrev_b32_e32 v10, 16, v149
	v_add_f32_e32 v2, 1.0, v2
	v_rcp_f32_e32 v26, v2
	v_mul_f32_e32 v2, 0xbfb8aa3b, v11
	v_exp_f32_e32 v2, v2
	v_and_b32_e32 v11, 0xffff0000, v149
	v_pk_mul_f32 v[8:9], v[8:9], v[10:11]
	v_add_f32_e32 v2, 1.0, v2
	v_rcp_f32_e32 v27, v2
	v_mul_f32_e32 v2, 0xbfb8aa3b, v10
	v_exp_f32_e32 v2, v2
	v_lshlrev_b32_e32 v10, 16, v150
	v_pk_mul_f32 v[6:7], v[6:7], v[26:27]
	v_add_f32_e32 v2, 1.0, v2
	v_rcp_f32_e32 v22, v2
	v_mul_f32_e32 v2, 0xbfb8aa3b, v11
	v_exp_f32_e32 v2, v2
	v_and_b32_e32 v11, 0xffff0000, v150
	s_waitcnt lgkmcnt(0)
	v_pk_mul_f32 v[18:19], v[18:19], v[10:11]
	v_cvt_pk_bf16_f32 v6, v6, v7
	v_add_f32_e32 v2, 1.0, v2
	v_rcp_f32_e32 v23, v2
	v_mul_f32_e32 v2, 0xbfb8aa3b, v10
	v_exp_f32_e32 v2, v2
	v_pk_mul_f32 v[8:9], v[8:9], v[22:23]
	s_nop 0
	v_cvt_pk_bf16_f32 v7, v8, v9
	v_add_f32_e32 v2, 1.0, v2
	v_rcp_f32_e32 v22, v2
	v_mul_f32_e32 v2, 0xbfb8aa3b, v11
	v_exp_f32_e32 v2, v2
	s_nop 0
	v_add_f32_e32 v2, 1.0, v2
	v_rcp_f32_e32 v23, v2
	s_nop 0
	v_pk_mul_f32 v[10:11], v[18:19], v[22:23]
	v_lshlrev_b32_e32 v18, 16, v151
	v_mul_f32_e32 v2, 0xbfb8aa3b, v18
	v_exp_f32_e32 v2, v2
	v_and_b32_e32 v19, 0xffff0000, v151
	v_pk_mul_f32 v[20:21], v[20:21], v[18:19]
	v_cvt_pk_bf16_f32 v8, v10, v11
	v_add_f32_e32 v2, 1.0, v2
	v_rcp_f32_e32 v22, v2
	v_mul_f32_e32 v2, 0xbfb8aa3b, v19
	v_exp_f32_e32 v2, v2
	s_nop 0
	v_add_f32_e32 v2, 1.0, v2
	v_rcp_f32_e32 v23, v2
	s_nop 0
	v_pk_mul_f32 v[18:19], v[20:21], v[22:23]
	s_nop 0
	v_cvt_pk_bf16_f32 v9, v18, v19
	global_store_dwordx4 v[52:53], v[6:9], off offset:128
	ds_read_b128 v[6:9], v60 offset:2176
	ds_read_b128 v[18:21], v60 offset:2192
	s_waitcnt vmcnt(7)
	v_lshlrev_b32_e32 v10, 16, v152
	v_mul_f32_e32 v2, 0xbfb8aa3b, v10
	v_exp_f32_e32 v2, v2
	v_and_b32_e32 v11, 0xffff0000, v152
	s_waitcnt lgkmcnt(1)
	v_pk_mul_f32 v[6:7], v[6:7], v[10:11]
	v_lshlrev_b32_e32 v10, 16, v153
	v_add_f32_e32 v2, 1.0, v2
	v_rcp_f32_e32 v26, v2
	v_mul_f32_e32 v2, 0xbfb8aa3b, v11
	v_exp_f32_e32 v2, v2
	v_and_b32_e32 v11, 0xffff0000, v153
	v_pk_mul_f32 v[8:9], v[8:9], v[10:11]
	v_add_f32_e32 v2, 1.0, v2
	v_rcp_f32_e32 v27, v2
	v_mul_f32_e32 v2, 0xbfb8aa3b, v10
	v_exp_f32_e32 v2, v2
	v_lshlrev_b32_e32 v10, 16, v154
	v_pk_mul_f32 v[6:7], v[6:7], v[26:27]
	v_add_f32_e32 v2, 1.0, v2
	v_rcp_f32_e32 v22, v2
	v_mul_f32_e32 v2, 0xbfb8aa3b, v11
	v_exp_f32_e32 v2, v2
	v_and_b32_e32 v11, 0xffff0000, v154
	s_waitcnt lgkmcnt(0)
	v_pk_mul_f32 v[18:19], v[18:19], v[10:11]
	v_cvt_pk_bf16_f32 v6, v6, v7
	v_add_f32_e32 v2, 1.0, v2
	v_rcp_f32_e32 v23, v2
	v_mul_f32_e32 v2, 0xbfb8aa3b, v10
	v_exp_f32_e32 v2, v2
	v_pk_mul_f32 v[8:9], v[8:9], v[22:23]
	s_nop 0
	v_cvt_pk_bf16_f32 v7, v8, v9
	v_add_f32_e32 v2, 1.0, v2
	v_rcp_f32_e32 v22, v2
	v_mul_f32_e32 v2, 0xbfb8aa3b, v11
	v_exp_f32_e32 v2, v2
	s_nop 0
	v_add_f32_e32 v2, 1.0, v2
	v_rcp_f32_e32 v23, v2
	s_nop 0
	v_pk_mul_f32 v[10:11], v[18:19], v[22:23]
	v_lshlrev_b32_e32 v18, 16, v155
	v_mul_f32_e32 v2, 0xbfb8aa3b, v18
	v_exp_f32_e32 v2, v2
	v_and_b32_e32 v19, 0xffff0000, v155
	v_pk_mul_f32 v[20:21], v[20:21], v[18:19]
	v_cvt_pk_bf16_f32 v8, v10, v11
	v_add_f32_e32 v2, 1.0, v2
	v_rcp_f32_e32 v22, v2
	v_mul_f32_e32 v2, 0xbfb8aa3b, v19
	v_exp_f32_e32 v2, v2
	s_nop 0
	v_add_f32_e32 v2, 1.0, v2
	v_rcp_f32_e32 v23, v2
	s_nop 0
	v_pk_mul_f32 v[18:19], v[20:21], v[22:23]
	s_nop 0
	v_cvt_pk_bf16_f32 v9, v18, v19
	global_store_dwordx4 v[16:17], v[6:9], off offset:128
	ds_read_b128 v[6:9], v60 offset:4352
	ds_read_b128 v[16:19], v60 offset:4368
	s_waitcnt vmcnt(7)
	v_lshlrev_b32_e32 v10, 16, v156
	v_mul_f32_e32 v2, 0xbfb8aa3b, v10
	v_exp_f32_e32 v2, v2
	v_and_b32_e32 v11, 0xffff0000, v156
	s_waitcnt lgkmcnt(1)
	v_pk_mul_f32 v[6:7], v[6:7], v[10:11]
	v_lshlrev_b32_e32 v10, 16, v157
	v_add_f32_e32 v2, 1.0, v2
	v_rcp_f32_e32 v24, v2
	v_mul_f32_e32 v2, 0xbfb8aa3b, v11
	v_exp_f32_e32 v2, v2
	v_and_b32_e32 v11, 0xffff0000, v157
	v_pk_mul_f32 v[8:9], v[8:9], v[10:11]
	v_add_f32_e32 v2, 1.0, v2
	v_rcp_f32_e32 v25, v2
	v_mul_f32_e32 v2, 0xbfb8aa3b, v10
	v_exp_f32_e32 v2, v2
	v_lshlrev_b32_e32 v10, 16, v158
	v_pk_mul_f32 v[6:7], v[6:7], v[24:25]
	v_add_f32_e32 v2, 1.0, v2
	v_rcp_f32_e32 v20, v2
	v_mul_f32_e32 v2, 0xbfb8aa3b, v11
	v_exp_f32_e32 v2, v2
	v_and_b32_e32 v11, 0xffff0000, v158
	s_waitcnt lgkmcnt(0)
	v_pk_mul_f32 v[16:17], v[16:17], v[10:11]
	v_cvt_pk_bf16_f32 v6, v6, v7
	v_add_f32_e32 v2, 1.0, v2
	v_rcp_f32_e32 v21, v2
	v_mul_f32_e32 v2, 0xbfb8aa3b, v10
	v_exp_f32_e32 v2, v2
	v_pk_mul_f32 v[8:9], v[8:9], v[20:21]
	s_nop 0
	v_cvt_pk_bf16_f32 v7, v8, v9
	v_add_f32_e32 v2, 1.0, v2
	v_rcp_f32_e32 v20, v2
	v_mul_f32_e32 v2, 0xbfb8aa3b, v11
	v_exp_f32_e32 v2, v2
	s_nop 0
	v_add_f32_e32 v2, 1.0, v2
	v_rcp_f32_e32 v21, v2
	s_nop 0
	v_pk_mul_f32 v[10:11], v[16:17], v[20:21]
	v_lshlrev_b32_e32 v16, 16, v159
	v_mul_f32_e32 v2, 0xbfb8aa3b, v16
	v_exp_f32_e32 v2, v2
	v_and_b32_e32 v17, 0xffff0000, v159
	v_pk_mul_f32 v[18:19], v[18:19], v[16:17]
	v_cvt_pk_bf16_f32 v8, v10, v11
	v_add_f32_e32 v2, 1.0, v2
	v_rcp_f32_e32 v20, v2
	v_mul_f32_e32 v2, 0xbfb8aa3b, v17
	v_exp_f32_e32 v2, v2
	s_nop 0
	v_add_f32_e32 v2, 1.0, v2
	v_rcp_f32_e32 v21, v2
	s_nop 0
	v_pk_mul_f32 v[16:17], v[18:19], v[20:21]
	s_nop 0
	v_cvt_pk_bf16_f32 v9, v16, v17
	global_store_dwordx4 v[12:13], v[6:9], off offset:128
	ds_read_b128 v[6:9], v60 offset:6528
	ds_read_b128 v[10:13], v60 offset:6544
	s_waitcnt vmcnt(7)
	v_lshlrev_b32_e32 v18, 16, v160
	v_mul_f32_e32 v2, 0xbfb8aa3b, v18
	v_exp_f32_e32 v2, v2
	v_and_b32_e32 v19, 0xffff0000, v160
	v_lshlrev_b32_e32 v14, 16, v161
	v_and_b32_e32 v15, 0xffff0000, v161
	v_add_f32_e32 v2, 1.0, v2
	v_rcp_f32_e32 v20, v2
	v_mul_f32_e32 v2, 0xbfb8aa3b, v19
	v_exp_f32_e32 v2, v2
	s_waitcnt lgkmcnt(1)
	v_pk_mul_f32 v[6:7], v[6:7], v[18:19]
	v_pk_mul_f32 v[8:9], v[8:9], v[14:15]
	v_add_f32_e32 v2, 1.0, v2
	v_rcp_f32_e32 v21, v2
	v_mul_f32_e32 v2, 0xbfb8aa3b, v14
	v_exp_f32_e32 v2, v2
	v_lshlrev_b32_e32 v14, 16, v162
	v_pk_mul_f32 v[6:7], v[6:7], v[20:21]
	v_add_f32_e32 v2, 1.0, v2
	v_rcp_f32_e32 v18, v2
	v_mul_f32_e32 v2, 0xbfb8aa3b, v15
	v_exp_f32_e32 v2, v2
	v_and_b32_e32 v15, 0xffff0000, v162
	s_waitcnt lgkmcnt(0)
	v_pk_mul_f32 v[10:11], v[10:11], v[14:15]
	v_cvt_pk_bf16_f32 v6, v6, v7
	v_add_f32_e32 v2, 1.0, v2
	v_rcp_f32_e32 v19, v2
	v_mul_f32_e32 v2, 0xbfb8aa3b, v14
	v_exp_f32_e32 v2, v2
	v_lshlrev_b32_e32 v14, 16, v163
	v_pk_mul_f32 v[8:9], v[8:9], v[18:19]
	v_add_f32_e32 v2, 1.0, v2
	v_rcp_f32_e32 v18, v2
	v_mul_f32_e32 v2, 0xbfb8aa3b, v15
	v_exp_f32_e32 v2, v2
	v_and_b32_e32 v15, 0xffff0000, v163
	v_pk_mul_f32 v[12:13], v[12:13], v[14:15]
	v_cvt_pk_bf16_f32 v7, v8, v9
	v_add_f32_e32 v2, 1.0, v2
	v_rcp_f32_e32 v19, v2
	v_mul_f32_e32 v2, 0xbfb8aa3b, v14
	v_exp_f32_e32 v2, v2
	v_pk_mul_f32 v[10:11], v[10:11], v[18:19]
	s_nop 0
	v_cvt_pk_bf16_f32 v8, v10, v11
	v_add_f32_e32 v2, 1.0, v2
	v_rcp_f32_e32 v16, v2
	v_mul_f32_e32 v2, 0xbfb8aa3b, v15
	v_exp_f32_e32 v2, v2
	s_nop 0
	v_add_f32_e32 v2, 1.0, v2
	v_rcp_f32_e32 v17, v2
	s_nop 0
	v_pk_mul_f32 v[12:13], v[12:13], v[16:17]
	s_nop 0
	v_cvt_pk_bf16_f32 v9, v12, v13
	global_store_dwordx4 v[4:5], v[6:9], off offset:128
	s_waitcnt lgkmcnt(0)
	s_barrier

.LBB0_2699:
	s_waitcnt vmcnt(0)
	s_waitcnt vmcnt(0) lgkmcnt(0)
	s_barrier
	s_and_saveexec_b64 s[18:19], s[6:7]
	ds_write_b32 v205, v234
	s_or_b64 exec, exec, s[18:19]
	s_waitcnt lgkmcnt(0)
	ds_read_b128 v[4:7], v190
	ds_read_b128 v[8:11], v190 offset:32
	s_or_b32 s6, s16, s43
	s_ashr_i32 s7, s44, 31
	s_add_u32 s16, s6, s44
	s_addc_u32 s17, s17, s7
	s_waitcnt lgkmcnt(1)
	v_rcp_f32_e32 v79, v4
	v_rcp_f32_e32 v77, v5
	v_rcp_f32_e32 v76, v6
	v_rcp_f32_e32 v75, v7
	ds_read_b128 v[4:7], v190 offset:64
	s_mul_i32 s6, s17, 0x3000
	s_mul_hi_u32 s7, s16, 0x3000
	s_add_i32 s7, s7, s6
	s_mul_i32 s6, s16, 0x3000
	s_add_u32 s6, s34, s6
	s_addc_u32 s7, s35, s7
	s_lshl_b32 s15, s42, 8
	s_add_u32 s6, s6, s15
	s_waitcnt lgkmcnt(0)
	v_rcp_f32_e32 v72, v4
	v_rcp_f32_e32 v70, v5
	v_rcp_f32_e32 v68, v6
	v_rcp_f32_e32 v67, v7
	ds_read_b128 v[4:7], v190 offset:96
	s_addc_u32 s7, s7, 0
	s_lshl_b64 s[16:17], s[16:17], 12
	s_add_u32 s16, s30, s16
	s_addc_u32 s17, s31, s17
	s_add_u32 s16, s16, s15
	s_mulk_i32 s40, 0x2200
	v_and_b32_e32 v2, 56, v188
	s_addc_u32 s17, s17, 0
	s_add_i32 s15, s40, 0
	s_waitcnt lgkmcnt(0)
	v_rcp_f32_e32 v78, v4
	v_rcp_f32_e32 v63, v5
	v_rcp_f32_e32 v62, v6
	v_lshlrev_b32_e32 v4, 2, v186
	v_lshlrev_b32_e32 v5, 2, v2
	v_lshlrev_b32_e32 v2, 1, v2
	v_mul_u32_u24_e32 v6, 0x440, v187
	v_rcp_f32_e32 v74, v8
	v_lshl_add_u64 v[14:15], s[16:17], 0, v[2:3]
	v_lshl_add_u64 v[58:59], s[6:7], 0, v[2:3]
	v_mul_f32_e32 v2, v98, v79
	v_add3_u32 v98, s15, v4, v6
	v_mul_f32_e32 v54, v82, v79
	v_rcp_f32_e32 v73, v9
	v_mul_f32_e32 v4, v99, v77
	ds_write2_b32 v98, v2, v54 offset1:32
	v_mul_f32_e32 v2, v83, v77
	v_rcp_f32_e32 v71, v10
	v_mul_f32_e32 v6, v100, v76
	ds_write2_b32 v98, v4, v2 offset0:68 offset1:100
	v_mul_f32_e32 v2, v84, v76
	v_rcp_f32_e32 v69, v11
	v_rcp_f32_e32 v61, v7
	v_mul_f32_e32 v7, v101, v75
	ds_write2_b32 v98, v6, v2 offset0:136 offset1:168
	v_mul_f32_e32 v2, v85, v75
	v_mul_f32_e32 v8, v102, v74
	ds_write2_b32 v98, v7, v2 offset0:204 offset1:236
	v_mul_f32_e32 v2, v86, v74
	v_add_u32_e32 v82, 0x800, v98
	v_mul_f32_e32 v9, v103, v73
	ds_write2_b32 v82, v8, v2 offset0:32 offset1:64
	v_mul_f32_e32 v2, v87, v73
	v_mul_f32_e32 v10, v104, v71
	ds_write2_b32 v82, v9, v2 offset0:100 offset1:132
	v_mul_f32_e32 v2, v88, v71
	v_mul_f32_e32 v11, v105, v69
	ds_write2_b32 v82, v10, v2 offset0:168 offset1:200
	v_mul_f32_e32 v2, v89, v69
	v_add_u32_e32 v83, 0xa00, v98
	v_mul_f32_e32 v12, v106, v72
	ds_write2_b32 v83, v11, v2 offset0:108 offset1:140
	v_mul_f32_e32 v2, v90, v72
	v_add_u32_e32 v80, 0x1000, v98
	v_mul_f32_e32 v13, v107, v70
	ds_write2_b32 v80, v12, v2 offset0:64 offset1:96
	v_mul_f32_e32 v2, v91, v70
	v_mul_f32_e32 v16, v108, v68
	ds_write2_b32 v80, v13, v2 offset0:132 offset1:164
	v_mul_f32_e32 v2, v92, v68
	v_mul_f32_e32 v17, v109, v67
	ds_write2_b32 v80, v16, v2 offset0:200 offset1:232
	v_mul_f32_e32 v2, v93, v67
	v_add_u32_e32 v81, 0x1400, v98
	v_mul_f32_e32 v50, v110, v78
	ds_write2_b32 v81, v17, v2 offset0:12 offset1:44
	v_mul_f32_e32 v2, v94, v78
	v_add_u32_e32 v64, 0x1800, v98
	v_mul_f32_e32 v51, v111, v63
	ds_write2_b32 v64, v50, v2 offset0:96 offset1:128
	v_mul_f32_e32 v2, v95, v63
	v_mul_f32_e32 v52, v112, v62
	ds_write2_b32 v64, v51, v2 offset0:164 offset1:196
	v_mul_f32_e32 v2, v96, v62
	v_add_u32_e32 v65, 0x1a00, v98
	v_mul_f32_e32 v53, v113, v61
	ds_write2_b32 v65, v52, v2 offset0:104 offset1:136
	v_mul_f32_e32 v2, v97, v61
	v_add_u32_e32 v66, 0x1c00, v98
	v_lshrrev_b32_e32 v84, 3, v185
	ds_write2_b32 v66, v53, v2 offset0:44 offset1:76
	v_mul_u32_u24_e32 v2, 0x110, v84
	v_add3_u32 v60, s15, v5, v2
	v_lshlrev_b32_e32 v2, 12, v84
	s_waitcnt lgkmcnt(0)
	v_lshl_add_u64 v[56:57], v[14:15], 0, v[2:3]
	ds_read_b128 v[4:7], v60
	ds_read_b128 v[8:11], v60 offset:16
	s_mov_b64 s[98:99], 0x8000
	v_lshl_add_u64 v[164:165], v[56:57], 0, s[98:99]
	v_lshl_add_u64 v[166:167], v[164:165], 0, s[98:99]
	v_lshl_add_u64 v[168:169], v[166:167], 0, s[98:99]
	global_load_dwordx4 v[132:135], v[56:57], off
	global_load_dwordx4 v[136:139], v[164:165], off
	global_load_dwordx4 v[140:143], v[166:167], off
	global_load_dwordx4 v[144:147], v[168:169], off
	global_load_dwordx4 v[148:151], v[56:57], off offset:128
	global_load_dwordx4 v[152:155], v[164:165], off offset:128
	global_load_dwordx4 v[156:159], v[166:167], off offset:128
	global_load_dwordx4 v[160:163], v[168:169], off offset:128
	v_or_b32_e32 v85, 8, v84
	v_mul_f32_e32 v18, v18, v79
	s_movk_i32 s55, 0x1ff
	s_waitcnt vmcnt(7)
	v_lshlrev_b32_e32 v12, 16, v132
	v_mul_f32_e32 v2, 0xbfb8aa3b, v12
	v_exp_f32_e32 v2, v2
	v_and_b32_e32 v13, 0xffff0000, v132
	s_waitcnt lgkmcnt(1)
	v_pk_mul_f32 v[4:5], v[4:5], v[12:13]
	v_lshlrev_b32_e32 v12, 16, v133
	v_add_f32_e32 v2, 1.0, v2
	v_rcp_f32_e32 v16, v2
	v_mul_f32_e32 v2, 0xbfb8aa3b, v13
	v_exp_f32_e32 v2, v2
	v_and_b32_e32 v13, 0xffff0000, v133
	v_pk_mul_f32 v[6:7], v[6:7], v[12:13]
	v_add_f32_e32 v2, 1.0, v2
	v_rcp_f32_e32 v17, v2
	v_mul_f32_e32 v2, 0xbfb8aa3b, v12
	v_exp_f32_e32 v2, v2
	v_lshlrev_b32_e32 v12, 16, v134
	v_pk_mul_f32 v[4:5], v[4:5], v[16:17]
	v_add_f32_e32 v2, 1.0, v2
	v_rcp_f32_e32 v16, v2
	v_mul_f32_e32 v2, 0xbfb8aa3b, v13
	v_exp_f32_e32 v2, v2
	v_and_b32_e32 v13, 0xffff0000, v134
	s_waitcnt lgkmcnt(0)
	v_pk_mul_f32 v[8:9], v[8:9], v[12:13]
	v_cvt_pk_bf16_f32 v4, v4, v5
	v_add_f32_e32 v2, 1.0, v2
	v_rcp_f32_e32 v17, v2
	v_mul_f32_e32 v2, 0xbfb8aa3b, v12
	v_exp_f32_e32 v2, v2
	v_lshlrev_b32_e32 v12, 16, v135
	v_pk_mul_f32 v[6:7], v[6:7], v[16:17]
	v_add_f32_e32 v2, 1.0, v2
	v_rcp_f32_e32 v16, v2
	v_mul_f32_e32 v2, 0xbfb8aa3b, v13
	v_exp_f32_e32 v2, v2
	v_and_b32_e32 v13, 0xffff0000, v135
	v_pk_mul_f32 v[10:11], v[10:11], v[12:13]
	v_cvt_pk_bf16_f32 v5, v6, v7
	v_add_f32_e32 v2, 1.0, v2
	v_rcp_f32_e32 v17, v2
	v_mul_f32_e32 v2, 0xbfb8aa3b, v12
	v_exp_f32_e32 v2, v2
	v_mad_u64_u32 v[52:53], s[6:7], v84, s91, v[58:59]
	v_pk_mul_f32 v[8:9], v[8:9], v[16:17]
	v_add_f32_e32 v2, 1.0, v2
	v_rcp_f32_e32 v16, v2
	v_mul_f32_e32 v2, 0xbfb8aa3b, v13
	v_exp_f32_e32 v2, v2
	v_cvt_pk_bf16_f32 v6, v8, v9
	v_add_f32_e32 v2, 1.0, v2
	v_rcp_f32_e32 v17, v2
	v_lshlrev_b32_e32 v2, 12, v85
	v_lshl_add_u64 v[54:55], v[14:15], 0, v[2:3]
	v_pk_mul_f32 v[10:11], v[10:11], v[16:17]
	s_nop 0
	v_cvt_pk_bf16_f32 v7, v10, v11
	global_store_dwordx4 v[52:53], v[4:7], off
	ds_read_b128 v[86:89], v60 offset:2176
	ds_read_b128 v[4:7], v60 offset:2192
	s_waitcnt vmcnt(7)
	v_lshlrev_b32_e32 v12, 16, v136
	v_mul_f32_e32 v2, 0xbfb8aa3b, v12
	v_exp_f32_e32 v2, v2
	v_and_b32_e32 v13, 0xffff0000, v136
	v_lshlrev_b32_e32 v8, 16, v137
	s_waitcnt lgkmcnt(1)
	v_pk_mul_f32 v[50:51], v[86:87], v[12:13]
	v_add_f32_e32 v2, 1.0, v2
	v_rcp_f32_e32 v16, v2
	v_mul_f32_e32 v2, 0xbfb8aa3b, v13
	v_exp_f32_e32 v2, v2
	v_and_b32_e32 v9, 0xffff0000, v137
	v_add_f32_e32 v2, 1.0, v2
	v_rcp_f32_e32 v17, v2
	v_mul_f32_e32 v2, 0xbfb8aa3b, v8
	v_exp_f32_e32 v2, v2
	v_pk_mul_f32 v[12:13], v[50:51], v[16:17]
	v_pk_mul_f32 v[50:51], v[88:89], v[8:9]
	v_add_f32_e32 v2, 1.0, v2
	v_rcp_f32_e32 v16, v2
	v_mul_f32_e32 v2, 0xbfb8aa3b, v9
	v_exp_f32_e32 v2, v2
	s_nop 0
	v_add_f32_e32 v2, 1.0, v2
	v_rcp_f32_e32 v17, v2
	s_nop 0
	v_pk_mul_f32 v[8:9], v[50:51], v[16:17]
	v_lshlrev_b32_e32 v16, 16, v138
	v_mul_f32_e32 v2, 0xbfb8aa3b, v16
	v_exp_f32_e32 v2, v2
	v_and_b32_e32 v17, 0xffff0000, v138
	s_waitcnt lgkmcnt(0)
	v_pk_mul_f32 v[4:5], v[4:5], v[16:17]
	v_add_f32_e32 v2, 1.0, v2
	v_rcp_f32_e32 v50, v2
	v_mul_f32_e32 v2, 0xbfb8aa3b, v17
	v_exp_f32_e32 v2, v2
	s_nop 0
	v_add_f32_e32 v2, 1.0, v2
	v_rcp_f32_e32 v51, v2
	s_nop 0
	v_pk_mul_f32 v[16:17], v[4:5], v[50:51]
	v_lshlrev_b32_e32 v4, 16, v139
	v_mul_f32_e32 v2, 0xbfb8aa3b, v4
	v_exp_f32_e32 v2, v2
	v_and_b32_e32 v5, 0xffff0000, v139
	v_pk_mul_f32 v[6:7], v[6:7], v[4:5]
	v_cvt_pk_bf16_f32 v4, v12, v13
	v_add_f32_e32 v2, 1.0, v2
	v_rcp_f32_e32 v10, v2
	v_mul_f32_e32 v2, 0xbfb8aa3b, v5
	v_exp_f32_e32 v2, v2
	v_cvt_pk_bf16_f32 v5, v8, v9
	v_add_f32_e32 v2, 1.0, v2
	v_rcp_f32_e32 v11, v2
	s_nop 0
	v_pk_mul_f32 v[10:11], v[6:7], v[10:11]
	v_cvt_pk_bf16_f32 v6, v16, v17
	v_mad_u64_u32 v[16:17], s[6:7], v85, s91, v[58:59]
	v_or_b32_e32 v85, 16, v84
	v_cvt_pk_bf16_f32 v7, v10, v11
	v_lshlrev_b32_e32 v2, 12, v85
	global_store_dwordx4 v[16:17], v[4:7], off
	v_lshl_add_u64 v[50:51], v[14:15], 0, v[2:3]
	ds_read_b128 v[4:7], v60 offset:4352
	ds_read_b128 v[8:11], v60 offset:4368
	v_or_b32_e32 v84, 24, v84
	s_waitcnt vmcnt(7)
	v_lshlrev_b32_e32 v12, 16, v140
	v_mul_f32_e32 v2, 0xbfb8aa3b, v12
	v_exp_f32_e32 v2, v2
	v_and_b32_e32 v13, 0xffff0000, v140
	s_waitcnt lgkmcnt(1)
	v_pk_mul_f32 v[4:5], v[4:5], v[12:13]
	v_lshlrev_b32_e32 v12, 16, v141
	v_add_f32_e32 v2, 1.0, v2
	v_rcp_f32_e32 v90, v2
	v_mul_f32_e32 v2, 0xbfb8aa3b, v13
	v_exp_f32_e32 v2, v2
	v_and_b32_e32 v13, 0xffff0000, v141
	v_pk_mul_f32 v[6:7], v[6:7], v[12:13]
	v_add_f32_e32 v2, 1.0, v2
	v_rcp_f32_e32 v91, v2
	v_mul_f32_e32 v2, 0xbfb8aa3b, v12
	v_exp_f32_e32 v2, v2
	v_lshlrev_b32_e32 v12, 16, v142
	v_pk_mul_f32 v[4:5], v[4:5], v[90:91]
	v_add_f32_e32 v2, 1.0, v2
	v_rcp_f32_e32 v86, v2
	v_mul_f32_e32 v2, 0xbfb8aa3b, v13
	v_exp_f32_e32 v2, v2
	v_and_b32_e32 v13, 0xffff0000, v142
	s_waitcnt lgkmcnt(0)
	v_pk_mul_f32 v[8:9], v[8:9], v[12:13]
	v_cvt_pk_bf16_f32 v4, v4, v5
	v_add_f32_e32 v2, 1.0, v2
	v_rcp_f32_e32 v87, v2
	v_mul_f32_e32 v2, 0xbfb8aa3b, v12
	v_exp_f32_e32 v2, v2
	v_lshlrev_b32_e32 v12, 16, v143
	v_pk_mul_f32 v[6:7], v[6:7], v[86:87]
	v_add_f32_e32 v2, 1.0, v2
	v_rcp_f32_e32 v86, v2
	v_mul_f32_e32 v2, 0xbfb8aa3b, v13
	v_exp_f32_e32 v2, v2
	v_and_b32_e32 v13, 0xffff0000, v143
	v_pk_mul_f32 v[10:11], v[10:11], v[12:13]
	v_cvt_pk_bf16_f32 v5, v6, v7
	v_add_f32_e32 v2, 1.0, v2
	v_rcp_f32_e32 v87, v2
	v_mul_f32_e32 v2, 0xbfb8aa3b, v12
	v_exp_f32_e32 v2, v2
	v_pk_mul_f32 v[8:9], v[8:9], v[86:87]
	s_nop 0
	v_cvt_pk_bf16_f32 v6, v8, v9
	v_add_f32_e32 v2, 1.0, v2
	v_rcp_f32_e32 v86, v2
	v_mul_f32_e32 v2, 0xbfb8aa3b, v13
	v_exp_f32_e32 v2, v2
	v_mad_u64_u32 v[12:13], s[6:7], v85, s91, v[58:59]
	v_add_f32_e32 v2, 1.0, v2
	v_rcp_f32_e32 v87, v2
	v_lshlrev_b32_e32 v2, 12, v84
	v_lshl_add_u64 v[14:15], v[14:15], 0, v[2:3]
	v_pk_mul_f32 v[10:11], v[10:11], v[86:87]
	s_nop 0
	v_cvt_pk_bf16_f32 v7, v10, v11
	global_store_dwordx4 v[12:13], v[4:7], off
	ds_read_b128 v[8:11], v60 offset:6528
	ds_read_b128 v[4:7], v60 offset:6544
	s_waitcnt vmcnt(7)
	v_lshlrev_b32_e32 v90, 16, v144
	v_mul_f32_e32 v2, 0xbfb8aa3b, v90
	v_exp_f32_e32 v2, v2
	v_and_b32_e32 v91, 0xffff0000, v144
	v_lshlrev_b32_e32 v86, 16, v145
	v_and_b32_e32 v87, 0xffff0000, v145
	v_add_f32_e32 v2, 1.0, v2
	v_rcp_f32_e32 v92, v2
	v_mul_f32_e32 v2, 0xbfb8aa3b, v91
	v_exp_f32_e32 v2, v2
	s_waitcnt lgkmcnt(1)
	v_pk_mul_f32 v[8:9], v[8:9], v[90:91]
	v_pk_mul_f32 v[10:11], v[10:11], v[86:87]
	v_add_f32_e32 v2, 1.0, v2
	v_rcp_f32_e32 v93, v2
	v_mul_f32_e32 v2, 0xbfb8aa3b, v86
	v_exp_f32_e32 v2, v2
	v_lshlrev_b32_e32 v86, 16, v146
	v_pk_mul_f32 v[8:9], v[8:9], v[92:93]
	v_add_f32_e32 v2, 1.0, v2
	v_rcp_f32_e32 v90, v2
	v_mul_f32_e32 v2, 0xbfb8aa3b, v87
	v_exp_f32_e32 v2, v2
	v_and_b32_e32 v87, 0xffff0000, v146
	s_waitcnt lgkmcnt(0)
	v_pk_mul_f32 v[4:5], v[4:5], v[86:87]
	v_add_f32_e32 v2, 1.0, v2
	v_rcp_f32_e32 v91, v2
	v_mul_f32_e32 v2, 0xbfb8aa3b, v86
	v_exp_f32_e32 v2, v2
	v_lshlrev_b32_e32 v86, 16, v147
	v_pk_mul_f32 v[10:11], v[10:11], v[90:91]
	v_add_f32_e32 v2, 1.0, v2
	v_rcp_f32_e32 v90, v2
	v_mul_f32_e32 v2, 0xbfb8aa3b, v87
	v_exp_f32_e32 v2, v2
	v_and_b32_e32 v87, 0xffff0000, v147
	v_pk_mul_f32 v[6:7], v[6:7], v[86:87]
	v_add_f32_e32 v2, 1.0, v2
	v_rcp_f32_e32 v91, v2
	v_mul_f32_e32 v2, 0xbfb8aa3b, v86
	v_exp_f32_e32 v2, v2
	v_pk_mul_f32 v[4:5], v[4:5], v[90:91]
	v_add_f32_e32 v2, 1.0, v2
	v_rcp_f32_e32 v88, v2
	v_mul_f32_e32 v2, 0xbfb8aa3b, v87
	v_exp_f32_e32 v2, v2
	s_nop 0
	v_add_f32_e32 v2, 1.0, v2
	v_rcp_f32_e32 v89, v2
	v_mul_f32_e32 v2, v34, v79
	v_mul_f32_e32 v34, v41, v69
	v_mul_f32_e32 v41, v48, v62
	v_pk_mul_f32 v[86:87], v[6:7], v[88:89]
	v_cvt_pk_bf16_f32 v6, v8, v9
	v_cvt_pk_bf16_f32 v7, v10, v11
	v_cvt_pk_bf16_f32 v8, v4, v5
	v_cvt_pk_bf16_f32 v9, v86, v87
	v_mad_u64_u32 v[4:5], s[6:7], v84, s91, v[58:59]
	global_store_dwordx4 v[4:5], v[6:9], off
	s_waitcnt lgkmcnt(0)
	ds_write2_b32 v98, v2, v18 offset1:32
	v_mul_f32_e32 v2, v19, v77
	v_mul_f32_e32 v6, v35, v77
	v_mul_f32_e32 v7, v36, v76
	ds_write2_b32 v98, v6, v2 offset0:68 offset1:100
	v_mul_f32_e32 v2, v20, v76
	v_mul_f32_e32 v8, v37, v75
	ds_write2_b32 v98, v7, v2 offset0:136 offset1:168
	v_mul_f32_e32 v2, v21, v75
	v_mul_f32_e32 v9, v38, v74
	ds_write2_b32 v98, v8, v2 offset0:204 offset1:236
	v_mul_f32_e32 v2, v22, v74
	v_mul_f32_e32 v10, v39, v73
	ds_write2_b32 v82, v9, v2 offset0:32 offset1:64
	v_mul_f32_e32 v2, v23, v73
	v_mul_f32_e32 v11, v40, v71
	ds_write2_b32 v82, v10, v2 offset0:100 offset1:132
	v_mul_f32_e32 v2, v24, v71
	ds_write2_b32 v82, v11, v2 offset0:168 offset1:200
	v_mul_f32_e32 v2, v25, v69
	v_mul_f32_e32 v35, v42, v72
	ds_write2_b32 v83, v34, v2 offset0:108 offset1:140
	v_mul_f32_e32 v2, v26, v72
	v_mul_f32_e32 v36, v43, v70
	ds_write2_b32 v80, v35, v2 offset0:64 offset1:96
	v_mul_f32_e32 v2, v27, v70
	v_mul_f32_e32 v37, v44, v68
	ds_write2_b32 v80, v36, v2 offset0:132 offset1:164
	v_mul_f32_e32 v2, v28, v68
	v_mul_f32_e32 v38, v45, v67
	ds_write2_b32 v80, v37, v2 offset0:200 offset1:232
	v_mul_f32_e32 v2, v29, v67
	v_mul_f32_e32 v39, v46, v78
	ds_write2_b32 v81, v38, v2 offset0:12 offset1:44
	v_mul_f32_e32 v2, v30, v78
	v_mul_f32_e32 v40, v47, v63
	ds_write2_b32 v64, v39, v2 offset0:96 offset1:128
	v_mul_f32_e32 v2, v31, v63
	ds_write2_b32 v64, v40, v2 offset0:164 offset1:196
	v_mul_f32_e32 v2, v32, v62
	v_mul_f32_e32 v42, v49, v61
	ds_write2_b32 v65, v41, v2 offset0:104 offset1:136
	v_mul_f32_e32 v2, v33, v61
	ds_write2_b32 v66, v42, v2 offset0:44 offset1:76
	s_waitcnt lgkmcnt(0)
	ds_read_b128 v[6:9], v60
	ds_read_b128 v[18:21], v60 offset:16
	s_mov_b64 s[6:7], 0
	s_waitcnt vmcnt(7)
	v_lshlrev_b32_e32 v10, 16, v148
	v_mul_f32_e32 v2, 0xbfb8aa3b, v10
	v_exp_f32_e32 v2, v2
	v_and_b32_e32 v11, 0xffff0000, v148
	s_waitcnt lgkmcnt(1)
	v_pk_mul_f32 v[6:7], v[6:7], v[10:11]
	v_lshlrev_b32_e32 v10, 16, v149
	v_add_f32_e32 v2, 1.0, v2
	v_rcp_f32_e32 v26, v2
	v_mul_f32_e32 v2, 0xbfb8aa3b, v11
	v_exp_f32_e32 v2, v2
	v_and_b32_e32 v11, 0xffff0000, v149
	v_pk_mul_f32 v[8:9], v[8:9], v[10:11]
	v_add_f32_e32 v2, 1.0, v2
	v_rcp_f32_e32 v27, v2
	v_mul_f32_e32 v2, 0xbfb8aa3b, v10
	v_exp_f32_e32 v2, v2
	v_lshlrev_b32_e32 v10, 16, v150
	v_pk_mul_f32 v[6:7], v[6:7], v[26:27]
	v_add_f32_e32 v2, 1.0, v2
	v_rcp_f32_e32 v22, v2
	v_mul_f32_e32 v2, 0xbfb8aa3b, v11
	v_exp_f32_e32 v2, v2
	v_and_b32_e32 v11, 0xffff0000, v150
	s_waitcnt lgkmcnt(0)
	v_pk_mul_f32 v[18:19], v[18:19], v[10:11]
	v_cvt_pk_bf16_f32 v6, v6, v7
	v_add_f32_e32 v2, 1.0, v2
	v_rcp_f32_e32 v23, v2
	v_mul_f32_e32 v2, 0xbfb8aa3b, v10
	v_exp_f32_e32 v2, v2
	v_pk_mul_f32 v[8:9], v[8:9], v[22:23]
	s_nop 0
	v_cvt_pk_bf16_f32 v7, v8, v9
	v_add_f32_e32 v2, 1.0, v2
	v_rcp_f32_e32 v22, v2
	v_mul_f32_e32 v2, 0xbfb8aa3b, v11
	v_exp_f32_e32 v2, v2
	s_nop 0
	v_add_f32_e32 v2, 1.0, v2
	v_rcp_f32_e32 v23, v2
	s_nop 0
	v_pk_mul_f32 v[10:11], v[18:19], v[22:23]
	v_lshlrev_b32_e32 v18, 16, v151
	v_mul_f32_e32 v2, 0xbfb8aa3b, v18
	v_exp_f32_e32 v2, v2
	v_and_b32_e32 v19, 0xffff0000, v151
	v_pk_mul_f32 v[20:21], v[20:21], v[18:19]
	v_cvt_pk_bf16_f32 v8, v10, v11
	v_add_f32_e32 v2, 1.0, v2
	v_rcp_f32_e32 v22, v2
	v_mul_f32_e32 v2, 0xbfb8aa3b, v19
	v_exp_f32_e32 v2, v2
	s_nop 0
	v_add_f32_e32 v2, 1.0, v2
	v_rcp_f32_e32 v23, v2
	s_nop 0
	v_pk_mul_f32 v[18:19], v[20:21], v[22:23]
	s_nop 0
	v_cvt_pk_bf16_f32 v9, v18, v19
	global_store_dwordx4 v[52:53], v[6:9], off offset:128
	ds_read_b128 v[6:9], v60 offset:2176
	ds_read_b128 v[18:21], v60 offset:2192
	s_waitcnt vmcnt(7)
	v_lshlrev_b32_e32 v10, 16, v152
	v_mul_f32_e32 v2, 0xbfb8aa3b, v10
	v_exp_f32_e32 v2, v2
	v_and_b32_e32 v11, 0xffff0000, v152
	s_waitcnt lgkmcnt(1)
	v_pk_mul_f32 v[6:7], v[6:7], v[10:11]
	v_lshlrev_b32_e32 v10, 16, v153
	v_add_f32_e32 v2, 1.0, v2
	v_rcp_f32_e32 v26, v2
	v_mul_f32_e32 v2, 0xbfb8aa3b, v11
	v_exp_f32_e32 v2, v2
	v_and_b32_e32 v11, 0xffff0000, v153
	v_pk_mul_f32 v[8:9], v[8:9], v[10:11]
	v_add_f32_e32 v2, 1.0, v2
	v_rcp_f32_e32 v27, v2
	v_mul_f32_e32 v2, 0xbfb8aa3b, v10
	v_exp_f32_e32 v2, v2
	v_lshlrev_b32_e32 v10, 16, v154
	v_pk_mul_f32 v[6:7], v[6:7], v[26:27]
	v_add_f32_e32 v2, 1.0, v2
	v_rcp_f32_e32 v22, v2
	v_mul_f32_e32 v2, 0xbfb8aa3b, v11
	v_exp_f32_e32 v2, v2
	v_and_b32_e32 v11, 0xffff0000, v154
	s_waitcnt lgkmcnt(0)
	v_pk_mul_f32 v[18:19], v[18:19], v[10:11]
	v_cvt_pk_bf16_f32 v6, v6, v7
	v_add_f32_e32 v2, 1.0, v2
	v_rcp_f32_e32 v23, v2
	v_mul_f32_e32 v2, 0xbfb8aa3b, v10
	v_exp_f32_e32 v2, v2
	v_pk_mul_f32 v[8:9], v[8:9], v[22:23]
	s_nop 0
	v_cvt_pk_bf16_f32 v7, v8, v9
	v_add_f32_e32 v2, 1.0, v2
	v_rcp_f32_e32 v22, v2
	v_mul_f32_e32 v2, 0xbfb8aa3b, v11
	v_exp_f32_e32 v2, v2
	s_nop 0
	v_add_f32_e32 v2, 1.0, v2
	v_rcp_f32_e32 v23, v2
	s_nop 0
	v_pk_mul_f32 v[10:11], v[18:19], v[22:23]
	v_lshlrev_b32_e32 v18, 16, v155
	v_mul_f32_e32 v2, 0xbfb8aa3b, v18
	v_exp_f32_e32 v2, v2
	v_and_b32_e32 v19, 0xffff0000, v155
	v_pk_mul_f32 v[20:21], v[20:21], v[18:19]
	v_cvt_pk_bf16_f32 v8, v10, v11
	v_add_f32_e32 v2, 1.0, v2
	v_rcp_f32_e32 v22, v2
	v_mul_f32_e32 v2, 0xbfb8aa3b, v19
	v_exp_f32_e32 v2, v2
	s_nop 0
	v_add_f32_e32 v2, 1.0, v2
	v_rcp_f32_e32 v23, v2
	s_nop 0
	v_pk_mul_f32 v[18:19], v[20:21], v[22:23]
	s_nop 0
	v_cvt_pk_bf16_f32 v9, v18, v19
	global_store_dwordx4 v[16:17], v[6:9], off offset:128
	ds_read_b128 v[6:9], v60 offset:4352
	ds_read_b128 v[16:19], v60 offset:4368
	s_waitcnt vmcnt(7)
	v_lshlrev_b32_e32 v10, 16, v156
	v_mul_f32_e32 v2, 0xbfb8aa3b, v10
	v_exp_f32_e32 v2, v2
	v_and_b32_e32 v11, 0xffff0000, v156
	s_waitcnt lgkmcnt(1)
	v_pk_mul_f32 v[6:7], v[6:7], v[10:11]
	v_lshlrev_b32_e32 v10, 16, v157
	v_add_f32_e32 v2, 1.0, v2
	v_rcp_f32_e32 v24, v2
	v_mul_f32_e32 v2, 0xbfb8aa3b, v11
	v_exp_f32_e32 v2, v2
	v_and_b32_e32 v11, 0xffff0000, v157
	v_pk_mul_f32 v[8:9], v[8:9], v[10:11]
	v_add_f32_e32 v2, 1.0, v2
	v_rcp_f32_e32 v25, v2
	v_mul_f32_e32 v2, 0xbfb8aa3b, v10
	v_exp_f32_e32 v2, v2
	v_lshlrev_b32_e32 v10, 16, v158
	v_pk_mul_f32 v[6:7], v[6:7], v[24:25]
	v_add_f32_e32 v2, 1.0, v2
	v_rcp_f32_e32 v20, v2
	v_mul_f32_e32 v2, 0xbfb8aa3b, v11
	v_exp_f32_e32 v2, v2
	v_and_b32_e32 v11, 0xffff0000, v158
	s_waitcnt lgkmcnt(0)
	v_pk_mul_f32 v[16:17], v[16:17], v[10:11]
	v_cvt_pk_bf16_f32 v6, v6, v7
	v_add_f32_e32 v2, 1.0, v2
	v_rcp_f32_e32 v21, v2
	v_mul_f32_e32 v2, 0xbfb8aa3b, v10
	v_exp_f32_e32 v2, v2
	v_pk_mul_f32 v[8:9], v[8:9], v[20:21]
	s_nop 0
	v_cvt_pk_bf16_f32 v7, v8, v9
	v_add_f32_e32 v2, 1.0, v2
	v_rcp_f32_e32 v20, v2
	v_mul_f32_e32 v2, 0xbfb8aa3b, v11
	v_exp_f32_e32 v2, v2
	s_nop 0
	v_add_f32_e32 v2, 1.0, v2
	v_rcp_f32_e32 v21, v2
	s_nop 0
	v_pk_mul_f32 v[10:11], v[16:17], v[20:21]
	v_lshlrev_b32_e32 v16, 16, v159
	v_mul_f32_e32 v2, 0xbfb8aa3b, v16
	v_exp_f32_e32 v2, v2
	v_and_b32_e32 v17, 0xffff0000, v159
	v_pk_mul_f32 v[18:19], v[18:19], v[16:17]
	v_cvt_pk_bf16_f32 v8, v10, v11
	v_add_f32_e32 v2, 1.0, v2
	v_rcp_f32_e32 v20, v2
	v_mul_f32_e32 v2, 0xbfb8aa3b, v17
	v_exp_f32_e32 v2, v2
	s_nop 0
	v_add_f32_e32 v2, 1.0, v2
	v_rcp_f32_e32 v21, v2
	s_nop 0
	v_pk_mul_f32 v[16:17], v[18:19], v[20:21]
	s_nop 0
	v_cvt_pk_bf16_f32 v9, v16, v17
	global_store_dwordx4 v[12:13], v[6:9], off offset:128
	ds_read_b128 v[6:9], v60 offset:6528
	ds_read_b128 v[10:13], v60 offset:6544
	s_waitcnt vmcnt(7)
	v_lshlrev_b32_e32 v18, 16, v160
	v_mul_f32_e32 v2, 0xbfb8aa3b, v18
	v_exp_f32_e32 v2, v2
	v_and_b32_e32 v19, 0xffff0000, v160
	v_lshlrev_b32_e32 v14, 16, v161
	v_and_b32_e32 v15, 0xffff0000, v161
	v_add_f32_e32 v2, 1.0, v2
	v_rcp_f32_e32 v20, v2
	v_mul_f32_e32 v2, 0xbfb8aa3b, v19
	v_exp_f32_e32 v2, v2
	s_waitcnt lgkmcnt(1)
	v_pk_mul_f32 v[6:7], v[6:7], v[18:19]
	v_pk_mul_f32 v[8:9], v[8:9], v[14:15]
	v_add_f32_e32 v2, 1.0, v2
	v_rcp_f32_e32 v21, v2
	v_mul_f32_e32 v2, 0xbfb8aa3b, v14
	v_exp_f32_e32 v2, v2
	v_lshlrev_b32_e32 v14, 16, v162
	v_pk_mul_f32 v[6:7], v[6:7], v[20:21]
	v_add_f32_e32 v2, 1.0, v2
	v_rcp_f32_e32 v18, v2
	v_mul_f32_e32 v2, 0xbfb8aa3b, v15
	v_exp_f32_e32 v2, v2
	v_and_b32_e32 v15, 0xffff0000, v162
	s_waitcnt lgkmcnt(0)
	v_pk_mul_f32 v[10:11], v[10:11], v[14:15]
	v_cvt_pk_bf16_f32 v6, v6, v7
	v_add_f32_e32 v2, 1.0, v2
	v_rcp_f32_e32 v19, v2
	v_mul_f32_e32 v2, 0xbfb8aa3b, v14
	v_exp_f32_e32 v2, v2
	v_lshlrev_b32_e32 v14, 16, v163
	v_pk_mul_f32 v[8:9], v[8:9], v[18:19]
	v_add_f32_e32 v2, 1.0, v2
	v_rcp_f32_e32 v18, v2
	v_mul_f32_e32 v2, 0xbfb8aa3b, v15
	v_exp_f32_e32 v2, v2
	v_and_b32_e32 v15, 0xffff0000, v163
	v_pk_mul_f32 v[12:13], v[12:13], v[14:15]
	v_cvt_pk_bf16_f32 v7, v8, v9
	v_add_f32_e32 v2, 1.0, v2
	v_rcp_f32_e32 v19, v2
	v_mul_f32_e32 v2, 0xbfb8aa3b, v14
	v_exp_f32_e32 v2, v2
	v_pk_mul_f32 v[10:11], v[10:11], v[18:19]
	s_nop 0
	v_cvt_pk_bf16_f32 v8, v10, v11
	v_add_f32_e32 v2, 1.0, v2
	v_rcp_f32_e32 v16, v2
	v_mul_f32_e32 v2, 0xbfb8aa3b, v15
	v_exp_f32_e32 v2, v2
	s_nop 0
	v_add_f32_e32 v2, 1.0, v2
	v_rcp_f32_e32 v17, v2
	s_nop 0
	v_pk_mul_f32 v[12:13], v[12:13], v[16:17]
	s_nop 0
	v_cvt_pk_bf16_f32 v9, v12, v13
	global_store_dwordx4 v[4:5], v[6:9], off offset:128
	s_waitcnt lgkmcnt(0)
	s_barrier

.LBB0_3456:
	s_add_u32 s8, s6, 0xfff80080
	s_addc_u32 s9, s7, -1
	s_add_i32 s43, 0, 0x10000
	s_cmp_eq_u32 s42, 28
	s_cselect_b32 s11, s12, s9
	s_cselect_b32 s10, s13, s8
	v_add_u32_e32 v2, s43, v194
	s_cselect_b32 s9, s27, s37
	s_cselect_b32 s8, s29, s36
	s_add_i32 s48, 0, 0x14000
	ds_read_b128 v[30:33], v2
	ds_read_b128 v[34:37], v2 offset:1024
	ds_read_b128 v[46:49], v2 offset:2048
	ds_read_b128 v[50:53], v2 offset:3072
	v_add_u32_e32 v2, s48, v194
	ds_read_b128 v[162:165], v2
	ds_read_b128 v[166:169], v2 offset:1024
	ds_read_b128 v[170:173], v2 offset:2048
	ds_read_b128 v[174:177], v2 offset:3072
	v_lshl_add_u64 v[4:5], s[6:7], 0, v[158:159]
	s_add_i32 m0, s55, 0xc000
	ds_read_b128 v[178:181], v195
	ds_read_b128 v[182:185], v195 offset:1024
	ds_read_b128 v[186:189], v195 offset:2048
	ds_read_b128 v[196:199], v195 offset:3072
	ds_read_b128 v[204:207], v195 offset:4096
	ds_read_b128 v[208:211], v195 offset:5120
	ds_read_b128 v[212:215], v195 offset:6144
	ds_read_b128 v[226:229], v195 offset:7168
	global_load_lds_dwordx4 v[4:5], off
	v_lshl_add_u64 v[4:5], s[6:7], 0, v[160:161]
	s_add_i32 m0, s55, 0xe000
	s_nop 0
	global_load_lds_dwordx4 v[4:5], off
	s_waitcnt vmcnt(8)
	s_waitcnt lgkmcnt(0)
	s_barrier
	v_mfma_i32_16x16x64_i8 v[146:149], v[30:33], v[178:181], v[146:149]
	v_mfma_i32_16x16x64_i8 v[142:145], v[46:49], v[178:181], v[142:145]
	v_mfma_i32_16x16x64_i8 v[130:133], v[30:33], v[186:189], v[130:133]
	v_mfma_i32_16x16x64_i8 v[126:129], v[46:49], v[186:189], v[126:129]
	v_mfma_i32_16x16x64_i8 v[114:117], v[30:33], v[204:207], v[114:117]
	v_mfma_i32_16x16x64_i8 v[110:113], v[46:49], v[204:207], v[110:113]
	v_mfma_i32_16x16x64_i8 v[98:101], v[30:33], v[212:215], v[98:101]
	v_mfma_i32_16x16x64_i8 v[94:97], v[46:49], v[212:215], v[94:97]
	v_mfma_i32_16x16x64_i8 v[146:149], v[34:37], v[182:185], v[146:149]
	v_mfma_i32_16x16x64_i8 v[142:145], v[50:53], v[182:185], v[142:145]
	v_mfma_i32_16x16x64_i8 v[130:133], v[34:37], v[196:199], v[130:133]
	v_mfma_i32_16x16x64_i8 v[126:129], v[50:53], v[196:199], v[126:129]
	v_mfma_i32_16x16x64_i8 v[114:117], v[34:37], v[208:211], v[114:117]
	v_mfma_i32_16x16x64_i8 v[110:113], v[50:53], v[208:211], v[110:113]
	v_mfma_i32_16x16x64_i8 v[98:101], v[34:37], v[226:229], v[98:101]
	v_mfma_i32_16x16x64_i8 v[94:97], v[50:53], v[226:229], v[94:97]
	v_mfma_i32_16x16x64_i8 v[138:141], v[162:165], v[178:181], v[138:141]
	v_mfma_i32_16x16x64_i8 v[134:137], v[170:173], v[178:181], v[134:137]
	v_mfma_i32_16x16x64_i8 v[122:125], v[162:165], v[186:189], v[122:125]
	v_mfma_i32_16x16x64_i8 v[118:121], v[170:173], v[186:189], v[118:121]
	v_mfma_i32_16x16x64_i8 v[106:109], v[162:165], v[204:207], v[106:109]
	v_mfma_i32_16x16x64_i8 v[102:105], v[170:173], v[204:207], v[102:105]
	v_mfma_i32_16x16x64_i8 v[90:93], v[162:165], v[212:215], v[90:93]
	v_mfma_i32_16x16x64_i8 v[86:89], v[170:173], v[212:215], v[86:89]
	v_mfma_i32_16x16x64_i8 v[138:141], v[166:169], v[182:185], v[138:141]
	v_mfma_i32_16x16x64_i8 v[134:137], v[174:177], v[182:185], v[134:137]
	v_mfma_i32_16x16x64_i8 v[122:125], v[166:169], v[196:199], v[122:125]
	v_mfma_i32_16x16x64_i8 v[118:121], v[174:177], v[196:199], v[118:121]
	v_mfma_i32_16x16x64_i8 v[106:109], v[166:169], v[208:211], v[106:109]
	v_mfma_i32_16x16x64_i8 v[102:105], v[174:177], v[208:211], v[102:105]
	v_mfma_i32_16x16x64_i8 v[90:93], v[166:169], v[226:229], v[90:93]
	v_mfma_i32_16x16x64_i8 v[86:89], v[174:177], v[226:229], v[86:89]
	s_barrier
	s_add_i32 s43, s43, s54
	v_lshl_add_u64 v[190:191], s[8:9], 0, v[154:155]
	s_mov_b32 m0, s43
	ds_read_b128 v[178:181], v195 offset:16384
	ds_read_b128 v[182:185], v195 offset:17408
	ds_read_b128 v[186:189], v195 offset:18432
	ds_read_b128 v[196:199], v195 offset:19456
	ds_read_b128 v[204:207], v195 offset:20480
	ds_read_b128 v[208:211], v195 offset:21504
	ds_read_b128 v[212:215], v195 offset:22528
	ds_read_b128 v[226:229], v195 offset:23552
	global_load_lds_dwordx4 v[190:191], off
	s_add_i32 m0, s43, 0x2000
	s_add_u32 s44, s8, 0x80000
	v_lshl_add_u64 v[230:231], s[8:9], 0, v[150:151]
	s_addc_u32 s45, s9, 0
	s_add_i32 s43, s48, s54
	global_load_lds_dwordx4 v[230:231], off
	v_lshl_add_u64 v[4:5], s[44:45], 0, v[154:155]
	s_mov_b32 m0, s43
	v_lshl_add_u64 v[232:233], s[10:11], 0, v[156:157]
	global_load_lds_dwordx4 v[4:5], off
	v_lshl_add_u64 v[4:5], s[44:45], 0, v[150:151]
	s_add_i32 m0, s43, 0x2000
	v_lshl_add_u64 v[234:235], s[10:11], 0, v[152:153]
	global_load_lds_dwordx4 v[4:5], off
	s_mov_b32 m0, s55
	s_nop 0
	global_load_lds_dwordx4 v[232:233], off
	s_mov_b32 m0, s56
	s_nop 0
	global_load_lds_dwordx4 v[234:235], off
	s_waitcnt vmcnt(8)
	s_waitcnt lgkmcnt(0)
	s_barrier
	v_mfma_i32_16x16x64_i8 v[82:85], v[30:33], v[178:181], v[82:85]
	v_mfma_i32_16x16x64_i8 v[78:81], v[46:49], v[178:181], v[78:81]
	v_mfma_i32_16x16x64_i8 v[66:69], v[30:33], v[186:189], v[66:69]
	v_mfma_i32_16x16x64_i8 v[62:65], v[46:49], v[186:189], v[62:65]
	v_mfma_i32_16x16x64_i8 v[42:45], v[30:33], v[204:207], v[42:45]
	v_mfma_i32_16x16x64_i8 v[38:41], v[46:49], v[204:207], v[38:41]
	v_mfma_i32_16x16x64_i8 v[18:21], v[30:33], v[212:215], v[18:21]
	v_mfma_i32_16x16x64_i8 v[14:17], v[46:49], v[212:215], v[14:17]
	v_mfma_i32_16x16x64_i8 v[82:85], v[34:37], v[182:185], v[82:85]
	v_mfma_i32_16x16x64_i8 v[78:81], v[50:53], v[182:185], v[78:81]
	v_mfma_i32_16x16x64_i8 v[66:69], v[34:37], v[196:199], v[66:69]
	v_mfma_i32_16x16x64_i8 v[62:65], v[50:53], v[196:199], v[62:65]
	v_mfma_i32_16x16x64_i8 v[42:45], v[34:37], v[208:211], v[42:45]
	v_mfma_i32_16x16x64_i8 v[38:41], v[50:53], v[208:211], v[38:41]
	v_mfma_i32_16x16x64_i8 v[18:21], v[34:37], v[226:229], v[18:21]
	v_mfma_i32_16x16x64_i8 v[14:17], v[50:53], v[226:229], v[14:17]
	v_mfma_i32_16x16x64_i8 v[26:29], v[162:165], v[204:207], v[26:29]
	v_mfma_i32_16x16x64_i8 v[22:25], v[170:173], v[204:207], v[22:25]
	v_mfma_i32_16x16x64_i8 v[10:13], v[162:165], v[212:215], v[10:13]
	v_mfma_i32_16x16x64_i8 v[4:7], v[170:173], v[212:215], v[6:9]
	v_mfma_i32_16x16x64_i8 v[30:33], v[162:165], v[178:181], v[74:77]
	v_mfma_i32_16x16x64_i8 v[34:37], v[170:173], v[178:181], v[70:73]
	v_mfma_i32_16x16x64_i8 v[46:49], v[162:165], v[186:189], v[58:61]
	v_mfma_i32_16x16x64_i8 v[50:53], v[170:173], v[186:189], v[54:57]
	v_mfma_i32_16x16x64_i8 v[26:29], v[166:169], v[208:211], v[26:29]
	v_mfma_i32_16x16x64_i8 v[22:25], v[174:177], v[208:211], v[22:25]
	v_mfma_i32_16x16x64_i8 v[10:13], v[166:169], v[226:229], v[10:13]
	v_mfma_i32_16x16x64_i8 v[4:7], v[174:177], v[226:229], v[4:7]
	v_mfma_i32_16x16x64_i8 v[30:33], v[166:169], v[182:185], v[30:33]
	v_mfma_i32_16x16x64_i8 v[34:37], v[174:177], v[182:185], v[34:37]
	v_mfma_i32_16x16x64_i8 v[46:49], v[166:169], v[196:199], v[46:49]
	v_mfma_i32_16x16x64_i8 v[50:53], v[174:177], v[196:199], v[50:53]
	s_barrier
	s_add_i32 s43, 0, 0x18000
	v_add_u32_e32 v2, s43, v194
	s_add_i32 s44, 0, 0x1c000
	ds_read_b128 v[54:57], v2
	ds_read_b128 v[58:61], v2 offset:1024
	ds_read_b128 v[70:73], v2 offset:2048
	ds_read_b128 v[74:77], v2 offset:3072
	v_add_u32_e32 v2, s44, v194
	ds_read_b128 v[162:165], v2
	ds_read_b128 v[166:169], v2 offset:1024
	ds_read_b128 v[170:173], v2 offset:2048
	ds_read_b128 v[174:177], v2 offset:3072
	s_add_u32 s10, s10, 0x80000
	s_addc_u32 s11, s11, 0
	s_mov_b32 m0, s57
	v_lshl_add_u64 v[8:9], s[10:11], 0, v[156:157]
	ds_read_b128 v[178:181], v195 offset:32768
	ds_read_b128 v[182:185], v195 offset:33792
	ds_read_b128 v[186:189], v195 offset:34816
	ds_read_b128 v[196:199], v195 offset:35840
	ds_read_b128 v[204:207], v195 offset:36864
	ds_read_b128 v[208:211], v195 offset:37888
	ds_read_b128 v[212:215], v195 offset:38912
	ds_read_b128 v[226:229], v195 offset:39936
	global_load_lds_dwordx4 v[8:9], off
	v_lshl_add_u64 v[8:9], s[10:11], 0, v[152:153]
	s_mov_b32 m0, s59
	s_nop 0
	global_load_lds_dwordx4 v[8:9], off
	s_waitcnt vmcnt(8)
	s_waitcnt lgkmcnt(0)
	s_barrier
	v_mfma_i32_16x16x64_i8 v[146:149], v[54:57], v[178:181], v[146:149]
	v_mfma_i32_16x16x64_i8 v[142:145], v[70:73], v[178:181], v[142:145]
	v_mfma_i32_16x16x64_i8 v[130:133], v[54:57], v[186:189], v[130:133]
	v_mfma_i32_16x16x64_i8 v[126:129], v[70:73], v[186:189], v[126:129]
	v_mfma_i32_16x16x64_i8 v[114:117], v[54:57], v[204:207], v[114:117]
	v_mfma_i32_16x16x64_i8 v[110:113], v[70:73], v[204:207], v[110:113]
	v_mfma_i32_16x16x64_i8 v[98:101], v[54:57], v[212:215], v[98:101]
	v_mfma_i32_16x16x64_i8 v[94:97], v[70:73], v[212:215], v[94:97]
	v_mfma_i32_16x16x64_i8 v[146:149], v[58:61], v[182:185], v[146:149]
	v_mfma_i32_16x16x64_i8 v[142:145], v[74:77], v[182:185], v[142:145]
	v_mfma_i32_16x16x64_i8 v[130:133], v[58:61], v[196:199], v[130:133]
	v_mfma_i32_16x16x64_i8 v[126:129], v[74:77], v[196:199], v[126:129]
	v_mfma_i32_16x16x64_i8 v[114:117], v[58:61], v[208:211], v[114:117]
	v_mfma_i32_16x16x64_i8 v[110:113], v[74:77], v[208:211], v[110:113]
	v_mfma_i32_16x16x64_i8 v[98:101], v[58:61], v[226:229], v[98:101]
	v_mfma_i32_16x16x64_i8 v[94:97], v[74:77], v[226:229], v[94:97]
	v_mfma_i32_16x16x64_i8 v[138:141], v[162:165], v[178:181], v[138:141]
	v_mfma_i32_16x16x64_i8 v[134:137], v[170:173], v[178:181], v[134:137]
	v_mfma_i32_16x16x64_i8 v[122:125], v[162:165], v[186:189], v[122:125]
	v_mfma_i32_16x16x64_i8 v[118:121], v[170:173], v[186:189], v[118:121]
	v_mfma_i32_16x16x64_i8 v[106:109], v[162:165], v[204:207], v[106:109]
	v_mfma_i32_16x16x64_i8 v[102:105], v[170:173], v[204:207], v[102:105]
	v_mfma_i32_16x16x64_i8 v[90:93], v[162:165], v[212:215], v[90:93]
	v_mfma_i32_16x16x64_i8 v[86:89], v[170:173], v[212:215], v[86:89]
	v_mfma_i32_16x16x64_i8 v[138:141], v[166:169], v[182:185], v[138:141]
	v_mfma_i32_16x16x64_i8 v[134:137], v[174:177], v[182:185], v[134:137]
	v_mfma_i32_16x16x64_i8 v[122:125], v[166:169], v[196:199], v[122:125]
	v_mfma_i32_16x16x64_i8 v[118:121], v[174:177], v[196:199], v[118:121]
	v_mfma_i32_16x16x64_i8 v[106:109], v[166:169], v[208:211], v[106:109]
	v_mfma_i32_16x16x64_i8 v[102:105], v[174:177], v[208:211], v[102:105]
	v_mfma_i32_16x16x64_i8 v[90:93], v[166:169], v[226:229], v[90:93]
	v_mfma_i32_16x16x64_i8 v[86:89], v[174:177], v[226:229], v[86:89]
	s_barrier
	s_add_i32 s10, s43, s54
	v_lshl_add_u64 v[8:9], v[190:191], 0, s[94:95]
	s_mov_b32 m0, s10
	ds_read_b128 v[178:181], v195 offset:49152
	ds_read_b128 v[182:185], v195 offset:50176
	ds_read_b128 v[186:189], v195 offset:51200
	ds_read_b128 v[196:199], v195 offset:52224
	ds_read_b128 v[204:207], v195 offset:53248
	ds_read_b128 v[208:211], v195 offset:54272
	ds_read_b128 v[212:215], v195 offset:55296
	ds_read_b128 v[226:229], v195 offset:56320
	global_load_lds_dwordx4 v[8:9], off
	s_add_i32 m0, s10, 0x2000
	s_add_u32 s8, s8, 0x80080
	v_lshl_add_u64 v[8:9], v[230:231], 0, s[94:95]
	s_addc_u32 s9, s9, 0
	s_add_i32 s10, s44, s54
	global_load_lds_dwordx4 v[8:9], off
	v_lshl_add_u64 v[8:9], s[8:9], 0, v[154:155]
	s_mov_b32 m0, s10
	s_nop 0
	global_load_lds_dwordx4 v[8:9], off
	v_lshl_add_u64 v[8:9], s[8:9], 0, v[150:151]
	s_add_i32 m0, s10, 0x2000
	s_nop 0
	global_load_lds_dwordx4 v[8:9], off
	v_lshl_add_u64 v[8:9], v[232:233], 0, s[94:95]
	s_mov_b32 m0, s71
	s_nop 0
	global_load_lds_dwordx4 v[8:9], off
	v_lshl_add_u64 v[8:9], v[234:235], 0, s[94:95]
	s_mov_b32 m0, s74
	s_nop 0
	global_load_lds_dwordx4 v[8:9], off
	s_waitcnt vmcnt(8)
	s_waitcnt lgkmcnt(0)
	s_barrier
	v_mfma_i32_16x16x64_i8 v[82:85], v[54:57], v[178:181], v[82:85]
	v_mfma_i32_16x16x64_i8 v[78:81], v[70:73], v[178:181], v[78:81]
	v_mfma_i32_16x16x64_i8 v[66:69], v[54:57], v[186:189], v[66:69]
	v_mfma_i32_16x16x64_i8 v[62:65], v[70:73], v[186:189], v[62:65]
	v_mfma_i32_16x16x64_i8 v[42:45], v[54:57], v[204:207], v[42:45]
	v_mfma_i32_16x16x64_i8 v[38:41], v[70:73], v[204:207], v[38:41]
	v_mfma_i32_16x16x64_i8 v[18:21], v[54:57], v[212:215], v[18:21]
	v_mfma_i32_16x16x64_i8 v[14:17], v[70:73], v[212:215], v[14:17]
	v_mfma_i32_16x16x64_i8 v[82:85], v[58:61], v[182:185], v[82:85]
	v_mfma_i32_16x16x64_i8 v[78:81], v[74:77], v[182:185], v[78:81]
	v_mfma_i32_16x16x64_i8 v[66:69], v[58:61], v[196:199], v[66:69]
	v_mfma_i32_16x16x64_i8 v[62:65], v[74:77], v[196:199], v[62:65]
	v_mfma_i32_16x16x64_i8 v[42:45], v[58:61], v[208:211], v[42:45]
	v_mfma_i32_16x16x64_i8 v[38:41], v[74:77], v[208:211], v[38:41]
	v_mfma_i32_16x16x64_i8 v[18:21], v[58:61], v[226:229], v[18:21]
	v_mfma_i32_16x16x64_i8 v[14:17], v[74:77], v[226:229], v[14:17]
	v_mfma_i32_16x16x64_i8 v[30:33], v[162:165], v[178:181], v[30:33]
	v_mfma_i32_16x16x64_i8 v[74:77], v[166:169], v[182:185], v[30:33]
	v_mfma_i32_16x16x64_i8 v[30:33], v[170:173], v[178:181], v[34:37]
	v_mfma_i32_16x16x64_i8 v[70:73], v[174:177], v[182:185], v[30:33]
	v_mfma_i32_16x16x64_i8 v[30:33], v[162:165], v[186:189], v[46:49]
	v_mfma_i32_16x16x64_i8 v[58:61], v[166:169], v[196:199], v[30:33]
	v_mfma_i32_16x16x64_i8 v[30:33], v[170:173], v[186:189], v[50:53]
	v_mfma_i32_16x16x64_i8 v[26:29], v[162:165], v[204:207], v[26:29]
	v_mfma_i32_16x16x64_i8 v[22:25], v[170:173], v[204:207], v[22:25]
	v_mfma_i32_16x16x64_i8 v[8:11], v[162:165], v[212:215], v[10:13]
	v_mfma_i32_16x16x64_i8 v[4:7], v[170:173], v[212:215], v[4:7]
	v_mfma_i32_16x16x64_i8 v[54:57], v[174:177], v[196:199], v[30:33]
	v_mfma_i32_16x16x64_i8 v[26:29], v[166:169], v[208:211], v[26:29]
	v_mfma_i32_16x16x64_i8 v[22:25], v[174:177], v[208:211], v[22:25]
	v_mfma_i32_16x16x64_i8 v[10:13], v[166:169], v[226:229], v[8:11]
	v_mfma_i32_16x16x64_i8 v[6:9], v[174:177], v[226:229], v[4:7]
	s_barrier
	s_add_i32 s42, s42, 2
	s_add_u32 s6, s6, 0x100
	s_addc_u32 s7, s7, 0
	s_add_u32 s36, s36, 0x100
	s_addc_u32 s37, s37, 0
	s_cmp_gt_u32 s42, 29
	s_cbranch_scc0 .LBB0_3456
	s_and_b64 vcc, exec, s[20:21]
	s_cbranch_vccz .LBB0_3459
	s_barrier

.LBB0_3768:
	s_add_u32 s22, s18, s20
	s_addc_u32 s23, s19, s21
	s_add_u32 s22, s22, 0x100
	s_addc_u32 s23, s23, 0
	s_add_u32 s57, s54, s20
	s_addc_u32 s58, s55, s21
	s_cmpk_eq_i32 s20, 0x2f00
	s_cselect_b32 s25, s7, s23
	s_cselect_b32 s24, s6, s22
	s_cselect_b32 s23, s17, s58
	s_cselect_b32 s22, s16, s57
	s_add_i32 s57, 0, 0x10000
	v_add_u32_e32 v2, s57, v184
	s_add_i32 s62, 0, 0x14000
	ds_read_b128 v[134:137], v2
	ds_read_b128 v[138:141], v2 offset:1024
	ds_read_b128 v[142:145], v2 offset:2048
	ds_read_b128 v[146:149], v2 offset:3072
	v_add_u32_e32 v2, s62, v184
	ds_read_b128 v[150:153], v2
	ds_read_b128 v[154:157], v2 offset:1024
	ds_read_b128 v[158:161], v2 offset:2048
	ds_read_b128 v[162:165], v2 offset:3072
	v_lshl_add_u64 v[4:5], v[178:179], 0, s[20:21]
	s_add_i32 m0, s28, 0xc000
	ds_read_b128 v[186:189], v185
	ds_read_b128 v[190:193], v185 offset:1024
	ds_read_b128 v[194:197], v185 offset:2048
	ds_read_b128 v[204:207], v185 offset:3072
	ds_read_b128 v[208:211], v185 offset:4096
	ds_read_b128 v[212:215], v185 offset:5120
	ds_read_b128 v[226:229], v185 offset:6144
	ds_read_b128 v[230:233], v185 offset:7168
	global_load_lds_dwordx4 v[4:5], off
	v_lshl_add_u64 v[4:5], v[180:181], 0, s[20:21]
	s_add_i32 m0, s28, 0xe000
	s_nop 0
	global_load_lds_dwordx4 v[4:5], off
	s_waitcnt vmcnt(8)
	s_waitcnt lgkmcnt(0)
	s_barrier
	v_mfma_f32_16x16x32_bf16 v[130:133], v[134:137], v[186:189], v[130:133]
	v_mfma_f32_16x16x32_bf16 v[126:129], v[142:145], v[186:189], v[126:129]
	v_mfma_f32_16x16x32_bf16 v[114:117], v[134:137], v[194:197], v[114:117]
	v_mfma_f32_16x16x32_bf16 v[110:113], v[142:145], v[194:197], v[110:113]
	v_mfma_f32_16x16x32_bf16 v[98:101], v[134:137], v[208:211], v[98:101]
	v_mfma_f32_16x16x32_bf16 v[94:97], v[142:145], v[208:211], v[94:97]
	v_mfma_f32_16x16x32_bf16 v[82:85], v[134:137], v[226:229], v[82:85]
	v_mfma_f32_16x16x32_bf16 v[78:81], v[142:145], v[226:229], v[78:81]
	v_mfma_f32_16x16x32_bf16 v[130:133], v[138:141], v[190:193], v[130:133]
	v_mfma_f32_16x16x32_bf16 v[126:129], v[146:149], v[190:193], v[126:129]
	v_mfma_f32_16x16x32_bf16 v[114:117], v[138:141], v[204:207], v[114:117]
	v_mfma_f32_16x16x32_bf16 v[110:113], v[146:149], v[204:207], v[110:113]
	v_mfma_f32_16x16x32_bf16 v[98:101], v[138:141], v[212:215], v[98:101]
	v_mfma_f32_16x16x32_bf16 v[94:97], v[146:149], v[212:215], v[94:97]
	v_mfma_f32_16x16x32_bf16 v[82:85], v[138:141], v[230:233], v[82:85]
	v_mfma_f32_16x16x32_bf16 v[78:81], v[146:149], v[230:233], v[78:81]
	v_mfma_f32_16x16x32_bf16 v[122:125], v[150:153], v[186:189], v[122:125]
	v_mfma_f32_16x16x32_bf16 v[118:121], v[158:161], v[186:189], v[118:121]
	v_mfma_f32_16x16x32_bf16 v[106:109], v[150:153], v[194:197], v[106:109]
	v_mfma_f32_16x16x32_bf16 v[102:105], v[158:161], v[194:197], v[102:105]
	v_mfma_f32_16x16x32_bf16 v[90:93], v[150:153], v[208:211], v[90:93]
	v_mfma_f32_16x16x32_bf16 v[86:89], v[158:161], v[208:211], v[86:89]
	v_mfma_f32_16x16x32_bf16 v[74:77], v[150:153], v[226:229], v[74:77]
	v_mfma_f32_16x16x32_bf16 v[70:73], v[158:161], v[226:229], v[70:73]
	v_mfma_f32_16x16x32_bf16 v[122:125], v[154:157], v[190:193], v[122:125]
	v_mfma_f32_16x16x32_bf16 v[118:121], v[162:165], v[190:193], v[118:121]
	v_mfma_f32_16x16x32_bf16 v[106:109], v[154:157], v[204:207], v[106:109]
	v_mfma_f32_16x16x32_bf16 v[102:105], v[162:165], v[204:207], v[102:105]
	v_mfma_f32_16x16x32_bf16 v[90:93], v[154:157], v[212:215], v[90:93]
	v_mfma_f32_16x16x32_bf16 v[86:89], v[162:165], v[212:215], v[86:89]
	v_mfma_f32_16x16x32_bf16 v[74:77], v[154:157], v[230:233], v[74:77]
	v_mfma_f32_16x16x32_bf16 v[70:73], v[162:165], v[230:233], v[70:73]
	s_barrier
	s_add_i32 s57, s57, s27
	v_lshl_add_u64 v[198:199], s[22:23], 0, v[170:171]
	s_mov_b32 m0, s57
	ds_read_b128 v[186:189], v185 offset:16384
	ds_read_b128 v[190:193], v185 offset:17408
	ds_read_b128 v[194:197], v185 offset:18432
	ds_read_b128 v[204:207], v185 offset:19456
	ds_read_b128 v[208:211], v185 offset:20480
	ds_read_b128 v[212:215], v185 offset:21504
	ds_read_b128 v[226:229], v185 offset:22528
	ds_read_b128 v[230:233], v185 offset:23552
	global_load_lds_dwordx4 v[198:199], off
	s_add_i32 m0, s57, 0x2000
	s_add_u32 s58, s22, 0x180000
	v_lshl_add_u64 v[234:235], s[22:23], 0, v[166:167]
	s_addc_u32 s59, s23, 0
	s_add_i32 s57, s62, s27
	global_load_lds_dwordx4 v[234:235], off
	v_lshl_add_u64 v[4:5], s[58:59], 0, v[170:171]
	s_mov_b32 m0, s57
	v_lshl_add_u64 v[236:237], s[24:25], 0, v[172:173]
	global_load_lds_dwordx4 v[4:5], off
	v_lshl_add_u64 v[4:5], s[58:59], 0, v[166:167]
	s_add_i32 m0, s57, 0x2000
	v_lshl_add_u64 v[238:239], s[24:25], 0, v[168:169]
	global_load_lds_dwordx4 v[4:5], off
	s_mov_b32 m0, s28
	s_nop 0
	global_load_lds_dwordx4 v[236:237], off
	s_mov_b32 m0, s29
	s_nop 0
	global_load_lds_dwordx4 v[238:239], off
	s_waitcnt vmcnt(8)
	s_waitcnt lgkmcnt(0)
	s_barrier
	v_mfma_f32_16x16x32_bf16 v[66:69], v[134:137], v[186:189], v[66:69]
	v_mfma_f32_16x16x32_bf16 v[62:65], v[142:145], v[186:189], v[62:65]
	v_mfma_f32_16x16x32_bf16 v[50:53], v[134:137], v[194:197], v[50:53]
	v_mfma_f32_16x16x32_bf16 v[46:49], v[142:145], v[194:197], v[46:49]
	v_mfma_f32_16x16x32_bf16 v[34:37], v[134:137], v[208:211], v[34:37]
	v_mfma_f32_16x16x32_bf16 v[30:33], v[142:145], v[208:211], v[30:33]
	v_mfma_f32_16x16x32_bf16 v[18:21], v[134:137], v[226:229], v[18:21]
	v_mfma_f32_16x16x32_bf16 v[14:17], v[142:145], v[226:229], v[14:17]
	v_mfma_f32_16x16x32_bf16 v[66:69], v[138:141], v[190:193], v[66:69]
	v_mfma_f32_16x16x32_bf16 v[62:65], v[146:149], v[190:193], v[62:65]
	v_mfma_f32_16x16x32_bf16 v[50:53], v[138:141], v[204:207], v[50:53]
	v_mfma_f32_16x16x32_bf16 v[46:49], v[146:149], v[204:207], v[46:49]
	v_mfma_f32_16x16x32_bf16 v[34:37], v[138:141], v[212:215], v[34:37]
	v_mfma_f32_16x16x32_bf16 v[30:33], v[146:149], v[212:215], v[30:33]
	v_mfma_f32_16x16x32_bf16 v[18:21], v[138:141], v[230:233], v[18:21]
	v_mfma_f32_16x16x32_bf16 v[14:17], v[146:149], v[230:233], v[14:17]
	v_mfma_f32_16x16x32_bf16 v[58:61], v[150:153], v[186:189], v[58:61]
	v_mfma_f32_16x16x32_bf16 v[54:57], v[158:161], v[186:189], v[54:57]
	v_mfma_f32_16x16x32_bf16 v[42:45], v[150:153], v[194:197], v[42:45]
	v_mfma_f32_16x16x32_bf16 v[38:41], v[158:161], v[194:197], v[38:41]
	v_mfma_f32_16x16x32_bf16 v[26:29], v[150:153], v[208:211], v[26:29]
	v_mfma_f32_16x16x32_bf16 v[22:25], v[158:161], v[208:211], v[22:25]
	v_mfma_f32_16x16x32_bf16 v[10:13], v[150:153], v[226:229], v[10:13]
	v_mfma_f32_16x16x32_bf16 v[4:7], v[158:161], v[226:229], v[6:9]
	v_mfma_f32_16x16x32_bf16 v[58:61], v[154:157], v[190:193], v[58:61]
	v_mfma_f32_16x16x32_bf16 v[54:57], v[162:165], v[190:193], v[54:57]
	v_mfma_f32_16x16x32_bf16 v[42:45], v[154:157], v[204:207], v[42:45]
	v_mfma_f32_16x16x32_bf16 v[38:41], v[162:165], v[204:207], v[38:41]
	v_mfma_f32_16x16x32_bf16 v[26:29], v[154:157], v[212:215], v[26:29]
	v_mfma_f32_16x16x32_bf16 v[22:25], v[162:165], v[212:215], v[22:25]
	v_mfma_f32_16x16x32_bf16 v[10:13], v[154:157], v[230:233], v[10:13]
	v_mfma_f32_16x16x32_bf16 v[4:7], v[162:165], v[230:233], v[4:7]
	s_barrier
	s_add_i32 s57, 0, 0x18000
	v_add_u32_e32 v2, s57, v184
	s_add_i32 s58, 0, 0x1c000
	ds_read_b128 v[134:137], v2
	ds_read_b128 v[138:141], v2 offset:1024
	ds_read_b128 v[142:145], v2 offset:2048
	ds_read_b128 v[146:149], v2 offset:3072
	v_add_u32_e32 v2, s58, v184
	ds_read_b128 v[150:153], v2
	ds_read_b128 v[154:157], v2 offset:1024
	ds_read_b128 v[158:161], v2 offset:2048
	ds_read_b128 v[162:165], v2 offset:3072
	s_add_u32 s24, s24, 0x180000
	s_addc_u32 s25, s25, 0
	s_mov_b32 m0, s30
	v_lshl_add_u64 v[8:9], s[24:25], 0, v[172:173]
	ds_read_b128 v[186:189], v185 offset:32768
	ds_read_b128 v[190:193], v185 offset:33792
	ds_read_b128 v[194:197], v185 offset:34816
	ds_read_b128 v[204:207], v185 offset:35840
	ds_read_b128 v[208:211], v185 offset:36864
	ds_read_b128 v[212:215], v185 offset:37888
	ds_read_b128 v[226:229], v185 offset:38912
	ds_read_b128 v[230:233], v185 offset:39936
	global_load_lds_dwordx4 v[8:9], off
	v_lshl_add_u64 v[8:9], s[24:25], 0, v[168:169]
	s_mov_b32 m0, s31
	s_nop 0
	global_load_lds_dwordx4 v[8:9], off
	s_waitcnt vmcnt(8)
	s_waitcnt lgkmcnt(0)
	s_barrier
	v_mfma_f32_16x16x32_bf16 v[130:133], v[134:137], v[186:189], v[130:133]
	v_mfma_f32_16x16x32_bf16 v[126:129], v[142:145], v[186:189], v[126:129]
	v_mfma_f32_16x16x32_bf16 v[114:117], v[134:137], v[194:197], v[114:117]
	v_mfma_f32_16x16x32_bf16 v[110:113], v[142:145], v[194:197], v[110:113]
	v_mfma_f32_16x16x32_bf16 v[98:101], v[134:137], v[208:211], v[98:101]
	v_mfma_f32_16x16x32_bf16 v[94:97], v[142:145], v[208:211], v[94:97]
	v_mfma_f32_16x16x32_bf16 v[82:85], v[134:137], v[226:229], v[82:85]
	v_mfma_f32_16x16x32_bf16 v[78:81], v[142:145], v[226:229], v[78:81]
	v_mfma_f32_16x16x32_bf16 v[130:133], v[138:141], v[190:193], v[130:133]
	v_mfma_f32_16x16x32_bf16 v[126:129], v[146:149], v[190:193], v[126:129]
	v_mfma_f32_16x16x32_bf16 v[114:117], v[138:141], v[204:207], v[114:117]
	v_mfma_f32_16x16x32_bf16 v[110:113], v[146:149], v[204:207], v[110:113]
	v_mfma_f32_16x16x32_bf16 v[98:101], v[138:141], v[212:215], v[98:101]
	v_mfma_f32_16x16x32_bf16 v[94:97], v[146:149], v[212:215], v[94:97]
	v_mfma_f32_16x16x32_bf16 v[82:85], v[138:141], v[230:233], v[82:85]
	v_mfma_f32_16x16x32_bf16 v[78:81], v[146:149], v[230:233], v[78:81]
	v_mfma_f32_16x16x32_bf16 v[122:125], v[150:153], v[186:189], v[122:125]
	v_mfma_f32_16x16x32_bf16 v[118:121], v[158:161], v[186:189], v[118:121]
	v_mfma_f32_16x16x32_bf16 v[106:109], v[150:153], v[194:197], v[106:109]
	v_mfma_f32_16x16x32_bf16 v[102:105], v[158:161], v[194:197], v[102:105]
	v_mfma_f32_16x16x32_bf16 v[90:93], v[150:153], v[208:211], v[90:93]
	v_mfma_f32_16x16x32_bf16 v[86:89], v[158:161], v[208:211], v[86:89]
	v_mfma_f32_16x16x32_bf16 v[74:77], v[150:153], v[226:229], v[74:77]
	v_mfma_f32_16x16x32_bf16 v[70:73], v[158:161], v[226:229], v[70:73]
	v_mfma_f32_16x16x32_bf16 v[122:125], v[154:157], v[190:193], v[122:125]
	v_mfma_f32_16x16x32_bf16 v[118:121], v[162:165], v[190:193], v[118:121]
	v_mfma_f32_16x16x32_bf16 v[106:109], v[154:157], v[204:207], v[106:109]
	v_mfma_f32_16x16x32_bf16 v[102:105], v[162:165], v[204:207], v[102:105]
	v_mfma_f32_16x16x32_bf16 v[90:93], v[154:157], v[212:215], v[90:93]
	v_mfma_f32_16x16x32_bf16 v[86:89], v[162:165], v[212:215], v[86:89]
	v_mfma_f32_16x16x32_bf16 v[74:77], v[154:157], v[230:233], v[74:77]
	v_mfma_f32_16x16x32_bf16 v[70:73], v[162:165], v[230:233], v[70:73]
	s_barrier
	s_add_i32 s24, s57, s27
	v_lshl_add_u64 v[8:9], v[198:199], 0, s[94:95]
	s_mov_b32 m0, s24
	ds_read_b128 v[186:189], v185 offset:49152
	ds_read_b128 v[190:193], v185 offset:50176
	ds_read_b128 v[194:197], v185 offset:51200
	ds_read_b128 v[204:207], v185 offset:52224
	ds_read_b128 v[208:211], v185 offset:53248
	ds_read_b128 v[212:215], v185 offset:54272
	ds_read_b128 v[226:229], v185 offset:55296
	ds_read_b128 v[230:233], v185 offset:56320
	global_load_lds_dwordx4 v[8:9], off
	s_add_i32 m0, s24, 0x2000
	s_add_u32 s22, s22, 0x180080
	v_lshl_add_u64 v[8:9], v[234:235], 0, s[94:95]
	s_addc_u32 s23, s23, 0
	s_add_i32 s24, s58, s27
	global_load_lds_dwordx4 v[8:9], off
	v_lshl_add_u64 v[8:9], s[22:23], 0, v[170:171]
	s_mov_b32 m0, s24
	s_nop 0
	global_load_lds_dwordx4 v[8:9], off
	v_lshl_add_u64 v[8:9], s[22:23], 0, v[166:167]
	s_add_i32 m0, s24, 0x2000
	s_nop 0
	global_load_lds_dwordx4 v[8:9], off
	v_lshl_add_u64 v[8:9], v[236:237], 0, s[94:95]
	s_mov_b32 m0, s34
	s_nop 0
	global_load_lds_dwordx4 v[8:9], off
	v_lshl_add_u64 v[8:9], v[238:239], 0, s[94:95]
	s_mov_b32 m0, s35
	s_nop 0
	global_load_lds_dwordx4 v[8:9], off
	s_waitcnt vmcnt(8)
	s_waitcnt lgkmcnt(0)
	s_barrier
	v_mfma_f32_16x16x32_bf16 v[66:69], v[134:137], v[186:189], v[66:69]
	v_mfma_f32_16x16x32_bf16 v[62:65], v[142:145], v[186:189], v[62:65]
	v_mfma_f32_16x16x32_bf16 v[50:53], v[134:137], v[194:197], v[50:53]
	v_mfma_f32_16x16x32_bf16 v[46:49], v[142:145], v[194:197], v[46:49]
	v_mfma_f32_16x16x32_bf16 v[34:37], v[134:137], v[208:211], v[34:37]
	v_mfma_f32_16x16x32_bf16 v[30:33], v[142:145], v[208:211], v[30:33]
	v_mfma_f32_16x16x32_bf16 v[18:21], v[134:137], v[226:229], v[18:21]
	v_mfma_f32_16x16x32_bf16 v[14:17], v[142:145], v[226:229], v[14:17]
	v_mfma_f32_16x16x32_bf16 v[66:69], v[138:141], v[190:193], v[66:69]
	v_mfma_f32_16x16x32_bf16 v[62:65], v[146:149], v[190:193], v[62:65]
	v_mfma_f32_16x16x32_bf16 v[50:53], v[138:141], v[204:207], v[50:53]
	v_mfma_f32_16x16x32_bf16 v[46:49], v[146:149], v[204:207], v[46:49]
	v_mfma_f32_16x16x32_bf16 v[34:37], v[138:141], v[212:215], v[34:37]
	v_mfma_f32_16x16x32_bf16 v[30:33], v[146:149], v[212:215], v[30:33]
	v_mfma_f32_16x16x32_bf16 v[18:21], v[138:141], v[230:233], v[18:21]
	v_mfma_f32_16x16x32_bf16 v[14:17], v[146:149], v[230:233], v[14:17]
	v_mfma_f32_16x16x32_bf16 v[58:61], v[150:153], v[186:189], v[58:61]
	v_mfma_f32_16x16x32_bf16 v[54:57], v[158:161], v[186:189], v[54:57]
	v_mfma_f32_16x16x32_bf16 v[42:45], v[150:153], v[194:197], v[42:45]
	v_mfma_f32_16x16x32_bf16 v[38:41], v[158:161], v[194:197], v[38:41]
	v_mfma_f32_16x16x32_bf16 v[26:29], v[150:153], v[208:211], v[26:29]
	v_mfma_f32_16x16x32_bf16 v[22:25], v[158:161], v[208:211], v[22:25]
	v_mfma_f32_16x16x32_bf16 v[8:11], v[150:153], v[226:229], v[10:13]
	v_mfma_f32_16x16x32_bf16 v[4:7], v[158:161], v[226:229], v[4:7]
	v_mfma_f32_16x16x32_bf16 v[58:61], v[154:157], v[190:193], v[58:61]
	v_mfma_f32_16x16x32_bf16 v[54:57], v[162:165], v[190:193], v[54:57]
	v_mfma_f32_16x16x32_bf16 v[42:45], v[154:157], v[204:207], v[42:45]
	v_mfma_f32_16x16x32_bf16 v[38:41], v[162:165], v[204:207], v[38:41]
	v_mfma_f32_16x16x32_bf16 v[26:29], v[154:157], v[212:215], v[26:29]
	v_mfma_f32_16x16x32_bf16 v[22:25], v[162:165], v[212:215], v[22:25]
	v_mfma_f32_16x16x32_bf16 v[10:13], v[154:157], v[230:233], v[8:11]
	v_mfma_f32_16x16x32_bf16 v[6:9], v[162:165], v[230:233], v[4:7]
	s_barrier
	s_add_i32 s22, s56, 2
	s_add_u32 s20, s20, 0x100
	s_addc_u32 s21, s21, 0
	s_cmpk_gt_u32 s56, 0x5d
	s_cbranch_scc1 .LBB0_3771
	s_mov_b32 s56, s22
	s_cmp_lt_i32 s56, 64
	s_cbranch_scc1 .LBB0_3761

.LBB0_3844:
	s_add_u32 s22, s20, 0x4000
	s_addc_u32 s23, s21, 0
	s_cmp_eq_u32 s48, 60
	s_cselect_b32 s26, s44, s22
	s_cselect_b32 s27, s13, s23
	s_cselect_b32 s24, s45, s46
	s_cselect_b32 s25, s11, s47
	s_add_u32 s22, s26, 0x8000
	s_addc_u32 s23, s27, 0
	s_add_i32 s49, 0, 0x10000
	s_add_i32 s51, 0, 0x14000
	v_add_u32_e32 v158, s49, v144
	v_add_u32_e32 v174, s51, v144
	ds_read_b128 v[146:149], v158
	ds_read_b128 v[150:153], v158 offset:1024
	ds_read_b128 v[154:157], v158 offset:2048
	ds_read_b128 v[158:161], v158 offset:3072
	ds_read_b128 v[162:165], v174
	ds_read_b128 v[166:169], v174 offset:1024
	ds_read_b128 v[170:173], v174 offset:2048
	ds_read_b128 v[174:177], v174 offset:3072
	v_lshl_add_u64 v[198:199], s[20:21], 0, v[138:139]
	s_add_i32 m0, s29, 0xc000
	ds_read_b128 v[178:181], v145
	ds_read_b128 v[182:185], v145 offset:1024
	ds_read_b128 v[186:189], v145 offset:2048
	ds_read_b128 v[190:193], v145 offset:3072
	ds_read_b128 v[194:197], v145 offset:4096
	ds_read_b128 v[204:207], v145 offset:5120
	ds_read_b128 v[208:211], v145 offset:6144
	ds_read_b128 v[212:215], v145 offset:7168
	global_load_lds_dwordx4 v[198:199], off
	v_lshl_add_u64 v[198:199], s[20:21], 0, v[140:141]
	s_add_i32 m0, s29, 0xe000
	s_nop 0
	global_load_lds_dwordx4 v[198:199], off
	s_waitcnt vmcnt(8)
	s_waitcnt lgkmcnt(0)
	s_barrier
	v_mfma_f32_16x16x32_bf16 v[128:131], v[146:149], v[178:181], v[128:131]
	v_mfma_f32_16x16x32_bf16 v[124:127], v[154:157], v[178:181], v[124:127]
	v_mfma_f32_16x16x32_bf16 v[120:123], v[146:149], v[186:189], v[120:123]
	v_mfma_f32_16x16x32_bf16 v[116:119], v[154:157], v[186:189], v[116:119]
	v_mfma_f32_16x16x32_bf16 v[104:107], v[146:149], v[194:197], v[104:107]
	v_mfma_f32_16x16x32_bf16 v[100:103], v[154:157], v[194:197], v[100:103]
	v_mfma_f32_16x16x32_bf16 v[88:91], v[146:149], v[208:211], v[88:91]
	v_mfma_f32_16x16x32_bf16 v[84:87], v[154:157], v[208:211], v[84:87]
	v_mfma_f32_16x16x32_bf16 v[128:131], v[150:153], v[182:185], v[128:131]
	v_mfma_f32_16x16x32_bf16 v[124:127], v[158:161], v[182:185], v[124:127]
	v_mfma_f32_16x16x32_bf16 v[120:123], v[150:153], v[190:193], v[120:123]
	v_mfma_f32_16x16x32_bf16 v[116:119], v[158:161], v[190:193], v[116:119]
	v_mfma_f32_16x16x32_bf16 v[104:107], v[150:153], v[204:207], v[104:107]
	v_mfma_f32_16x16x32_bf16 v[100:103], v[158:161], v[204:207], v[100:103]
	v_mfma_f32_16x16x32_bf16 v[88:91], v[150:153], v[212:215], v[88:91]
	v_mfma_f32_16x16x32_bf16 v[84:87], v[158:161], v[212:215], v[84:87]
	v_mfma_f32_16x16x32_bf16 v[112:115], v[162:165], v[178:181], v[112:115]
	v_mfma_f32_16x16x32_bf16 v[108:111], v[170:173], v[178:181], v[108:111]
	v_mfma_f32_16x16x32_bf16 v[96:99], v[162:165], v[186:189], v[96:99]
	v_mfma_f32_16x16x32_bf16 v[92:95], v[170:173], v[186:189], v[92:95]
	v_mfma_f32_16x16x32_bf16 v[80:83], v[162:165], v[194:197], v[80:83]
	v_mfma_f32_16x16x32_bf16 v[76:79], v[170:173], v[194:197], v[76:79]
	v_mfma_f32_16x16x32_bf16 v[72:75], v[162:165], v[208:211], v[72:75]
	v_mfma_f32_16x16x32_bf16 v[68:71], v[170:173], v[208:211], v[68:71]
	v_mfma_f32_16x16x32_bf16 v[112:115], v[166:169], v[182:185], v[112:115]
	v_mfma_f32_16x16x32_bf16 v[108:111], v[174:177], v[182:185], v[108:111]
	v_mfma_f32_16x16x32_bf16 v[96:99], v[166:169], v[190:193], v[96:99]
	v_mfma_f32_16x16x32_bf16 v[92:95], v[174:177], v[190:193], v[92:95]
	v_mfma_f32_16x16x32_bf16 v[80:83], v[166:169], v[204:207], v[80:83]
	v_mfma_f32_16x16x32_bf16 v[76:79], v[174:177], v[204:207], v[76:79]
	v_mfma_f32_16x16x32_bf16 v[72:75], v[166:169], v[212:215], v[72:75]
	v_mfma_f32_16x16x32_bf16 v[68:71], v[174:177], v[212:215], v[68:71]
	s_barrier
	s_add_i32 s49, s49, s28
	v_lshl_add_u64 v[198:199], s[24:25], 0, v[2:3]
	s_mov_b32 m0, s49
	ds_read_b128 v[178:181], v145 offset:16384
	ds_read_b128 v[182:185], v145 offset:17408
	ds_read_b128 v[186:189], v145 offset:18432
	ds_read_b128 v[190:193], v145 offset:19456
	ds_read_b128 v[194:197], v145 offset:20480
	ds_read_b128 v[204:207], v145 offset:21504
	ds_read_b128 v[208:211], v145 offset:22528
	ds_read_b128 v[212:215], v145 offset:23552
	global_load_lds_dwordx4 v[198:199], off
	s_add_i32 m0, s49, 0x2000
	s_add_u32 s52, s24, 0x100000
	v_lshl_add_u64 v[226:227], s[24:25], 0, v[132:133]
	s_addc_u32 s53, s25, 0
	s_add_i32 s49, s51, s28
	global_load_lds_dwordx4 v[226:227], off
	v_lshl_add_u64 v[228:229], s[52:53], 0, v[2:3]
	s_mov_b32 m0, s49
	s_nop 0
	global_load_lds_dwordx4 v[228:229], off
	v_lshl_add_u64 v[228:229], s[52:53], 0, v[132:133]
	s_add_i32 m0, s49, 0x2000
	s_nop 0
	global_load_lds_dwordx4 v[228:229], off
	v_lshl_add_u64 v[228:229], s[26:27], 0, v[136:137]
	s_mov_b32 m0, s29
	s_nop 0
	global_load_lds_dwordx4 v[228:229], off
	v_lshl_add_u64 v[228:229], s[26:27], 0, v[134:135]
	s_mov_b32 m0, s30
	s_nop 0
	global_load_lds_dwordx4 v[228:229], off
	s_waitcnt vmcnt(8)
	s_waitcnt lgkmcnt(0)
	s_barrier
	v_mfma_f32_16x16x32_bf16 v[64:67], v[146:149], v[178:181], v[64:67]
	v_mfma_f32_16x16x32_bf16 v[60:63], v[154:157], v[178:181], v[60:63]
	v_mfma_f32_16x16x32_bf16 v[56:59], v[146:149], v[186:189], v[56:59]
	v_mfma_f32_16x16x32_bf16 v[52:55], v[154:157], v[186:189], v[52:55]
	v_mfma_f32_16x16x32_bf16 v[40:43], v[146:149], v[194:197], v[40:43]
	v_mfma_f32_16x16x32_bf16 v[36:39], v[154:157], v[194:197], v[36:39]
	v_mfma_f32_16x16x32_bf16 v[24:27], v[146:149], v[208:211], v[24:27]
	v_mfma_f32_16x16x32_bf16 v[20:23], v[154:157], v[208:211], v[20:23]
	v_mfma_f32_16x16x32_bf16 v[64:67], v[150:153], v[182:185], v[64:67]
	v_mfma_f32_16x16x32_bf16 v[60:63], v[158:161], v[182:185], v[60:63]
	v_mfma_f32_16x16x32_bf16 v[56:59], v[150:153], v[190:193], v[56:59]
	v_mfma_f32_16x16x32_bf16 v[52:55], v[158:161], v[190:193], v[52:55]
	v_mfma_f32_16x16x32_bf16 v[40:43], v[150:153], v[204:207], v[40:43]
	v_mfma_f32_16x16x32_bf16 v[36:39], v[158:161], v[204:207], v[36:39]
	v_mfma_f32_16x16x32_bf16 v[24:27], v[150:153], v[212:215], v[24:27]
	v_mfma_f32_16x16x32_bf16 v[20:23], v[158:161], v[212:215], v[20:23]
	v_mfma_f32_16x16x32_bf16 v[48:51], v[162:165], v[178:181], v[48:51]
	v_mfma_f32_16x16x32_bf16 v[44:47], v[170:173], v[178:181], v[44:47]
	v_mfma_f32_16x16x32_bf16 v[32:35], v[162:165], v[186:189], v[32:35]
	v_mfma_f32_16x16x32_bf16 v[28:31], v[170:173], v[186:189], v[28:31]
	v_mfma_f32_16x16x32_bf16 v[16:19], v[162:165], v[194:197], v[16:19]
	v_mfma_f32_16x16x32_bf16 v[12:15], v[170:173], v[194:197], v[12:15]
	v_mfma_f32_16x16x32_bf16 v[8:11], v[162:165], v[208:211], v[8:11]
	v_mfma_f32_16x16x32_bf16 v[4:7], v[170:173], v[208:211], v[4:7]
	v_mfma_f32_16x16x32_bf16 v[48:51], v[166:169], v[182:185], v[48:51]
	v_mfma_f32_16x16x32_bf16 v[44:47], v[174:177], v[182:185], v[44:47]
	v_mfma_f32_16x16x32_bf16 v[32:35], v[166:169], v[190:193], v[32:35]
	v_mfma_f32_16x16x32_bf16 v[28:31], v[174:177], v[190:193], v[28:31]
	v_mfma_f32_16x16x32_bf16 v[16:19], v[166:169], v[204:207], v[16:19]
	v_mfma_f32_16x16x32_bf16 v[12:15], v[174:177], v[204:207], v[12:15]
	v_mfma_f32_16x16x32_bf16 v[8:11], v[166:169], v[212:215], v[8:11]
	v_mfma_f32_16x16x32_bf16 v[4:7], v[174:177], v[212:215], v[4:7]
	s_barrier
	s_add_i32 s49, 0, 0x18000
	s_add_i32 s51, 0, 0x1c000
	v_add_u32_e32 v158, s49, v144
	v_add_u32_e32 v174, s51, v144
	ds_read_b128 v[146:149], v158
	ds_read_b128 v[150:153], v158 offset:1024
	ds_read_b128 v[154:157], v158 offset:2048
	ds_read_b128 v[158:161], v158 offset:3072
	ds_read_b128 v[162:165], v174
	ds_read_b128 v[166:169], v174 offset:1024
	ds_read_b128 v[170:173], v174 offset:2048
	ds_read_b128 v[174:177], v174 offset:3072
	s_add_u32 s26, s26, 0x4000
	s_addc_u32 s27, s27, 0
	s_mov_b32 m0, s31
	v_lshl_add_u64 v[228:229], s[26:27], 0, v[136:137]
	ds_read_b128 v[178:181], v145 offset:32768
	ds_read_b128 v[182:185], v145 offset:33792
	ds_read_b128 v[186:189], v145 offset:34816
	ds_read_b128 v[190:193], v145 offset:35840
	ds_read_b128 v[194:197], v145 offset:36864
	ds_read_b128 v[204:207], v145 offset:37888
	ds_read_b128 v[208:211], v145 offset:38912
	ds_read_b128 v[212:215], v145 offset:39936
	global_load_lds_dwordx4 v[228:229], off
	v_lshl_add_u64 v[228:229], s[26:27], 0, v[134:135]
	s_mov_b32 m0, s33
	s_nop 0
	global_load_lds_dwordx4 v[228:229], off
	s_waitcnt vmcnt(8)
	s_waitcnt lgkmcnt(0)
	s_barrier
	v_mfma_f32_16x16x32_bf16 v[128:131], v[146:149], v[178:181], v[128:131]
	v_mfma_f32_16x16x32_bf16 v[124:127], v[154:157], v[178:181], v[124:127]
	v_mfma_f32_16x16x32_bf16 v[120:123], v[146:149], v[186:189], v[120:123]
	v_mfma_f32_16x16x32_bf16 v[116:119], v[154:157], v[186:189], v[116:119]
	v_mfma_f32_16x16x32_bf16 v[104:107], v[146:149], v[194:197], v[104:107]
	v_mfma_f32_16x16x32_bf16 v[100:103], v[154:157], v[194:197], v[100:103]
	v_mfma_f32_16x16x32_bf16 v[88:91], v[146:149], v[208:211], v[88:91]
	v_mfma_f32_16x16x32_bf16 v[84:87], v[154:157], v[208:211], v[84:87]
	v_mfma_f32_16x16x32_bf16 v[128:131], v[150:153], v[182:185], v[128:131]
	v_mfma_f32_16x16x32_bf16 v[124:127], v[158:161], v[182:185], v[124:127]
	v_mfma_f32_16x16x32_bf16 v[120:123], v[150:153], v[190:193], v[120:123]
	v_mfma_f32_16x16x32_bf16 v[116:119], v[158:161], v[190:193], v[116:119]
	v_mfma_f32_16x16x32_bf16 v[104:107], v[150:153], v[204:207], v[104:107]
	v_mfma_f32_16x16x32_bf16 v[100:103], v[158:161], v[204:207], v[100:103]
	v_mfma_f32_16x16x32_bf16 v[88:91], v[150:153], v[212:215], v[88:91]
	v_mfma_f32_16x16x32_bf16 v[84:87], v[158:161], v[212:215], v[84:87]
	v_mfma_f32_16x16x32_bf16 v[112:115], v[162:165], v[178:181], v[112:115]
	v_mfma_f32_16x16x32_bf16 v[108:111], v[170:173], v[178:181], v[108:111]
	v_mfma_f32_16x16x32_bf16 v[96:99], v[162:165], v[186:189], v[96:99]
	v_mfma_f32_16x16x32_bf16 v[92:95], v[170:173], v[186:189], v[92:95]
	v_mfma_f32_16x16x32_bf16 v[80:83], v[162:165], v[194:197], v[80:83]
	v_mfma_f32_16x16x32_bf16 v[76:79], v[170:173], v[194:197], v[76:79]
	v_mfma_f32_16x16x32_bf16 v[72:75], v[162:165], v[208:211], v[72:75]
	v_mfma_f32_16x16x32_bf16 v[68:71], v[170:173], v[208:211], v[68:71]
	v_mfma_f32_16x16x32_bf16 v[112:115], v[166:169], v[182:185], v[112:115]
	v_mfma_f32_16x16x32_bf16 v[108:111], v[174:177], v[182:185], v[108:111]
	v_mfma_f32_16x16x32_bf16 v[96:99], v[166:169], v[190:193], v[96:99]
	v_mfma_f32_16x16x32_bf16 v[92:95], v[174:177], v[190:193], v[92:95]
	v_mfma_f32_16x16x32_bf16 v[80:83], v[166:169], v[204:207], v[80:83]
	v_mfma_f32_16x16x32_bf16 v[76:79], v[174:177], v[204:207], v[76:79]
	v_mfma_f32_16x16x32_bf16 v[72:75], v[166:169], v[212:215], v[72:75]
	v_mfma_f32_16x16x32_bf16 v[68:71], v[174:177], v[212:215], v[68:71]
	s_barrier
	s_add_i32 s26, s49, s28
	v_lshl_add_u64 v[198:199], v[198:199], 0, s[94:95]
	s_mov_b32 m0, s26
	ds_read_b128 v[178:181], v145 offset:49152
	ds_read_b128 v[182:185], v145 offset:50176
	ds_read_b128 v[186:189], v145 offset:51200
	ds_read_b128 v[190:193], v145 offset:52224
	ds_read_b128 v[194:197], v145 offset:53248
	ds_read_b128 v[204:207], v145 offset:54272
	ds_read_b128 v[208:211], v145 offset:55296
	ds_read_b128 v[212:215], v145 offset:56320
	global_load_lds_dwordx4 v[198:199], off
	s_add_i32 m0, s26, 0x2000
	s_add_u32 s24, s24, 0x100080
	v_lshl_add_u64 v[198:199], v[226:227], 0, s[94:95]
	s_addc_u32 s25, s25, 0
	s_add_i32 s26, s51, s28
	global_load_lds_dwordx4 v[198:199], off
	v_lshl_add_u64 v[198:199], s[24:25], 0, v[2:3]
	s_mov_b32 m0, s26
	s_nop 0
	global_load_lds_dwordx4 v[198:199], off
	v_lshl_add_u64 v[198:199], s[24:25], 0, v[132:133]
	s_add_i32 m0, s26, 0x2000
	s_nop 0
	global_load_lds_dwordx4 v[198:199], off
	v_lshl_add_u64 v[198:199], s[22:23], 0, v[136:137]
	s_mov_b32 m0, s37
	s_nop 0
	global_load_lds_dwordx4 v[198:199], off
	v_lshl_add_u64 v[198:199], s[22:23], 0, v[134:135]
	s_mov_b32 m0, s39
	s_nop 0
	global_load_lds_dwordx4 v[198:199], off
	s_waitcnt vmcnt(8)
	s_waitcnt lgkmcnt(0)
	s_barrier
	v_mfma_f32_16x16x32_bf16 v[64:67], v[146:149], v[178:181], v[64:67]
	v_mfma_f32_16x16x32_bf16 v[60:63], v[154:157], v[178:181], v[60:63]
	v_mfma_f32_16x16x32_bf16 v[56:59], v[146:149], v[186:189], v[56:59]
	v_mfma_f32_16x16x32_bf16 v[52:55], v[154:157], v[186:189], v[52:55]
	v_mfma_f32_16x16x32_bf16 v[40:43], v[146:149], v[194:197], v[40:43]
	v_mfma_f32_16x16x32_bf16 v[36:39], v[154:157], v[194:197], v[36:39]
	v_mfma_f32_16x16x32_bf16 v[24:27], v[146:149], v[208:211], v[24:27]
	v_mfma_f32_16x16x32_bf16 v[20:23], v[154:157], v[208:211], v[20:23]
	v_mfma_f32_16x16x32_bf16 v[64:67], v[150:153], v[182:185], v[64:67]
	v_mfma_f32_16x16x32_bf16 v[60:63], v[158:161], v[182:185], v[60:63]
	v_mfma_f32_16x16x32_bf16 v[56:59], v[150:153], v[190:193], v[56:59]
	v_mfma_f32_16x16x32_bf16 v[52:55], v[158:161], v[190:193], v[52:55]
	v_mfma_f32_16x16x32_bf16 v[40:43], v[150:153], v[204:207], v[40:43]
	v_mfma_f32_16x16x32_bf16 v[36:39], v[158:161], v[204:207], v[36:39]
	v_mfma_f32_16x16x32_bf16 v[24:27], v[150:153], v[212:215], v[24:27]
	v_mfma_f32_16x16x32_bf16 v[20:23], v[158:161], v[212:215], v[20:23]
	v_mfma_f32_16x16x32_bf16 v[48:51], v[162:165], v[178:181], v[48:51]
	v_mfma_f32_16x16x32_bf16 v[44:47], v[170:173], v[178:181], v[44:47]
	v_mfma_f32_16x16x32_bf16 v[32:35], v[162:165], v[186:189], v[32:35]
	v_mfma_f32_16x16x32_bf16 v[28:31], v[170:173], v[186:189], v[28:31]
	v_mfma_f32_16x16x32_bf16 v[16:19], v[162:165], v[194:197], v[16:19]
	v_mfma_f32_16x16x32_bf16 v[12:15], v[170:173], v[194:197], v[12:15]
	v_mfma_f32_16x16x32_bf16 v[8:11], v[162:165], v[208:211], v[8:11]
	v_mfma_f32_16x16x32_bf16 v[4:7], v[170:173], v[208:211], v[4:7]
	v_mfma_f32_16x16x32_bf16 v[48:51], v[166:169], v[182:185], v[48:51]
	v_mfma_f32_16x16x32_bf16 v[44:47], v[174:177], v[182:185], v[44:47]
	v_mfma_f32_16x16x32_bf16 v[32:35], v[166:169], v[190:193], v[32:35]
	v_mfma_f32_16x16x32_bf16 v[28:31], v[174:177], v[190:193], v[28:31]
	v_mfma_f32_16x16x32_bf16 v[16:19], v[166:169], v[204:207], v[16:19]
	v_mfma_f32_16x16x32_bf16 v[12:15], v[174:177], v[204:207], v[12:15]
	v_mfma_f32_16x16x32_bf16 v[8:11], v[166:169], v[212:215], v[8:11]
	v_mfma_f32_16x16x32_bf16 v[4:7], v[174:177], v[212:215], v[4:7]
	s_barrier
	s_add_i32 s48, s48, 2
	s_add_u32 s46, s46, 0x100
	s_addc_u32 s47, s47, 0
	s_add_u32 s20, s20, 0x10000
	s_addc_u32 s21, s21, 0
	s_cmp_gt_u32 s48, 61
	s_cbranch_scc0 .LBB0_3844
	s_and_b64 vcc, exec, s[8:9]
	s_cbranch_vccz .LBB0_3847
	s_barrier

.LBB0_3911:
	s_ashr_i32 s6, s10, 8
	s_ashr_i32 s7, s6, 31
	s_lshl_b64 s[6:7], s[6:7], 21
	s_add_u32 s6, s0, s6
	s_addc_u32 s7, s1, s7
	s_and_b32 s18, s11, 0x3fc0
	s_lshl_b32 s18, s18, 3
	s_add_u32 s6, s6, s18
	s_addc_u32 s7, s7, 0
	v_add_u32_e32 v116, 0x1000, v68
	v_add_u32_e32 v117, 0x2000, v68
	v_add_u32_e32 v118, 0x3000, v68
	global_load_dwordx2 v[138:139], v2, s[6:7] nt
	s_add_u32 s6, s6, 0x20000
	s_addc_u32 s7, s7, 0
	global_load_dwordx2 v[140:141], v2, s[6:7] nt
	s_add_u32 s6, s6, 0x20000
	s_addc_u32 s7, s7, 0
	global_load_dwordx2 v[142:143], v2, s[6:7] nt
	s_add_u32 s6, s6, 0x20000
	s_addc_u32 s7, s7, 0
	global_load_dwordx2 v[144:145], v2, s[6:7] nt
	s_add_u32 s6, s6, 0x20000
	s_addc_u32 s7, s7, 0
	global_load_dwordx2 v[146:147], v2, s[6:7] nt
	s_add_u32 s6, s6, 0x20000
	s_addc_u32 s7, s7, 0
	global_load_dwordx2 v[148:149], v2, s[6:7] nt
	s_add_u32 s6, s6, 0x20000
	s_addc_u32 s7, s7, 0
	global_load_dwordx2 v[150:151], v2, s[6:7] nt
	s_add_u32 s6, s6, 0x20000
	s_addc_u32 s7, s7, 0
	global_load_dwordx2 v[152:153], v2, s[6:7] nt
	s_add_u32 s6, s6, 0x20000
	s_addc_u32 s7, s7, 0
	global_load_dwordx2 v[246:247], v2, s[6:7] nt
	s_add_u32 s6, s6, 0x20000
	s_addc_u32 s7, s7, 0
	global_load_dwordx2 v[248:249], v2, s[6:7] nt
	s_add_u32 s6, s6, 0x20000
	s_addc_u32 s7, s7, 0
	global_load_dwordx2 v[250:251], v2, s[6:7] nt
	s_add_u32 s6, s6, 0x20000
	s_addc_u32 s7, s7, 0
	global_load_dwordx2 v[252:253], v2, s[6:7] nt
	s_add_u32 s6, s6, 0x20000
	s_addc_u32 s7, s7, 0
	global_load_dwordx2 v[100:101], v2, s[6:7] nt
	s_add_u32 s6, s6, 0x20000
	s_addc_u32 s7, s7, 0
	global_load_dwordx2 v[102:103], v2, s[6:7] nt
	s_add_u32 s6, s6, 0x20000
	s_addc_u32 s7, s7, 0
	global_load_dwordx2 v[104:105], v2, s[6:7] nt
	s_add_u32 s6, s6, 0x20000
	s_addc_u32 s7, s7, 0
	global_load_dwordx2 v[108:109], v2, s[6:7] nt
	global_load_dwordx4 v[64:67], v68, s[16:17] nt
	global_load_dwordx4 v[168:171], v[70:71], off
	global_load_dwordx4 v[60:63], v68, s[16:17] offset:1024 nt
	global_load_dwordx4 v[172:175], v[70:71], off offset:1024
	global_load_dwordx4 v[48:51], v68, s[16:17] offset:2048 nt
	global_load_dwordx4 v[176:179], v[70:71], off offset:2048
	global_load_dwordx4 v[56:59], v68, s[16:17] offset:3072 nt
	global_load_dwordx4 v[180:183], v[70:71], off offset:3072
	global_load_dwordx4 v[52:55], v116, s[16:17] nt
	global_load_dwordx4 v[184:187], v[98:99], off
	global_load_dwordx4 v[44:47], v116, s[16:17] offset:1024 nt
	global_load_dwordx4 v[188:191], v[98:99], off offset:1024
	global_load_dwordx4 v[40:43], v116, s[16:17] offset:2048 nt
	global_load_dwordx4 v[192:195], v[98:99], off offset:2048
	global_load_dwordx4 v[36:39], v116, s[16:17] offset:3072 nt
	global_load_dwordx4 v[196:199], v[98:99], off offset:3072
	global_load_dwordx4 v[32:35], v117, s[16:17] nt
	global_load_dwordx4 v[204:207], v[106:107], off
	global_load_dwordx4 v[28:31], v117, s[16:17] offset:1024 nt
	global_load_dwordx4 v[208:211], v[106:107], off offset:1024
	global_load_dwordx4 v[24:27], v117, s[16:17] offset:2048 nt
	global_load_dwordx4 v[212:215], v[106:107], off offset:2048
	global_load_dwordx4 v[20:23], v117, s[16:17] offset:3072 nt
	global_load_dwordx4 v[226:229], v[106:107], off offset:3072
	global_load_dwordx4 v[16:19], v118, s[16:17] nt
	global_load_dwordx4 v[230:233], v[114:115], off
	global_load_dwordx4 v[12:15], v118, s[16:17] offset:1024 nt
	global_load_dwordx4 v[234:237], v[114:115], off offset:1024
	global_load_dwordx4 v[8:11], v118, s[16:17] offset:2048 nt
	global_load_dwordx4 v[238:241], v[114:115], off offset:2048
	global_load_dwordx4 v[4:7], v118, s[16:17] offset:3072 nt
	global_load_dwordx4 v[242:245], v[114:115], off offset:3072
	s_waitcnt vmcnt(47)
	v_and_b32_e32 v127, 0xffff0000, v138
	v_and_b32_e32 v129, 0xffff0000, v139
	v_lshlrev_b32_e32 v126, 16, v138
	v_lshlrev_b32_e32 v128, 16, v139
	v_mul_f32_e32 v130, v127, v127
	v_mul_f32_e32 v131, v129, v129
	v_fmac_f32_e32 v130, v126, v126
	v_fmac_f32_e32 v131, v128, v128
	v_add_f32_e32 v132, v130, v131
	s_waitcnt vmcnt(46)
	v_and_b32_e32 v135, 0xffff0000, v140
	v_and_b32_e32 v137, 0xffff0000, v141
	v_lshlrev_b32_e32 v134, 16, v140
	v_lshlrev_b32_e32 v136, 16, v141
	v_mul_f32_e32 v156, v135, v135
	v_mul_f32_e32 v157, v137, v137
	v_fmac_f32_e32 v156, v134, v134
	v_fmac_f32_e32 v157, v136, v136
	v_add_f32_e32 v156, v156, v157
	v_add_f32_e32 v132, v132, v156
	s_waitcnt vmcnt(45)
	v_and_b32_e32 v127, 0xffff0000, v142
	v_and_b32_e32 v129, 0xffff0000, v143
	v_lshlrev_b32_e32 v126, 16, v142
	v_lshlrev_b32_e32 v128, 16, v143
	v_mul_f32_e32 v130, v127, v127
	v_mul_f32_e32 v131, v129, v129
	v_fmac_f32_e32 v130, v126, v126
	v_fmac_f32_e32 v131, v128, v128
	v_add_f32_e32 v130, v130, v131
	v_add_f32_e32 v132, v132, v130
	s_waitcnt vmcnt(44)
	v_and_b32_e32 v135, 0xffff0000, v144
	v_and_b32_e32 v137, 0xffff0000, v145
	v_lshlrev_b32_e32 v134, 16, v144
	v_lshlrev_b32_e32 v136, 16, v145
	v_mul_f32_e32 v156, v135, v135
	v_mul_f32_e32 v157, v137, v137
	v_fmac_f32_e32 v156, v134, v134
	v_fmac_f32_e32 v157, v136, v136
	v_add_f32_e32 v156, v156, v157
	v_add_f32_e32 v132, v132, v156
	s_waitcnt vmcnt(43)
	v_and_b32_e32 v127, 0xffff0000, v146
	v_and_b32_e32 v129, 0xffff0000, v147
	v_lshlrev_b32_e32 v126, 16, v146
	v_lshlrev_b32_e32 v128, 16, v147
	v_mul_f32_e32 v130, v127, v127
	v_mul_f32_e32 v131, v129, v129
	v_fmac_f32_e32 v130, v126, v126
	v_fmac_f32_e32 v131, v128, v128
	v_add_f32_e32 v130, v130, v131
	v_add_f32_e32 v132, v132, v130
	s_waitcnt vmcnt(42)
	v_and_b32_e32 v135, 0xffff0000, v148
	v_and_b32_e32 v137, 0xffff0000, v149
	v_lshlrev_b32_e32 v134, 16, v148
	v_lshlrev_b32_e32 v136, 16, v149
	v_mul_f32_e32 v156, v135, v135
	v_mul_f32_e32 v157, v137, v137
	v_fmac_f32_e32 v156, v134, v134
	v_fmac_f32_e32 v157, v136, v136
	v_add_f32_e32 v156, v156, v157
	v_add_f32_e32 v132, v132, v156
	s_waitcnt vmcnt(41)
	v_and_b32_e32 v127, 0xffff0000, v150
	v_and_b32_e32 v129, 0xffff0000, v151
	v_lshlrev_b32_e32 v126, 16, v150
	v_lshlrev_b32_e32 v128, 16, v151
	v_mul_f32_e32 v130, v127, v127
	v_mul_f32_e32 v131, v129, v129
	v_fmac_f32_e32 v130, v126, v126
	v_fmac_f32_e32 v131, v128, v128
	v_add_f32_e32 v130, v130, v131
	v_add_f32_e32 v132, v132, v130
	s_waitcnt vmcnt(40)
	v_and_b32_e32 v135, 0xffff0000, v152
	v_and_b32_e32 v137, 0xffff0000, v153
	v_lshlrev_b32_e32 v134, 16, v152
	v_lshlrev_b32_e32 v136, 16, v153
	v_mul_f32_e32 v156, v135, v135
	v_mul_f32_e32 v157, v137, v137
	v_fmac_f32_e32 v156, v134, v134
	v_fmac_f32_e32 v157, v136, v136
	v_add_f32_e32 v156, v156, v157
	v_add_f32_e32 v132, v132, v156
	s_waitcnt vmcnt(39)
	v_and_b32_e32 v127, 0xffff0000, v246
	v_and_b32_e32 v129, 0xffff0000, v247
	v_lshlrev_b32_e32 v126, 16, v246
	v_lshlrev_b32_e32 v128, 16, v247
	v_mul_f32_e32 v130, v127, v127
	v_mul_f32_e32 v131, v129, v129
	v_fmac_f32_e32 v130, v126, v126
	v_fmac_f32_e32 v131, v128, v128
	v_add_f32_e32 v130, v130, v131
	v_add_f32_e32 v132, v132, v130
	s_waitcnt vmcnt(38)
	v_and_b32_e32 v135, 0xffff0000, v248
	v_and_b32_e32 v137, 0xffff0000, v249
	v_lshlrev_b32_e32 v134, 16, v248
	v_lshlrev_b32_e32 v136, 16, v249
	v_mul_f32_e32 v156, v135, v135
	v_mul_f32_e32 v157, v137, v137
	v_fmac_f32_e32 v156, v134, v134
	v_fmac_f32_e32 v157, v136, v136
	v_add_f32_e32 v156, v156, v157
	v_add_f32_e32 v132, v132, v156
	s_waitcnt vmcnt(37)
	v_and_b32_e32 v127, 0xffff0000, v250
	v_and_b32_e32 v129, 0xffff0000, v251
	v_lshlrev_b32_e32 v126, 16, v250
	v_lshlrev_b32_e32 v128, 16, v251
	v_mul_f32_e32 v130, v127, v127
	v_mul_f32_e32 v131, v129, v129
	v_fmac_f32_e32 v130, v126, v126
	v_fmac_f32_e32 v131, v128, v128
	v_add_f32_e32 v130, v130, v131
	v_add_f32_e32 v132, v132, v130
	s_waitcnt vmcnt(36)
	v_and_b32_e32 v135, 0xffff0000, v252
	v_and_b32_e32 v137, 0xffff0000, v253
	v_lshlrev_b32_e32 v134, 16, v252
	v_lshlrev_b32_e32 v136, 16, v253
	v_mul_f32_e32 v156, v135, v135
	v_mul_f32_e32 v157, v137, v137
	v_fmac_f32_e32 v156, v134, v134
	v_fmac_f32_e32 v157, v136, v136
	v_add_f32_e32 v156, v156, v157
	v_add_f32_e32 v132, v132, v156
	s_waitcnt vmcnt(35)
	v_and_b32_e32 v127, 0xffff0000, v100
	v_and_b32_e32 v129, 0xffff0000, v101
	v_lshlrev_b32_e32 v126, 16, v100
	v_lshlrev_b32_e32 v128, 16, v101
	v_mul_f32_e32 v130, v127, v127
	v_mul_f32_e32 v131, v129, v129
	v_fmac_f32_e32 v130, v126, v126
	v_fmac_f32_e32 v131, v128, v128
	v_add_f32_e32 v130, v130, v131
	v_add_f32_e32 v132, v132, v130
	s_waitcnt vmcnt(34)
	v_and_b32_e32 v135, 0xffff0000, v102
	v_and_b32_e32 v137, 0xffff0000, v103
	v_lshlrev_b32_e32 v134, 16, v102
	v_lshlrev_b32_e32 v136, 16, v103
	v_mul_f32_e32 v156, v135, v135
	v_mul_f32_e32 v157, v137, v137
	v_fmac_f32_e32 v156, v134, v134
	v_fmac_f32_e32 v157, v136, v136
	v_add_f32_e32 v156, v156, v157
	v_add_f32_e32 v132, v132, v156
	s_waitcnt vmcnt(33)
	v_and_b32_e32 v127, 0xffff0000, v104
	v_and_b32_e32 v129, 0xffff0000, v105
	v_lshlrev_b32_e32 v126, 16, v104
	v_lshlrev_b32_e32 v128, 16, v105
	v_mul_f32_e32 v130, v127, v127
	v_mul_f32_e32 v131, v129, v129
	v_fmac_f32_e32 v130, v126, v126
	v_fmac_f32_e32 v131, v128, v128
	v_add_f32_e32 v130, v130, v131
	v_add_f32_e32 v132, v132, v130
	s_waitcnt vmcnt(32)
	v_and_b32_e32 v135, 0xffff0000, v108
	v_and_b32_e32 v137, 0xffff0000, v109
	v_lshlrev_b32_e32 v134, 16, v108
	v_lshlrev_b32_e32 v136, 16, v109
	v_mul_f32_e32 v156, v135, v135
	v_mul_f32_e32 v157, v137, v137
	v_fmac_f32_e32 v156, v134, v134
	v_fmac_f32_e32 v157, v136, v136
	v_add_f32_e32 v156, v156, v157
	v_add_f32_e32 v132, v132, v156
	s_mov_b32 s6, 0xf800000
	ds_bpermute_b32 v133, v155, v132
	s_waitcnt lgkmcnt(0)
	v_add_f32_e32 v132, v132, v133
	ds_bpermute_b32 v133, v160, v132
	s_waitcnt lgkmcnt(0)
	v_add_f32_e32 v132, v132, v133
	ds_bpermute_b32 v133, v161, v132
	s_waitcnt lgkmcnt(0)
	v_add_f32_e32 v132, v132, v133
	ds_bpermute_b32 v133, v162, v132
	s_waitcnt lgkmcnt(0)
	v_add_f32_e32 v132, v132, v133
	ds_bpermute_b32 v133, v163, v132
	s_waitcnt lgkmcnt(0)
	v_add_f32_e32 v132, v132, v133
	ds_bpermute_b32 v133, v164, v132
	s_waitcnt lgkmcnt(0)
	v_add_f32_e32 v132, v132, v133
	v_fmamk_f32 v126, v132, 0x39800000, v217
	v_mul_f32_e32 v127, 0x4f800000, v126
	v_cmp_gt_f32_e32 vcc, s6, v126
	s_nop 1
	v_cndmask_b32_e32 v126, v126, v127, vcc
	v_sqrt_f32_e32 v127, v126
	s_nop 0
	v_add_u32_e32 v128, -1, v127
	v_fma_f32 v129, -v128, v127, v126
	v_cmp_ge_f32_e64 s[6:7], 0, v129
	v_add_u32_e32 v129, 1, v127
	s_nop 0
	v_cndmask_b32_e64 v128, v127, v128, s[6:7]
	v_fma_f32 v127, -v129, v127, v126
	v_cmp_lt_f32_e64 s[6:7], 0, v127
	s_nop 1
	v_cndmask_b32_e64 v127, v128, v129, s[6:7]
	v_mul_f32_e32 v128, 0x37800000, v127
	v_cndmask_b32_e32 v127, v127, v128, vcc
	v_cmp_class_f32_e32 vcc, v126, v218
	s_nop 1
	v_cndmask_b32_e32 v126, v127, v126, vcc
	v_div_scale_f32 v127, s[6:7], v126, v126, 1.0
	v_rcp_f32_e32 v128, v127
	s_nop 0
	v_fma_f32 v129, -v127, v128, 1.0
	v_fmac_f32_e32 v128, v129, v128
	v_div_scale_f32 v129, vcc, 1.0, v126, 1.0
	v_mul_f32_e32 v130, v129, v128
	v_fma_f32 v131, -v127, v130, v129
	v_fmac_f32_e32 v130, v131, v128
	v_fma_f32 v127, -v127, v130, v129
	v_div_fmas_f32 v127, v127, v128, v130
	v_div_fixup_f32 v154, v127, v126, 1.0
	v_lshlrev_b32_e32 v126, 16, v138
	v_and_b32_e32 v127, 0xffff0000, v138
	v_lshlrev_b32_e32 v128, 16, v139
	v_and_b32_e32 v129, 0xffff0000, v139
	v_pk_mul_f32 v[126:127], v[154:155], v[126:127] op_sel_hi:[0,1]
	v_pk_mul_f32 v[128:129], v[154:155], v[128:129] op_sel_hi:[0,1]
	s_waitcnt vmcnt(30)
	v_pk_fma_f32 v[64:65], v[168:169], v[126:127], v[64:65]
	v_pk_fma_f32 v[66:67], v[170:171], v[128:129], v[66:67]
	global_store_dwordx4 v68, v[64:67], s[12:13] nt
	v_lshlrev_b32_e32 v134, 16, v140
	v_and_b32_e32 v135, 0xffff0000, v140
	v_lshlrev_b32_e32 v136, 16, v141
	v_and_b32_e32 v137, 0xffff0000, v141
	v_pk_mul_f32 v[134:135], v[154:155], v[134:135] op_sel_hi:[0,1]
	v_pk_mul_f32 v[136:137], v[154:155], v[136:137] op_sel_hi:[0,1]
	s_waitcnt vmcnt(29)
	v_pk_fma_f32 v[60:61], v[172:173], v[134:135], v[60:61]
	v_pk_fma_f32 v[62:63], v[174:175], v[136:137], v[62:63]
	global_store_dwordx4 v68, v[60:63], s[12:13] offset:1024 nt
	v_lshlrev_b32_e32 v126, 16, v142
	v_and_b32_e32 v127, 0xffff0000, v142
	v_lshlrev_b32_e32 v128, 16, v143
	v_and_b32_e32 v129, 0xffff0000, v143
	v_pk_mul_f32 v[126:127], v[154:155], v[126:127] op_sel_hi:[0,1]
	v_pk_mul_f32 v[128:129], v[154:155], v[128:129] op_sel_hi:[0,1]
	s_waitcnt vmcnt(28)
	v_pk_fma_f32 v[48:49], v[176:177], v[126:127], v[48:49]
	v_pk_fma_f32 v[50:51], v[178:179], v[128:129], v[50:51]
	global_store_dwordx4 v68, v[48:51], s[12:13] offset:2048 nt
	v_lshlrev_b32_e32 v134, 16, v144
	v_and_b32_e32 v135, 0xffff0000, v144
	v_lshlrev_b32_e32 v136, 16, v145
	v_and_b32_e32 v137, 0xffff0000, v145
	v_pk_mul_f32 v[134:135], v[154:155], v[134:135] op_sel_hi:[0,1]
	v_pk_mul_f32 v[136:137], v[154:155], v[136:137] op_sel_hi:[0,1]
	s_waitcnt vmcnt(27)
	v_pk_fma_f32 v[56:57], v[180:181], v[134:135], v[56:57]
	v_pk_fma_f32 v[58:59], v[182:183], v[136:137], v[58:59]
	global_store_dwordx4 v68, v[56:59], s[12:13] offset:3072 nt
	v_lshlrev_b32_e32 v126, 16, v146
	v_and_b32_e32 v127, 0xffff0000, v146
	v_lshlrev_b32_e32 v128, 16, v147
	v_and_b32_e32 v129, 0xffff0000, v147
	v_pk_mul_f32 v[126:127], v[154:155], v[126:127] op_sel_hi:[0,1]
	v_pk_mul_f32 v[128:129], v[154:155], v[128:129] op_sel_hi:[0,1]
	s_waitcnt vmcnt(26)
	v_pk_fma_f32 v[52:53], v[184:185], v[126:127], v[52:53]
	v_pk_fma_f32 v[54:55], v[186:187], v[128:129], v[54:55]
	global_store_dwordx4 v116, v[52:55], s[12:13] nt
	v_lshlrev_b32_e32 v134, 16, v148
	v_and_b32_e32 v135, 0xffff0000, v148
	v_lshlrev_b32_e32 v136, 16, v149
	v_and_b32_e32 v137, 0xffff0000, v149
	v_pk_mul_f32 v[134:135], v[154:155], v[134:135] op_sel_hi:[0,1]
	v_pk_mul_f32 v[136:137], v[154:155], v[136:137] op_sel_hi:[0,1]
	s_waitcnt vmcnt(25)
	v_pk_fma_f32 v[44:45], v[188:189], v[134:135], v[44:45]
	v_pk_fma_f32 v[46:47], v[190:191], v[136:137], v[46:47]
	global_store_dwordx4 v116, v[44:47], s[12:13] offset:1024 nt
	v_lshlrev_b32_e32 v126, 16, v150
	v_and_b32_e32 v127, 0xffff0000, v150
	v_lshlrev_b32_e32 v128, 16, v151
	v_and_b32_e32 v129, 0xffff0000, v151
	v_pk_mul_f32 v[126:127], v[154:155], v[126:127] op_sel_hi:[0,1]
	v_pk_mul_f32 v[128:129], v[154:155], v[128:129] op_sel_hi:[0,1]
	s_waitcnt vmcnt(24)
	v_pk_fma_f32 v[40:41], v[192:193], v[126:127], v[40:41]
	v_pk_fma_f32 v[42:43], v[194:195], v[128:129], v[42:43]
	global_store_dwordx4 v116, v[40:43], s[12:13] offset:2048 nt
	v_lshlrev_b32_e32 v134, 16, v152
	v_and_b32_e32 v135, 0xffff0000, v152
	v_lshlrev_b32_e32 v136, 16, v153
	v_and_b32_e32 v137, 0xffff0000, v153
	v_pk_mul_f32 v[134:135], v[154:155], v[134:135] op_sel_hi:[0,1]
	v_pk_mul_f32 v[136:137], v[154:155], v[136:137] op_sel_hi:[0,1]
	s_waitcnt vmcnt(23)
	v_pk_fma_f32 v[36:37], v[196:197], v[134:135], v[36:37]
	v_pk_fma_f32 v[38:39], v[198:199], v[136:137], v[38:39]
	global_store_dwordx4 v116, v[36:39], s[12:13] offset:3072 nt
	v_lshlrev_b32_e32 v126, 16, v246
	v_and_b32_e32 v127, 0xffff0000, v246
	v_lshlrev_b32_e32 v128, 16, v247
	v_and_b32_e32 v129, 0xffff0000, v247
	v_pk_mul_f32 v[126:127], v[154:155], v[126:127] op_sel_hi:[0,1]
	v_pk_mul_f32 v[128:129], v[154:155], v[128:129] op_sel_hi:[0,1]
	s_waitcnt vmcnt(22)
	v_pk_fma_f32 v[32:33], v[204:205], v[126:127], v[32:33]
	v_pk_fma_f32 v[34:35], v[206:207], v[128:129], v[34:35]
	global_store_dwordx4 v117, v[32:35], s[12:13] nt
	v_lshlrev_b32_e32 v134, 16, v248
	v_and_b32_e32 v135, 0xffff0000, v248
	v_lshlrev_b32_e32 v136, 16, v249
	v_and_b32_e32 v137, 0xffff0000, v249
	v_pk_mul_f32 v[134:135], v[154:155], v[134:135] op_sel_hi:[0,1]
	v_pk_mul_f32 v[136:137], v[154:155], v[136:137] op_sel_hi:[0,1]
	s_waitcnt vmcnt(21)
	v_pk_fma_f32 v[28:29], v[208:209], v[134:135], v[28:29]
	v_pk_fma_f32 v[30:31], v[210:211], v[136:137], v[30:31]
	global_store_dwordx4 v117, v[28:31], s[12:13] offset:1024 nt
	v_lshlrev_b32_e32 v126, 16, v250
	v_and_b32_e32 v127, 0xffff0000, v250
	v_lshlrev_b32_e32 v128, 16, v251
	v_and_b32_e32 v129, 0xffff0000, v251
	v_pk_mul_f32 v[126:127], v[154:155], v[126:127] op_sel_hi:[0,1]
	v_pk_mul_f32 v[128:129], v[154:155], v[128:129] op_sel_hi:[0,1]
	s_waitcnt vmcnt(20)
	v_pk_fma_f32 v[24:25], v[212:213], v[126:127], v[24:25]
	v_pk_fma_f32 v[26:27], v[214:215], v[128:129], v[26:27]
	global_store_dwordx4 v117, v[24:27], s[12:13] offset:2048 nt
	v_lshlrev_b32_e32 v134, 16, v252
	v_and_b32_e32 v135, 0xffff0000, v252
	v_lshlrev_b32_e32 v136, 16, v253
	v_and_b32_e32 v137, 0xffff0000, v253
	v_pk_mul_f32 v[134:135], v[154:155], v[134:135] op_sel_hi:[0,1]
	v_pk_mul_f32 v[136:137], v[154:155], v[136:137] op_sel_hi:[0,1]
	s_waitcnt vmcnt(19)
	v_pk_fma_f32 v[20:21], v[226:227], v[134:135], v[20:21]
	v_pk_fma_f32 v[22:23], v[228:229], v[136:137], v[22:23]
	global_store_dwordx4 v117, v[20:23], s[12:13] offset:3072 nt
	v_lshlrev_b32_e32 v126, 16, v100
	v_and_b32_e32 v127, 0xffff0000, v100
	v_lshlrev_b32_e32 v128, 16, v101
	v_and_b32_e32 v129, 0xffff0000, v101
	v_pk_mul_f32 v[126:127], v[154:155], v[126:127] op_sel_hi:[0,1]
	v_pk_mul_f32 v[128:129], v[154:155], v[128:129] op_sel_hi:[0,1]
	s_waitcnt vmcnt(18)
	v_pk_fma_f32 v[16:17], v[230:231], v[126:127], v[16:17]
	v_pk_fma_f32 v[18:19], v[232:233], v[128:129], v[18:19]
	global_store_dwordx4 v118, v[16:19], s[12:13] nt
	v_lshlrev_b32_e32 v134, 16, v102
	v_and_b32_e32 v135, 0xffff0000, v102
	v_lshlrev_b32_e32 v136, 16, v103
	v_and_b32_e32 v137, 0xffff0000, v103
	v_pk_mul_f32 v[134:135], v[154:155], v[134:135] op_sel_hi:[0,1]
	v_pk_mul_f32 v[136:137], v[154:155], v[136:137] op_sel_hi:[0,1]
	s_waitcnt vmcnt(17)
	v_pk_fma_f32 v[12:13], v[234:235], v[134:135], v[12:13]
	v_pk_fma_f32 v[14:15], v[236:237], v[136:137], v[14:15]
	global_store_dwordx4 v118, v[12:15], s[12:13] offset:1024 nt
	v_lshlrev_b32_e32 v126, 16, v104
	v_and_b32_e32 v127, 0xffff0000, v104
	v_lshlrev_b32_e32 v128, 16, v105
	v_and_b32_e32 v129, 0xffff0000, v105
	v_pk_mul_f32 v[126:127], v[154:155], v[126:127] op_sel_hi:[0,1]
	v_pk_mul_f32 v[128:129], v[154:155], v[128:129] op_sel_hi:[0,1]
	s_waitcnt vmcnt(16)
	v_pk_fma_f32 v[8:9], v[238:239], v[126:127], v[8:9]
	v_pk_fma_f32 v[10:11], v[240:241], v[128:129], v[10:11]
	global_store_dwordx4 v118, v[8:11], s[12:13] offset:2048 nt
	v_lshlrev_b32_e32 v134, 16, v108
	v_and_b32_e32 v135, 0xffff0000, v108
	v_lshlrev_b32_e32 v136, 16, v109
	v_and_b32_e32 v137, 0xffff0000, v109
	v_pk_mul_f32 v[134:135], v[154:155], v[134:135] op_sel_hi:[0,1]
	v_pk_mul_f32 v[136:137], v[154:155], v[136:137] op_sel_hi:[0,1]
	s_waitcnt vmcnt(15)
	v_pk_fma_f32 v[4:5], v[242:243], v[134:135], v[4:5]
	v_pk_fma_f32 v[6:7], v[244:245], v[136:137], v[6:7]
	global_store_dwordx4 v118, v[4:7], s[12:13] offset:3072 nt
	v_readlane_b32 s6, v255, 14
	v_readlane_b32 s7, v255, 15
	s_nop 3
	s_andn2_b64 vcc, exec, s[6:7]
	s_cbranch_vccnz .LBB0_3910
	global_load_dwordx4 v[168:171], v[72:73], off
	global_load_dwordx4 v[172:175], v[72:73], off offset:1024
	global_load_dwordx4 v[176:179], v[72:73], off offset:2048
	global_load_dwordx4 v[180:183], v[72:73], off offset:3072
	global_load_dwordx4 v[184:187], v[74:75], off
	global_load_dwordx4 v[188:191], v[76:77], off
	global_load_dwordx4 v[192:195], v[78:79], off
	global_load_dwordx4 v[196:199], v[80:81], off
	global_load_dwordx4 v[204:207], v[82:83], off
	global_load_dwordx4 v[208:211], v[84:85], off
	global_load_dwordx4 v[212:215], v[86:87], off
	global_load_dwordx4 v[226:229], v[88:89], off
	global_load_dwordx4 v[230:233], v[90:91], off
	global_load_dwordx4 v[234:237], v[92:93], off
	global_load_dwordx4 v[238:241], v[94:95], off
	global_load_dwordx4 v[242:245], v[96:97], off
	v_mul_f32_e32 v126, v65, v65
	v_mul_f32_e32 v127, v67, v67
	v_fmac_f32_e32 v126, v64, v64
	v_fmac_f32_e32 v127, v66, v66
	v_add_f32_e32 v126, v126, v127
	v_mul_f32_e32 v127, v61, v61
	v_mul_f32_e32 v128, v63, v63
	v_fmac_f32_e32 v127, v60, v60
	v_fmac_f32_e32 v128, v62, v62
	v_add_f32_e32 v127, v127, v128
	v_add_f32_e32 v126, v126, v127
	v_mul_f32_e32 v127, v49, v49
	v_mul_f32_e32 v128, v51, v51
	v_fmac_f32_e32 v127, v48, v48
	v_fmac_f32_e32 v128, v50, v50
	v_add_f32_e32 v127, v127, v128
	v_add_f32_e32 v126, v126, v127
	v_mul_f32_e32 v127, v57, v57
	v_mul_f32_e32 v128, v59, v59
	v_fmac_f32_e32 v127, v56, v56
	v_fmac_f32_e32 v128, v58, v58
	v_add_f32_e32 v127, v127, v128
	v_add_f32_e32 v126, v126, v127
	v_mul_f32_e32 v127, v53, v53
	v_mul_f32_e32 v128, v55, v55
	v_fmac_f32_e32 v127, v52, v52
	v_fmac_f32_e32 v128, v54, v54
	v_add_f32_e32 v127, v127, v128
	v_add_f32_e32 v126, v126, v127
	v_mul_f32_e32 v127, v45, v45
	v_mul_f32_e32 v128, v47, v47
	v_fmac_f32_e32 v127, v44, v44
	v_fmac_f32_e32 v128, v46, v46
	v_add_f32_e32 v127, v127, v128
	v_add_f32_e32 v126, v126, v127
	v_mul_f32_e32 v127, v41, v41
	v_mul_f32_e32 v128, v43, v43
	v_fmac_f32_e32 v127, v40, v40
	v_fmac_f32_e32 v128, v42, v42
	v_add_f32_e32 v127, v127, v128
	v_add_f32_e32 v126, v126, v127
	v_mul_f32_e32 v127, v37, v37
	v_mul_f32_e32 v128, v39, v39
	v_fmac_f32_e32 v127, v36, v36
	v_fmac_f32_e32 v128, v38, v38
	v_add_f32_e32 v127, v127, v128
	v_add_f32_e32 v126, v126, v127
	v_mul_f32_e32 v127, v33, v33
	v_mul_f32_e32 v128, v35, v35
	v_fmac_f32_e32 v127, v32, v32
	v_fmac_f32_e32 v128, v34, v34
	v_add_f32_e32 v127, v127, v128
	v_add_f32_e32 v126, v126, v127
	v_mul_f32_e32 v127, v29, v29
	v_mul_f32_e32 v128, v31, v31
	v_fmac_f32_e32 v127, v28, v28
	v_fmac_f32_e32 v128, v30, v30
	v_add_f32_e32 v127, v127, v128
	v_add_f32_e32 v126, v126, v127
	v_mul_f32_e32 v127, v25, v25
	v_mul_f32_e32 v128, v27, v27
	v_fmac_f32_e32 v127, v24, v24
	v_fmac_f32_e32 v128, v26, v26
	v_add_f32_e32 v127, v127, v128
	v_add_f32_e32 v126, v126, v127
	v_mul_f32_e32 v127, v21, v21
	v_mul_f32_e32 v128, v23, v23
	v_fmac_f32_e32 v127, v20, v20
	v_fmac_f32_e32 v128, v22, v22
	v_add_f32_e32 v127, v127, v128
	s_nop 0
	v_add_f32_e32 v126, v126, v127
	v_mul_f32_e32 v127, v17, v17
	v_mul_f32_e32 v128, v19, v19
	v_fmac_f32_e32 v127, v16, v16
	v_fmac_f32_e32 v128, v18, v18
	v_add_f32_e32 v127, v127, v128
	v_add_f32_e32 v126, v126, v127
	v_mul_f32_e32 v127, v13, v13
	v_mul_f32_e32 v128, v15, v15
	v_fmac_f32_e32 v127, v12, v12
	v_fmac_f32_e32 v128, v14, v14
	v_add_f32_e32 v127, v127, v128
	v_add_f32_e32 v126, v126, v127
	v_mul_f32_e32 v127, v9, v9
	v_mul_f32_e32 v128, v11, v11
	v_fmac_f32_e32 v127, v8, v8
	v_fmac_f32_e32 v128, v10, v10
	v_add_f32_e32 v127, v127, v128
	v_add_f32_e32 v126, v126, v127
	v_mul_f32_e32 v127, v5, v5
	v_mul_f32_e32 v128, v7, v7
	v_fmac_f32_e32 v127, v4, v4
	v_fmac_f32_e32 v128, v6, v6
	v_add_f32_e32 v127, v127, v128
	v_add_f32_e32 v126, v126, v127
	ds_bpermute_b32 v127, v155, v126
	s_mov_b32 s6, 0xf800000
	v_lshl_add_u64 v[136:137], s[8:9], 0, v[124:125]
	s_waitcnt lgkmcnt(0)
	v_add_f32_e32 v126, v126, v127
	ds_bpermute_b32 v127, v160, v126
	s_waitcnt lgkmcnt(0)
	v_add_f32_e32 v126, v126, v127
	ds_bpermute_b32 v127, v161, v126
	s_waitcnt lgkmcnt(0)
	v_add_f32_e32 v126, v126, v127
	ds_bpermute_b32 v127, v162, v126
	s_waitcnt lgkmcnt(0)
	v_add_f32_e32 v126, v126, v127
	ds_bpermute_b32 v127, v163, v126
	s_waitcnt lgkmcnt(0)
	v_add_f32_e32 v126, v126, v127
	ds_bpermute_b32 v127, v164, v126
	s_waitcnt lgkmcnt(0)
	v_add_f32_e32 v126, v126, v127
	v_fmamk_f32 v126, v126, 0x39800000, v217
	v_mul_f32_e32 v127, 0x4f800000, v126
	v_cmp_gt_f32_e32 vcc, s6, v126
	s_nop 1
	v_cndmask_b32_e32 v126, v126, v127, vcc
	v_sqrt_f32_e32 v127, v126
	s_nop 0
	v_add_u32_e32 v128, -1, v127
	v_fma_f32 v129, -v128, v127, v126
	v_cmp_ge_f32_e64 s[6:7], 0, v129
	v_add_u32_e32 v129, 1, v127
	s_nop 0
	v_cndmask_b32_e64 v128, v127, v128, s[6:7]
	v_fma_f32 v127, -v129, v127, v126
	v_cmp_lt_f32_e64 s[6:7], 0, v127
	s_nop 1
	v_cndmask_b32_e64 v127, v128, v129, s[6:7]
	v_mul_f32_e32 v128, 0x37800000, v127
	v_cndmask_b32_e32 v127, v127, v128, vcc
	v_cmp_class_f32_e32 vcc, v126, v218
	s_nop 1
	v_cndmask_b32_e32 v126, v127, v126, vcc
	v_div_scale_f32 v127, s[6:7], v126, v126, 1.0
	v_rcp_f32_e32 v128, v127
	s_mov_b32 s6, 0x28801000
	v_fma_f32 v129, -v127, v128, 1.0
	v_fmac_f32_e32 v128, v129, v128
	v_div_scale_f32 v129, vcc, 1.0, v126, 1.0
	v_mul_f32_e32 v130, v129, v128
	v_fma_f32 v131, -v127, v130, v129
	v_fmac_f32_e32 v130, v131, v128
	v_fma_f32 v127, -v127, v130, v129
	v_div_fmas_f32 v127, v127, v128, v130
	v_div_fixup_f32 v130, v127, v126, 1.0
	v_mul_f32_e32 v64, v64, v130
	s_waitcnt vmcnt(15)
	v_mul_f32_e32 v128, v168, v64
	v_mul_f32_e32 v64, v65, v130
	v_mul_f32_e32 v127, v169, v64
	v_mul_f32_e32 v64, v66, v130
	v_mul_f32_e32 v126, v170, v64
	v_mul_f32_e32 v64, v67, v130
	v_mul_f32_e32 v66, v171, v64
	v_bfe_u32 v64, v128, 16, 1
	v_add3_u32 v64, v128, v64, s80
	v_bfe_u32 v65, v127, 16, 1
	v_lshrrev_b32_e32 v64, 16, v64
	v_add3_u32 v65, v127, v65, s80
	v_and_or_b32 v132, v65, s85, v64
	v_bfe_u32 v64, v126, 16, 1
	v_add3_u32 v64, v126, v64, s80
	v_bfe_u32 v65, v66, 16, 1
	v_lshrrev_b32_e32 v64, 16, v64
	v_add3_u32 v65, v66, v65, s80
	v_and_or_b32 v133, v65, s85, v64
	v_add_co_u32_e32 v64, vcc, s6, v136
	v_mul_f32_e32 v60, v60, v130
	s_nop 0
	v_addc_co_u32_e32 v65, vcc, 0, v137, vcc
	global_store_dwordx2 v[64:65], v[132:133], off offset:-4096
	s_nop 0
	s_mov_b32 s6, 0x28800000
	v_add_co_u32_e32 v136, vcc, s6, v136
	v_mul_f32_e32 v48, v48, v130
	s_nop 0
	v_addc_co_u32_e32 v137, vcc, 0, v137, vcc
	v_mul_f32_e32 v49, v49, v130
	v_mul_f32_e32 v56, v56, v130
	v_mul_f32_e32 v57, v57, v130
	v_mul_f32_e32 v52, v52, v130
	v_mul_f32_e32 v53, v53, v130
	v_mul_f32_e32 v44, v44, v130
	v_mul_f32_e32 v45, v45, v130
	v_mul_f32_e32 v40, v40, v130
	v_mul_f32_e32 v41, v41, v130
	v_mul_f32_e32 v36, v36, v130
	v_mul_f32_e32 v37, v37, v130
	v_mul_f32_e32 v32, v32, v130
	v_mul_f32_e32 v33, v33, v130
	v_mul_f32_e32 v28, v28, v130
	v_mul_f32_e32 v29, v29, v130
	v_mul_f32_e32 v24, v24, v130
	v_mul_f32_e32 v25, v25, v130
	v_mul_f32_e32 v20, v20, v130
	v_mul_f32_e32 v21, v21, v130
	v_mul_f32_e32 v16, v16, v130
	v_mul_f32_e32 v17, v17, v130
	v_mul_f32_e32 v12, v12, v130
	v_mul_f32_e32 v13, v13, v130
	v_mul_f32_e32 v8, v8, v130
	v_mul_f32_e32 v9, v9, v130
	v_mul_f32_e32 v4, v4, v130
	v_mul_f32_e32 v5, v5, v130
	v_mul_f32_e32 v6, v6, v130
	s_mov_b32 s6, 0xda24260
	s_waitcnt vmcnt(15)
	v_mul_f32_e32 v129, v172, v60
	v_mul_f32_e32 v60, v61, v130
	v_mul_f32_e32 v67, v173, v60
	v_mul_f32_e32 v60, v62, v130
	v_bfe_u32 v62, v129, 16, 1
	v_mul_f32_e32 v61, v174, v60
	v_mul_f32_e32 v60, v63, v130
	v_add3_u32 v62, v129, v62, s80
	v_bfe_u32 v63, v67, 16, 1
	v_lshrrev_b32_e32 v62, 16, v62
	v_add3_u32 v63, v67, v63, s80
	v_mul_f32_e32 v60, v175, v60
	v_and_or_b32 v62, v63, s85, v62
	v_bfe_u32 v63, v61, 16, 1
	v_add3_u32 v63, v61, v63, s80
	v_bfe_u32 v131, v60, 16, 1
	v_lshrrev_b32_e32 v63, 16, v63
	v_add3_u32 v131, v60, v131, s80
	v_and_or_b32 v63, v131, s85, v63
	global_store_dwordx2 v[136:137], v[62:63], off offset:512
	s_nop 0
	v_mul_f32_e32 v62, v50, v130
	v_mul_f32_e32 v63, v51, v130
	s_waitcnt vmcnt(15)
	v_mul_f32_e32 v51, v176, v48
	v_mul_f32_e32 v50, v177, v49
	v_mul_f32_e32 v49, v178, v62
	v_mul_f32_e32 v48, v179, v63
	v_bfe_u32 v62, v51, 16, 1
	v_bfe_u32 v131, v49, 16, 1
	v_bfe_u32 v63, v50, 16, 1
	v_bfe_u32 v132, v48, 16, 1
	v_add3_u32 v62, v51, v62, s80
	v_add3_u32 v131, v49, v131, s80
	v_add3_u32 v63, v50, v63, s80
	v_add3_u32 v132, v48, v132, s80
	v_lshrrev_b32_e32 v62, 16, v62
	v_lshrrev_b32_e32 v131, 16, v131
	v_and_or_b32 v62, v63, s85, v62
	v_and_or_b32 v63, v132, s85, v131
	global_store_dwordx2 v[136:137], v[62:63], off offset:1024
	s_nop 0
	v_mul_f32_e32 v62, v58, v130
	v_mul_f32_e32 v63, v59, v130
	s_waitcnt vmcnt(15)
	v_mul_f32_e32 v59, v56, v180
	v_mul_f32_e32 v58, v57, v181
	v_mul_f32_e32 v57, v62, v182
	v_mul_f32_e32 v56, v63, v183
	v_bfe_u32 v62, v59, 16, 1
	v_bfe_u32 v131, v57, 16, 1
	v_bfe_u32 v63, v58, 16, 1
	v_bfe_u32 v132, v56, 16, 1
	v_add3_u32 v62, v59, v62, s80
	v_add3_u32 v131, v57, v131, s80
	v_add3_u32 v63, v58, v63, s80
	v_add3_u32 v132, v56, v132, s80
	v_lshrrev_b32_e32 v62, 16, v62
	v_lshrrev_b32_e32 v131, 16, v131
	v_and_or_b32 v62, v63, s85, v62
	v_and_or_b32 v63, v132, s85, v131
	global_store_dwordx2 v[136:137], v[62:63], off offset:1536
	s_nop 0
	v_mul_f32_e32 v62, v54, v130
	v_mul_f32_e32 v63, v55, v130
	s_waitcnt vmcnt(15)
	v_mul_f32_e32 v55, v52, v184
	v_mul_f32_e32 v54, v53, v185
	v_mul_f32_e32 v53, v62, v186
	v_mul_f32_e32 v52, v63, v187
	v_bfe_u32 v62, v55, 16, 1
	v_bfe_u32 v131, v53, 16, 1
	v_bfe_u32 v63, v54, 16, 1
	v_bfe_u32 v132, v52, 16, 1
	v_add3_u32 v62, v55, v62, s80
	v_add3_u32 v131, v53, v131, s80
	v_add3_u32 v63, v54, v63, s80
	v_add3_u32 v132, v52, v132, s80
	v_lshrrev_b32_e32 v62, 16, v62
	v_lshrrev_b32_e32 v131, 16, v131
	v_and_or_b32 v62, v63, s85, v62
	v_and_or_b32 v63, v132, s85, v131
	global_store_dwordx2 v[136:137], v[62:63], off offset:2048
	s_nop 0
	v_mul_f32_e32 v62, v46, v130
	v_mul_f32_e32 v63, v47, v130
	s_waitcnt vmcnt(15)
	v_mul_f32_e32 v47, v44, v188
	v_mul_f32_e32 v46, v45, v189
	v_mul_f32_e32 v45, v62, v190
	v_mul_f32_e32 v44, v63, v191
	v_bfe_u32 v62, v47, 16, 1
	v_bfe_u32 v131, v45, 16, 1
	v_bfe_u32 v63, v46, 16, 1
	v_bfe_u32 v132, v44, 16, 1
	v_add3_u32 v62, v47, v62, s80
	v_add3_u32 v131, v45, v131, s80
	v_add3_u32 v63, v46, v63, s80
	v_add3_u32 v132, v44, v132, s80
	v_lshrrev_b32_e32 v62, 16, v62
	v_lshrrev_b32_e32 v131, 16, v131
	v_and_or_b32 v62, v63, s85, v62
	v_and_or_b32 v63, v132, s85, v131
	global_store_dwordx2 v[136:137], v[62:63], off offset:2560
	s_nop 0
	v_mul_f32_e32 v62, v42, v130
	v_mul_f32_e32 v63, v43, v130
	s_waitcnt vmcnt(15)
	v_mul_f32_e32 v43, v40, v192
	v_mul_f32_e32 v42, v41, v193
	v_mul_f32_e32 v41, v62, v194
	v_mul_f32_e32 v40, v63, v195
	v_bfe_u32 v62, v43, 16, 1
	v_bfe_u32 v131, v41, 16, 1
	v_bfe_u32 v63, v42, 16, 1
	v_bfe_u32 v132, v40, 16, 1
	v_add3_u32 v62, v43, v62, s80
	v_add3_u32 v131, v41, v131, s80
	v_add3_u32 v63, v42, v63, s80
	v_add3_u32 v132, v40, v132, s80
	v_lshrrev_b32_e32 v62, 16, v62
	v_lshrrev_b32_e32 v131, 16, v131
	v_and_or_b32 v62, v63, s85, v62
	v_and_or_b32 v63, v132, s85, v131
	global_store_dwordx2 v[136:137], v[62:63], off offset:3072
	s_nop 0
	v_mul_f32_e32 v62, v38, v130
	v_mul_f32_e32 v63, v39, v130
	s_waitcnt vmcnt(15)
	v_mul_f32_e32 v39, v36, v196
	v_mul_f32_e32 v38, v37, v197
	v_mul_f32_e32 v37, v62, v198
	v_mul_f32_e32 v36, v63, v199
	v_bfe_u32 v62, v39, 16, 1
	v_bfe_u32 v131, v37, 16, 1
	v_bfe_u32 v63, v38, 16, 1
	v_bfe_u32 v132, v36, 16, 1
	v_add3_u32 v62, v39, v62, s80
	v_add3_u32 v131, v37, v131, s80
	v_add3_u32 v63, v38, v63, s80
	v_add3_u32 v132, v36, v132, s80
	v_lshrrev_b32_e32 v62, 16, v62
	v_lshrrev_b32_e32 v131, 16, v131
	v_and_or_b32 v62, v63, s85, v62
	v_and_or_b32 v63, v132, s85, v131
	global_store_dwordx2 v[136:137], v[62:63], off offset:3584
	s_nop 0
	v_mul_f32_e32 v62, v34, v130
	v_mul_f32_e32 v63, v35, v130
	s_waitcnt vmcnt(15)
	v_mul_f32_e32 v35, v32, v204
	v_mul_f32_e32 v34, v33, v205
	v_mul_f32_e32 v33, v62, v206
	v_mul_f32_e32 v32, v63, v207
	v_bfe_u32 v62, v35, 16, 1
	v_bfe_u32 v131, v33, 16, 1
	v_bfe_u32 v63, v34, 16, 1
	v_bfe_u32 v132, v32, 16, 1
	v_add3_u32 v62, v35, v62, s80
	v_add3_u32 v131, v33, v131, s80
	v_add3_u32 v63, v34, v63, s80
	v_add3_u32 v132, v32, v132, s80
	v_lshrrev_b32_e32 v62, 16, v62
	v_lshrrev_b32_e32 v131, 16, v131
	v_and_or_b32 v62, v63, s85, v62
	v_and_or_b32 v63, v132, s85, v131
	global_store_dwordx2 v[64:65], v[62:63], off
	s_nop 0
	v_mul_f32_e32 v62, v30, v130
	v_mul_f32_e32 v63, v31, v130
	s_waitcnt vmcnt(15)
	v_mul_f32_e32 v31, v28, v208
	v_mul_f32_e32 v30, v29, v209
	v_mul_f32_e32 v29, v62, v210
	v_mul_f32_e32 v28, v63, v211
	v_bfe_u32 v62, v31, 16, 1
	v_bfe_u32 v131, v29, 16, 1
	v_bfe_u32 v63, v30, 16, 1
	v_bfe_u32 v132, v28, 16, 1
	v_add3_u32 v62, v31, v62, s80
	v_add3_u32 v131, v29, v131, s80
	v_add3_u32 v63, v30, v63, s80
	v_add3_u32 v132, v28, v132, s80
	v_lshrrev_b32_e32 v62, 16, v62
	v_lshrrev_b32_e32 v131, 16, v131
	v_and_or_b32 v62, v63, s85, v62
	v_and_or_b32 v63, v132, s85, v131
	global_store_dwordx2 v[64:65], v[62:63], off offset:512
	s_nop 0
	v_mul_f32_e32 v62, v26, v130
	v_mul_f32_e32 v63, v27, v130
	s_waitcnt vmcnt(15)
	v_mul_f32_e32 v27, v24, v212
	v_mul_f32_e32 v26, v25, v213
	v_mul_f32_e32 v25, v62, v214
	v_mul_f32_e32 v24, v63, v215
	v_bfe_u32 v62, v27, 16, 1
	v_bfe_u32 v131, v25, 16, 1
	v_bfe_u32 v63, v26, 16, 1
	v_bfe_u32 v132, v24, 16, 1
	v_add3_u32 v62, v27, v62, s80
	v_add3_u32 v131, v25, v131, s80
	v_add3_u32 v63, v26, v63, s80
	v_add3_u32 v132, v24, v132, s80
	v_lshrrev_b32_e32 v62, 16, v62
	v_lshrrev_b32_e32 v131, 16, v131
	v_and_or_b32 v62, v63, s85, v62
	v_and_or_b32 v63, v132, s85, v131
	global_store_dwordx2 v[64:65], v[62:63], off offset:1024
	s_nop 0
	v_mul_f32_e32 v62, v22, v130
	v_mul_f32_e32 v63, v23, v130
	s_waitcnt vmcnt(15)
	v_mul_f32_e32 v23, v20, v226
	v_mul_f32_e32 v22, v21, v227
	v_mul_f32_e32 v21, v62, v228
	v_mul_f32_e32 v20, v63, v229
	v_bfe_u32 v62, v23, 16, 1
	v_bfe_u32 v131, v21, 16, 1
	v_bfe_u32 v63, v22, 16, 1
	v_bfe_u32 v132, v20, 16, 1
	v_add3_u32 v62, v23, v62, s80
	v_add3_u32 v131, v21, v131, s80
	v_add3_u32 v63, v22, v63, s80
	v_add3_u32 v132, v20, v132, s80
	v_lshrrev_b32_e32 v62, 16, v62
	v_lshrrev_b32_e32 v131, 16, v131
	v_and_or_b32 v62, v63, s85, v62
	v_and_or_b32 v63, v132, s85, v131
	global_store_dwordx2 v[64:65], v[62:63], off offset:1536
	s_nop 0
	v_mul_f32_e32 v62, v18, v130
	v_mul_f32_e32 v63, v19, v130
	s_waitcnt vmcnt(15)
	v_mul_f32_e32 v19, v16, v230
	v_mul_f32_e32 v18, v17, v231
	v_mul_f32_e32 v17, v62, v232
	v_mul_f32_e32 v16, v63, v233
	v_bfe_u32 v62, v19, 16, 1
	v_bfe_u32 v131, v17, 16, 1
	v_bfe_u32 v63, v18, 16, 1
	v_bfe_u32 v132, v16, 16, 1
	v_add3_u32 v62, v19, v62, s80
	v_add3_u32 v131, v17, v131, s80
	v_add3_u32 v63, v18, v63, s80
	v_add3_u32 v132, v16, v132, s80
	v_lshrrev_b32_e32 v62, 16, v62
	v_lshrrev_b32_e32 v131, 16, v131
	v_and_or_b32 v62, v63, s85, v62
	v_and_or_b32 v63, v132, s85, v131
	global_store_dwordx2 v[64:65], v[62:63], off offset:2048
	s_nop 0
	v_mul_f32_e32 v62, v14, v130
	v_mul_f32_e32 v63, v15, v130
	s_waitcnt vmcnt(15)
	v_mul_f32_e32 v15, v12, v234
	v_mul_f32_e32 v14, v13, v235
	v_mul_f32_e32 v13, v62, v236
	v_mul_f32_e32 v12, v63, v237
	v_bfe_u32 v62, v15, 16, 1
	v_bfe_u32 v131, v13, 16, 1
	v_bfe_u32 v63, v14, 16, 1
	v_bfe_u32 v132, v12, 16, 1
	v_add3_u32 v62, v15, v62, s80
	v_add3_u32 v131, v13, v131, s80
	v_add3_u32 v63, v14, v63, s80
	v_add3_u32 v132, v12, v132, s80
	v_lshrrev_b32_e32 v62, 16, v62
	v_lshrrev_b32_e32 v131, 16, v131
	v_and_or_b32 v62, v63, s85, v62
	v_and_or_b32 v63, v132, s85, v131
	global_store_dwordx2 v[64:65], v[62:63], off offset:2560
	s_nop 0
	v_mul_f32_e32 v62, v10, v130
	v_mul_f32_e32 v63, v11, v130
	v_mul_f32_e32 v130, v7, v130
	v_max_f32_e64 v7, |v128|, |v127|
	s_waitcnt vmcnt(15)
	v_mul_f32_e32 v11, v8, v238
	v_mul_f32_e32 v10, v9, v239
	v_mul_f32_e32 v9, v62, v240
	v_mul_f32_e32 v8, v63, v241
	v_bfe_u32 v62, v11, 16, 1
	v_bfe_u32 v131, v9, 16, 1
	v_bfe_u32 v63, v10, 16, 1
	v_bfe_u32 v132, v8, 16, 1
	v_add3_u32 v62, v11, v62, s80
	v_add3_u32 v131, v9, v131, s80
	v_add3_u32 v63, v10, v63, s80
	v_add3_u32 v132, v8, v132, s80
	v_lshrrev_b32_e32 v62, 16, v62
	v_lshrrev_b32_e32 v131, 16, v131
	v_and_or_b32 v62, v63, s85, v62
	v_and_or_b32 v63, v132, s85, v131
	global_store_dwordx2 v[64:65], v[62:63], off offset:3072
	s_nop 0
	v_max_f32_e64 v62, |v126|, |v66|
	v_max3_f32 v7, v7, 0, v62
	v_max_f32_e64 v62, |v129|, |v67|
	v_max_f32_e64 v63, |v61|, |v60|
	v_max3_f32 v7, v7, v62, v63
	v_max_f32_e64 v62, |v51|, |v50|
	v_max_f32_e64 v63, |v49|, |v48|
	v_max3_f32 v7, v7, v62, v63
	v_max_f32_e64 v62, |v59|, |v58|
	v_max_f32_e64 v63, |v57|, |v56|
	v_max3_f32 v7, v7, v62, v63
	v_max_f32_e64 v62, |v55|, |v54|
	v_max_f32_e64 v63, |v53|, |v52|
	v_max3_f32 v7, v7, v62, v63
	v_max_f32_e64 v62, |v47|, |v46|
	v_max_f32_e64 v63, |v45|, |v44|
	v_max3_f32 v7, v7, v62, v63
	v_max_f32_e64 v62, |v43|, |v42|
	v_max_f32_e64 v63, |v41|, |v40|
	v_max3_f32 v7, v7, v62, v63
	v_max_f32_e64 v62, |v39|, |v38|
	v_max_f32_e64 v63, |v37|, |v36|
	v_max3_f32 v7, v7, v62, v63
	v_max_f32_e64 v62, |v35|, |v34|
	v_max_f32_e64 v63, |v33|, |v32|
	v_max3_f32 v7, v7, v62, v63
	v_max_f32_e64 v62, |v31|, |v30|
	v_max_f32_e64 v63, |v29|, |v28|
	v_max3_f32 v7, v7, v62, v63
	v_max_f32_e64 v62, |v27|, |v26|
	v_max_f32_e64 v63, |v25|, |v24|
	v_max3_f32 v7, v7, v62, v63
	v_max_f32_e64 v62, |v23|, |v22|
	v_max_f32_e64 v63, |v21|, |v20|
	v_max3_f32 v7, v7, v62, v63
	v_max_f32_e64 v62, |v19|, |v18|
	v_max_f32_e64 v63, |v17|, |v16|
	v_max3_f32 v7, v7, v62, v63
	v_max_f32_e64 v62, |v15|, |v14|
	v_max_f32_e64 v63, |v13|, |v12|
	v_max3_f32 v7, v7, v62, v63
	v_max_f32_e64 v62, |v11|, |v10|
	v_max_f32_e64 v63, |v9|, |v8|
	v_max3_f32 v131, v7, v62, v63
	s_waitcnt vmcnt(15)
	v_mul_f32_e32 v63, v4, v242
	v_mul_f32_e32 v62, v5, v243
	v_mul_f32_e32 v7, v6, v244
	v_mul_f32_e32 v6, v130, v245
	v_max_f32_e64 v4, |v63|, |v62|
	v_max_f32_e64 v5, |v7|, |v6|
	v_max3_f32 v4, v131, v4, v5
	ds_bpermute_b32 v5, v155, v4
	v_bfe_u32 v130, v63, 16, 1
	v_add3_u32 v130, v63, v130, s80
	v_bfe_u32 v131, v62, 16, 1
	v_lshrrev_b32_e32 v130, 16, v130
	s_waitcnt lgkmcnt(0)
	v_max_f32_e32 v5, v5, v5
	v_max_f32_e32 v4, v4, v5
	ds_bpermute_b32 v5, v160, v4
	v_add3_u32 v131, v62, v131, s80
	s_waitcnt lgkmcnt(0)
	v_max_f32_e32 v5, v5, v5
	v_max_f32_e32 v4, v4, v5
	ds_bpermute_b32 v5, v161, v4
	s_waitcnt lgkmcnt(0)
	v_max_f32_e32 v5, v5, v5
	v_max_f32_e32 v4, v4, v5
	ds_bpermute_b32 v5, v162, v4
	s_waitcnt lgkmcnt(0)
	v_max_f32_e32 v5, v5, v5
	v_max_f32_e32 v5, v4, v5
	ds_bpermute_b32 v132, v163, v5
	v_and_or_b32 v4, v131, s85, v130
	v_bfe_u32 v130, v7, 16, 1
	v_add3_u32 v130, v7, v130, s80
	v_lshrrev_b32_e32 v130, 16, v130
	s_waitcnt lgkmcnt(0)
	v_max_f32_e32 v131, v132, v132
	v_max_f32_e32 v131, v5, v131
	ds_bpermute_b32 v132, v164, v131
	v_bfe_u32 v5, v6, 16, 1
	v_add3_u32 v5, v6, v5, s80
	v_and_or_b32 v5, v5, s85, v130
	global_store_dwordx2 v[64:65], v[4:5], off offset:3584
	s_waitcnt lgkmcnt(0)
	v_max3_f32 v4, v131, v132, s6
	s_and_saveexec_b64 s[6:7], s[4:5]
	s_cbranch_execz .LBB0_3909
	s_add_u32 s18, s8, s14
	v_mul_f32_e32 v5, 0x3c010204, v4
	s_addc_u32 s19, s9, s15
	global_store_dword v3, v5, s[18:19]
	s_branch .LBB0_3909
